# GEMM K-loops: reorder each 16-MFMA block so the two MFMAs of one accumulator are adjacent (k0,k1 chain), same math
# speedup vs baseline: 1.0100x; 1.0100x over previous
.LBB0_100:
	v_lshlrev_b32_e32 v68, 4, v66
	global_load_dwordx4 v[62:65], v68, s[4:5]
	global_load_dwordx4 v[54:57], v68, s[4:5] offset:1024
	global_load_dwordx4 v[50:53], v68, s[4:5] offset:2048
	v_lshl_add_u64 v[2:3], s[4:5], 0, v[68:69]
	v_add_co_u32_e32 v4, vcc, s23, v2
	global_load_dwordx4 v[30:33], v68, s[4:5] offset:3072
	s_nop 0
	v_addc_co_u32_e32 v5, vcc, 0, v3, vcc
	global_load_dwordx4 v[34:37], v[4:5], off offset:-4096
	v_add_co_u32_e32 v14, vcc, s22, v2
	s_waitcnt vmcnt(4)
	v_mov_b32_e32 v122, v63
	v_addc_co_u32_e32 v15, vcc, 0, v3, vcc
	global_load_dwordx4 v[18:21], v[14:15], off offset:1024
	global_load_dwordx4 v[10:13], v[14:15], off offset:2048
	global_load_dwordx4 v[6:9], v[14:15], off offset:3072
	global_load_dwordx4 v[58:61], v[4:5], off
	global_load_dwordx4 v[46:49], v[4:5], off offset:1024
	global_load_dwordx4 v[42:45], v[4:5], off offset:2048
	v_add_co_u32_e32 v22, vcc, s25, v2
	v_mov_b32_e32 v123, v64
	s_nop 0
	v_addc_co_u32_e32 v23, vcc, 0, v3, vcc
	global_load_dwordx4 v[26:29], v[4:5], off offset:3072
	global_load_dwordx4 v[14:17], v[22:23], off
	global_load_dwordx4 v[38:41], v[22:23], off offset:1024
	s_nop 0
	global_load_dwordx4 v[2:5], v[22:23], off offset:3072
	s_nop 0
	global_load_dwordx4 v[22:25], v[22:23], off offset:2048
	v_mov_b32_e32 v124, v62
	v_mov_b32_e32 v125, v65
	s_waitcnt vmcnt(14)
	v_mov_b32_e32 v126, v55
	v_mov_b32_e32 v127, v56
	v_mov_b32_e32 v142, v54
	v_mov_b32_e32 v143, v57
	v_pk_add_f32 v[122:123], v[122:123], v[124:125]
	v_pk_add_f32 v[124:125], v[126:127], v[142:143]
	v_add_f32_e32 v68, v122, v123
	v_pk_add_f32 v[122:123], v[124:125], v[124:125] op_sel:[0,1] op_sel_hi:[1,0]
	s_waitcnt vmcnt(13)
	v_add_f32_e32 v144, v50, v51
	v_add_f32_e32 v146, v52, v53
	s_waitcnt vmcnt(12)
	v_mov_b32_e32 v145, v32
	v_mov_b32_e32 v147, v33
	v_mov_b32_e32 v149, v30
	v_add_f32_e32 v148, 0, v68
	v_mov_b32_e32 v123, v31
	v_pk_add_f32 v[126:127], v[144:145], v[146:147]
	s_waitcnt vmcnt(11)
	v_mov_b32_e32 v142, v35
	v_mov_b32_e32 v143, v36
	v_mov_b32_e32 v144, v34
	v_mov_b32_e32 v145, v37
	v_pk_add_f32 v[122:123], v[148:149], v[122:123]
	v_pk_add_f32 v[124:125], v[142:143], v[144:145]
	v_pk_add_f32 v[122:123], v[122:123], v[126:127]
	v_pk_add_f32 v[124:125], v[124:125], v[124:125] op_sel:[0,1] op_sel_hi:[1,0]
	v_pk_add_f32 v[122:123], v[122:123], v[122:123] op_sel:[0,1] op_sel_hi:[1,0]
	s_waitcnt vmcnt(10)
	v_add_f32_e32 v146, v18, v19
	v_add_f32_e32 v150, v20, v21
	s_waitcnt vmcnt(9)
	v_mov_b32_e32 v147, v12
	v_mov_b32_e32 v151, v13
	v_mov_b32_e32 v125, v11
	v_mov_b32_e32 v123, v10
	s_waitcnt vmcnt(8)
	v_mov_b32_e32 v152, v7
	v_mov_b32_e32 v153, v8
	v_mov_b32_e32 v154, v6
	v_mov_b32_e32 v155, v9
	v_pk_add_f32 v[142:143], v[146:147], v[150:151]
	v_pk_add_f32 v[122:123], v[122:123], v[124:125]
	v_pk_add_f32 v[144:145], v[152:153], v[154:155]
	v_pk_add_f32 v[122:123], v[122:123], v[142:143]
	v_pk_add_f32 v[144:145], v[144:145], v[144:145] op_sel:[0,1] op_sel_hi:[1,0]
	v_pk_add_f32 v[122:123], v[122:123], v[122:123] op_sel:[0,1] op_sel_hi:[1,0]
	s_waitcnt vmcnt(7)
	v_add_f32_e32 v156, v58, v59
	s_waitcnt vmcnt(6)
	v_mov_b32_e32 v157, v48
	v_add_f32_e32 v158, v60, v61
	v_mov_b32_e32 v159, v49
	v_mov_b32_e32 v145, v47
	v_mov_b32_e32 v123, v46
	s_waitcnt vmcnt(5)
	v_mov_b32_e32 v160, v43
	v_mov_b32_e32 v161, v44
	v_mov_b32_e32 v162, v42
	v_mov_b32_e32 v163, v45
	v_pk_add_f32 v[146:147], v[156:157], v[158:159]
	v_pk_add_f32 v[122:123], v[122:123], v[144:145]
	v_pk_add_f32 v[150:151], v[160:161], v[162:163]
	v_pk_add_f32 v[122:123], v[122:123], v[146:147]
	v_pk_add_f32 v[148:149], v[150:151], v[150:151] op_sel:[0,1] op_sel_hi:[1,0]
	v_pk_add_f32 v[122:123], v[122:123], v[122:123] op_sel:[0,1] op_sel_hi:[1,0]
	s_waitcnt vmcnt(4)
	v_add_f32_e32 v164, v26, v27
	s_waitcnt vmcnt(3)
	v_mov_b32_e32 v165, v16
	v_add_f32_e32 v166, v28, v29
	v_mov_b32_e32 v167, v17
	v_mov_b32_e32 v149, v15
	v_mov_b32_e32 v123, v14
	v_pk_add_f32 v[152:153], v[164:165], v[166:167]
	v_pk_add_f32 v[122:123], v[122:123], v[148:149]
	s_waitcnt vmcnt(2)
	v_mov_b32_e32 v124, v39
	v_mov_b32_e32 v125, v40
	v_mov_b32_e32 v126, v38
	v_mov_b32_e32 v127, v41
	v_pk_add_f32 v[122:123], v[122:123], v[152:153]
	v_pk_add_f32 v[124:125], v[124:125], v[126:127]
	v_pk_add_f32 v[122:123], v[122:123], v[122:123] op_sel:[0,1] op_sel_hi:[1,0]
	v_pk_add_f32 v[124:125], v[124:125], v[124:125] op_sel:[0,1] op_sel_hi:[1,0]
	s_waitcnt vmcnt(1)
	v_mov_b32_e32 v123, v2
	v_mov_b32_e32 v125, v3
	v_pk_add_f32 v[122:123], v[122:123], v[124:125]
	s_waitcnt vmcnt(0)
	v_add_f32_e32 v124, v22, v23
	v_mov_b32_e32 v125, v4
	v_add_f32_e32 v126, v24, v25
	v_mov_b32_e32 v127, v5
	v_pk_add_f32 v[124:125], v[124:125], v[126:127]
	s_nop 0
	v_pk_add_f32 v[122:123], v[122:123], v[124:125]
	s_nop 0
	v_add_f32_e32 v68, v122, v123
	ds_bpermute_b32 v122, v1, v68
	s_waitcnt lgkmcnt(0)
	v_add_f32_e32 v68, v68, v122
	ds_bpermute_b32 v122, v67, v68
	s_waitcnt lgkmcnt(0)
	v_add_f32_e32 v68, v68, v122
	ds_bpermute_b32 v122, v128, v68
	s_waitcnt lgkmcnt(0)
	v_add_f32_e32 v68, v68, v122
	ds_bpermute_b32 v122, v129, v68
	s_waitcnt lgkmcnt(0)
	v_add_f32_e32 v68, v68, v122
	ds_bpermute_b32 v122, v130, v68
	s_waitcnt lgkmcnt(0)
	v_add_f32_e32 v68, v68, v122
	ds_bpermute_b32 v122, v131, v68
	s_waitcnt lgkmcnt(0)
	v_add_f32_e32 v68, v68, v122
	v_fmamk_f32 v127, v68, 0xb9800000, v63
	v_fmamk_f32 v126, v68, 0xb9800000, v62
	v_fmamk_f32 v65, v68, 0xb9800000, v65
	v_fmac_f32_e32 v64, 0xb9800000, v68
	v_fmamk_f32 v63, v68, 0xb9800000, v55
	v_fmamk_f32 v62, v68, 0xb9800000, v54
	v_fmamk_f32 v57, v68, 0xb9800000, v57
	v_fmac_f32_e32 v56, 0xb9800000, v68
	v_pk_mul_f32 v[54:55], v[64:65], v[64:65]
	v_pk_mul_f32 v[122:123], v[126:127], v[126:127]
	v_pk_mul_f32 v[124:125], v[56:57], v[56:57]
	v_pk_mul_f32 v[142:143], v[62:63], v[62:63]
	v_pk_mov_b32 v[144:145], v[122:123], v[54:55] op_sel:[1,0]
	v_mov_b32_e32 v123, v55
	v_pk_add_f32 v[54:55], v[144:145], v[122:123]
	v_pk_mov_b32 v[122:123], v[142:143], v[124:125] op_sel:[1,0]
	v_mov_b32_e32 v143, v125
	v_pk_add_f32 v[124:125], v[122:123], v[142:143]
	v_fmamk_f32 v122, v68, 0xb9800000, v50
	v_fmamk_f32 v123, v68, 0xb9800000, v51
	v_mul_f32_e32 v50, v122, v122
	v_fmac_f32_e32 v52, 0xb9800000, v68
	v_pk_fma_f32 v[50:51], v[122:123], v[122:123], v[50:51] op_sel_hi:[1,1,0]
	v_fmamk_f32 v53, v68, 0xb9800000, v53
	v_mul_f32_e32 v50, v52, v52
	v_pk_fma_f32 v[142:143], v[52:53], v[52:53], v[50:51] op_sel_hi:[1,1,0]
	v_fmamk_f32 v31, v68, 0xb9800000, v31
	v_fmac_f32_e32 v30, 0xb9800000, v68
	v_mul_f32_e32 v50, v30, v30
	v_mul_f32_e32 v142, v31, v31
	v_pk_add_f32 v[50:51], v[50:51], v[142:143]
	v_pk_add_f32 v[54:55], v[54:55], v[54:55] op_sel_hi:[0,1]
	v_pk_add_f32 v[142:143], v[124:125], v[124:125] op_sel_hi:[0,1]
	v_fmamk_f32 v125, v68, 0xb9800000, v33
	v_fmamk_f32 v124, v68, 0xb9800000, v32
	v_mul_f32_e32 v54, v124, v124
	v_mul_f32_e32 v142, v125, v125
	v_pk_add_f32 v[32:33], v[54:55], v[142:143]
	v_fmamk_f32 v55, v68, 0xb9800000, v35
	v_fmamk_f32 v54, v68, 0xb9800000, v34
	v_fmamk_f32 v37, v68, 0xb9800000, v37
	v_fmac_f32_e32 v36, 0xb9800000, v68
	v_pk_add_f32 v[32:33], v[50:51], v[32:33]
	v_pk_mul_f32 v[34:35], v[36:37], v[36:37]
	v_pk_mul_f32 v[50:51], v[54:55], v[54:55]
	v_fmac_f32_e32 v20, 0xb9800000, v68
	v_pk_mov_b32 v[142:143], v[50:51], v[34:35] op_sel:[1,0]
	v_fmamk_f32 v34, v68, 0xb9800000, v18
	v_mov_b32_e32 v51, v35
	v_fmamk_f32 v35, v68, 0xb9800000, v19
	v_mul_f32_e32 v18, v34, v34
	v_pk_fma_f32 v[18:19], v[34:35], v[34:35], v[18:19] op_sel_hi:[1,1,0]
	v_fmamk_f32 v21, v68, 0xb9800000, v21
	v_mul_f32_e32 v18, v20, v20
	v_pk_add_f32 v[50:51], v[142:143], v[50:51]
	v_pk_fma_f32 v[142:143], v[20:21], v[20:21], v[18:19] op_sel_hi:[1,1,0]
	v_fmamk_f32 v11, v68, 0xb9800000, v11
	v_fmac_f32_e32 v10, 0xb9800000, v68
	v_mul_f32_e32 v18, v10, v10
	v_mul_f32_e32 v142, v11, v11
	v_pk_add_f32 v[18:19], v[18:19], v[142:143]
	v_pk_add_f32 v[32:33], v[32:33], v[32:33] op_sel_hi:[0,1]
	v_pk_add_f32 v[142:143], v[50:51], v[50:51] op_sel_hi:[0,1]
	v_fmamk_f32 v51, v68, 0xb9800000, v13
	v_fmamk_f32 v50, v68, 0xb9800000, v12
	v_mul_f32_e32 v142, v50, v50
	v_mul_f32_e32 v32, v51, v51
	v_pk_add_f32 v[12:13], v[142:143], v[32:33]
	v_fmamk_f32 v9, v68, 0xb9800000, v9
	v_pk_add_f32 v[18:19], v[18:19], v[12:13]
	v_fmamk_f32 v13, v68, 0xb9800000, v7
	v_fmamk_f32 v12, v68, 0xb9800000, v6
	v_fmac_f32_e32 v8, 0xb9800000, v68
	v_pk_mul_f32 v[6:7], v[8:9], v[8:9]
	v_pk_mul_f32 v[32:33], v[12:13], v[12:13]
	v_fmac_f32_e32 v60, 0xb9800000, v68
	v_pk_mov_b32 v[142:143], v[32:33], v[6:7] op_sel:[1,0]
	v_fmamk_f32 v6, v68, 0xb9800000, v58
	v_mov_b32_e32 v33, v7
	v_fmamk_f32 v7, v68, 0xb9800000, v59
	v_mul_f32_e32 v58, v6, v6
	v_pk_fma_f32 v[58:59], v[6:7], v[6:7], v[58:59] op_sel_hi:[1,1,0]
	v_fmamk_f32 v61, v68, 0xb9800000, v61
	v_mul_f32_e32 v58, v60, v60
	v_pk_add_f32 v[32:33], v[142:143], v[32:33]
	v_pk_fma_f32 v[142:143], v[60:61], v[60:61], v[58:59] op_sel_hi:[1,1,0]
	v_fmamk_f32 v47, v68, 0xb9800000, v47
	v_fmac_f32_e32 v46, 0xb9800000, v68
	v_mul_f32_e32 v58, v46, v46
	v_mul_f32_e32 v142, v47, v47
	v_pk_add_f32 v[58:59], v[58:59], v[142:143]
	v_pk_add_f32 v[18:19], v[18:19], v[18:19] op_sel_hi:[0,1]
	v_pk_add_f32 v[142:143], v[32:33], v[32:33] op_sel_hi:[0,1]
	v_fmamk_f32 v33, v68, 0xb9800000, v49
	v_fmamk_f32 v32, v68, 0xb9800000, v48
	v_mul_f32_e32 v142, v32, v32
	v_mul_f32_e32 v18, v33, v33
	v_pk_add_f32 v[18:19], v[142:143], v[18:19]
	v_fmamk_f32 v45, v68, 0xb9800000, v45
	v_pk_add_f32 v[48:49], v[58:59], v[18:19]
	v_fmamk_f32 v19, v68, 0xb9800000, v43
	v_fmamk_f32 v18, v68, 0xb9800000, v42
	v_fmac_f32_e32 v44, 0xb9800000, v68
	v_pk_mul_f32 v[42:43], v[44:45], v[44:45]
	v_pk_mul_f32 v[58:59], v[18:19], v[18:19]
	v_fmamk_f32 v26, v68, 0xb9800000, v26
	v_pk_mov_b32 v[142:143], v[58:59], v[42:43] op_sel:[1,0]
	v_mov_b32_e32 v59, v43
	v_pk_add_f32 v[42:43], v[142:143], v[58:59]
	v_fmamk_f32 v27, v68, 0xb9800000, v27
	v_mul_f32_e32 v58, v26, v26
	v_fmac_f32_e32 v28, 0xb9800000, v68
	v_pk_fma_f32 v[58:59], v[26:27], v[26:27], v[58:59] op_sel_hi:[1,1,0]
	v_fmamk_f32 v29, v68, 0xb9800000, v29
	v_mul_f32_e32 v58, v28, v28
	v_pk_fma_f32 v[142:143], v[28:29], v[28:29], v[58:59] op_sel_hi:[1,1,0]
	v_fmamk_f32 v15, v68, 0xb9800000, v15
	v_fmac_f32_e32 v14, 0xb9800000, v68
	v_mul_f32_e32 v58, v14, v14
	v_mul_f32_e32 v142, v15, v15
	v_pk_add_f32 v[58:59], v[58:59], v[142:143]
	v_pk_add_f32 v[48:49], v[48:49], v[48:49] op_sel_hi:[0,1]
	v_pk_add_f32 v[142:143], v[42:43], v[42:43] op_sel_hi:[0,1]
	v_fmamk_f32 v43, v68, 0xb9800000, v17
	v_fmamk_f32 v42, v68, 0xb9800000, v16
	v_mul_f32_e32 v142, v42, v42
	v_mul_f32_e32 v48, v43, v43
	v_pk_add_f32 v[16:17], v[142:143], v[48:49]
	v_fmamk_f32 v41, v68, 0xb9800000, v41
	v_pk_add_f32 v[48:49], v[58:59], v[16:17]
	v_fmamk_f32 v17, v68, 0xb9800000, v39
	v_fmamk_f32 v16, v68, 0xb9800000, v38
	v_fmac_f32_e32 v40, 0xb9800000, v68
	v_pk_mul_f32 v[38:39], v[40:41], v[40:41]
	v_pk_mul_f32 v[58:59], v[16:17], v[16:17]
	v_fmamk_f32 v22, v68, 0xb9800000, v22
	v_pk_mov_b32 v[142:143], v[58:59], v[38:39] op_sel:[1,0]
	v_mov_b32_e32 v59, v39
	v_pk_add_f32 v[38:39], v[142:143], v[58:59]
	v_fmamk_f32 v23, v68, 0xb9800000, v23
	v_mul_f32_e32 v58, v22, v22
	v_fmac_f32_e32 v24, 0xb9800000, v68
	v_pk_fma_f32 v[58:59], v[22:23], v[22:23], v[58:59] op_sel_hi:[1,1,0]
	v_fmamk_f32 v25, v68, 0xb9800000, v25
	v_mul_f32_e32 v58, v24, v24
	v_pk_fma_f32 v[142:143], v[24:25], v[24:25], v[58:59] op_sel_hi:[1,1,0]
	v_fmamk_f32 v3, v68, 0xb9800000, v3
	v_fmac_f32_e32 v2, 0xb9800000, v68
	v_mul_f32_e32 v58, v2, v2
	v_mul_f32_e32 v142, v3, v3
	v_pk_add_f32 v[58:59], v[58:59], v[142:143]
	global_load_dwordx4 v[142:145], v[70:71], off
	global_load_dwordx4 v[146:149], v[72:73], off
	v_fmamk_f32 v5, v68, 0xb9800000, v5
	v_fmamk_f32 v4, v68, 0xb9800000, v4
	v_pk_add_f32 v[48:49], v[48:49], v[48:49] op_sel_hi:[0,1]
	v_pk_add_f32 v[38:39], v[38:39], v[38:39] op_sel_hi:[0,1]
	v_mul_f32_e32 v38, v4, v4
	v_mul_f32_e32 v48, v5, v5
	v_pk_add_f32 v[38:39], v[38:39], v[48:49]
	s_nop 0
	v_pk_add_f32 v[38:39], v[58:59], v[38:39]
	s_nop 0
	v_add_f32_e32 v38, v38, v39
	ds_bpermute_b32 v39, v1, v38
	s_waitcnt lgkmcnt(0)
	v_add_f32_e32 v38, v38, v39
	ds_bpermute_b32 v39, v67, v38
	s_waitcnt lgkmcnt(0)
	v_add_f32_e32 v38, v38, v39
	ds_bpermute_b32 v39, v128, v38
	s_waitcnt lgkmcnt(0)
	v_add_f32_e32 v38, v38, v39
	ds_bpermute_b32 v39, v129, v38
	s_waitcnt lgkmcnt(0)
	v_add_f32_e32 v38, v38, v39
	ds_bpermute_b32 v39, v130, v38
	s_waitcnt lgkmcnt(0)
	v_add_f32_e32 v38, v38, v39
	ds_bpermute_b32 v39, v131, v38
	s_waitcnt lgkmcnt(0)
	v_add_f32_e32 v38, v38, v39
	v_fmamk_f32 v38, v38, 0x39800000, v132
	v_mul_f32_e32 v39, 0x4f800000, v38
	v_cmp_gt_f32_e32 vcc, s28, v38
	s_nop 1
	v_cndmask_b32_e32 v38, v38, v39, vcc
	v_sqrt_f32_e32 v39, v38
	s_nop 0
	v_add_u32_e32 v48, -1, v39
	v_fma_f32 v49, -v48, v39, v38
	v_cmp_ge_f32_e64 s[4:5], 0, v49
	v_add_u32_e32 v49, 1, v39
	s_nop 0
	v_cndmask_b32_e64 v48, v39, v48, s[4:5]
	v_fma_f32 v39, -v49, v39, v38
	v_cmp_lt_f32_e64 s[4:5], 0, v39
	s_nop 1
	v_cndmask_b32_e64 v39, v48, v49, s[4:5]
	v_mul_f32_e32 v48, 0x37800000, v39
	v_cndmask_b32_e32 v39, v39, v48, vcc
	v_cmp_class_f32_e32 vcc, v38, v133
	s_nop 1
	v_cndmask_b32_e32 v38, v39, v38, vcc
	v_div_scale_f32 v39, s[4:5], v38, v38, 1.0
	v_rcp_f32_e32 v48, v39
	s_lshl_b64 s[4:5], s[12:13], 13
	s_add_u32 s4, s20, s4
	s_addc_u32 s5, s21, s5
	v_fma_f32 v49, -v39, v48, 1.0
	v_fmac_f32_e32 v48, v49, v48
	v_div_scale_f32 v49, vcc, 1.0, v38, 1.0
	v_mul_f32_e32 v58, v49, v48
	v_fma_f32 v59, -v39, v58, v49
	v_fmac_f32_e32 v58, v59, v48
	v_fma_f32 v39, -v39, v58, v49
	v_div_fmas_f32 v39, v39, v48, v58
	v_div_fixup_f32 v38, v39, v38, 1.0
	v_pk_mul_f32 v[48:49], v[64:65], v[38:39] op_sel_hi:[1,0]
	v_pk_mul_f32 v[58:59], v[126:127], v[38:39] op_sel_hi:[1,0]
	s_waitcnt vmcnt(0)
	v_pk_fma_f32 v[48:49], v[144:145], v[48:49], v[148:149]
	v_pk_fma_f32 v[58:59], v[142:143], v[58:59], v[146:147]
	v_lshlrev_b32_e32 v39, 3, v66
	v_cvt_pk_bf16_f32 v58, v58, v59
	v_cvt_pk_bf16_f32 v59, v48, v49
	global_store_dwordx2 v39, v[58:59], s[4:5]
	global_load_dwordx4 v[142:145], v[70:71], off offset:1024
	global_load_dwordx4 v[146:149], v[72:73], off offset:1024
	v_pk_mul_f32 v[48:49], v[56:57], v[38:39] op_sel_hi:[1,0]
	v_pk_mul_f32 v[56:57], v[62:63], v[38:39] op_sel_hi:[1,0]
	v_pk_mul_f32 v[30:31], v[30:31], v[38:39] op_sel_hi:[1,0]
	v_pk_mul_f32 v[20:21], v[20:21], v[38:39] op_sel_hi:[1,0]
	v_pk_mul_f32 v[10:11], v[10:11], v[38:39] op_sel_hi:[1,0]
	v_pk_mul_f32 v[8:9], v[8:9], v[38:39] op_sel_hi:[1,0]
	v_pk_mul_f32 v[6:7], v[6:7], v[38:39] op_sel_hi:[1,0]
	v_pk_mul_f32 v[18:19], v[18:19], v[38:39] op_sel_hi:[1,0]
	v_pk_mul_f32 v[14:15], v[14:15], v[38:39] op_sel_hi:[1,0]
	s_add_u32 s16, s16, s18
	s_addc_u32 s17, s17, s19
	s_add_u32 s6, s6, s10
	v_pk_mul_f32 v[2:3], v[2:3], v[38:39] op_sel_hi:[1,0]
	v_pk_mul_f32 v[4:5], v[4:5], v[38:39] op_sel_hi:[1,0]
	s_addc_u32 s7, s7, s11
	s_cmp_lt_i32 s16, 0x8000
	s_waitcnt vmcnt(0)
	v_pk_fma_f32 v[48:49], v[144:145], v[48:49], v[148:149]
	v_pk_fma_f32 v[56:57], v[142:143], v[56:57], v[146:147]
	s_nop 0
	v_cvt_pk_bf16_f32 v56, v56, v57
	v_cvt_pk_bf16_f32 v57, v48, v49
	global_store_dwordx2 v39, v[56:57], s[4:5] offset:512
	global_load_dwordx4 v[56:59], v[70:71], off offset:2048
	s_nop 0
	global_load_dwordx4 v[62:65], v[72:73], off offset:2048
	v_pk_mul_f32 v[48:49], v[52:53], v[38:39] op_sel_hi:[1,0]
	v_pk_mul_f32 v[52:53], v[122:123], v[38:39] op_sel_hi:[1,0]
	s_waitcnt vmcnt(0)
	v_pk_fma_f32 v[48:49], v[58:59], v[48:49], v[64:65]
	v_pk_fma_f32 v[52:53], v[56:57], v[52:53], v[62:63]
	s_nop 0
	v_cvt_pk_bf16_f32 v52, v52, v53
	v_cvt_pk_bf16_f32 v53, v48, v49
	global_store_dwordx2 v39, v[52:53], s[4:5] offset:1024
	global_load_dwordx4 v[56:59], v[70:71], off offset:3072
	global_load_dwordx4 v[62:65], v[72:73], off offset:3072
	v_pk_mul_f32 v[48:49], v[124:125], v[38:39] op_sel_hi:[1,0]
	s_waitcnt vmcnt(0)
	v_pk_fma_f32 v[30:31], v[56:57], v[30:31], v[62:63]
	v_pk_fma_f32 v[48:49], v[58:59], v[48:49], v[64:65]
	v_cvt_pk_bf16_f32 v30, v30, v31
	v_cvt_pk_bf16_f32 v31, v48, v49
	global_store_dwordx2 v39, v[30:31], s[4:5] offset:1536
	global_load_dwordx4 v[56:59], v[74:75], off
	global_load_dwordx4 v[62:65], v[76:77], off
	v_pk_mul_f32 v[30:31], v[36:37], v[38:39] op_sel_hi:[1,0]
	v_pk_mul_f32 v[36:37], v[54:55], v[38:39] op_sel_hi:[1,0]
	s_waitcnt vmcnt(0)
	v_pk_fma_f32 v[30:31], v[58:59], v[30:31], v[64:65]
	v_pk_fma_f32 v[36:37], v[56:57], v[36:37], v[62:63]
	s_nop 0
	v_cvt_pk_bf16_f32 v36, v36, v37
	v_cvt_pk_bf16_f32 v37, v30, v31
	global_store_dwordx2 v39, v[36:37], s[4:5] offset:2048
	global_load_dwordx4 v[52:55], v[78:79], off
	global_load_dwordx4 v[56:59], v[80:81], off
	v_pk_mul_f32 v[30:31], v[34:35], v[38:39] op_sel_hi:[1,0]
	s_waitcnt vmcnt(0)
	v_pk_fma_f32 v[20:21], v[54:55], v[20:21], v[58:59]
	v_pk_fma_f32 v[30:31], v[52:53], v[30:31], v[56:57]
	s_nop 0
	v_cvt_pk_bf16_f32 v30, v30, v31
	v_cvt_pk_bf16_f32 v31, v20, v21
	global_store_dwordx2 v39, v[30:31], s[4:5] offset:2560
	global_load_dwordx4 v[34:37], v[82:83], off
	global_load_dwordx4 v[52:55], v[84:85], off
	v_pk_mul_f32 v[20:21], v[50:51], v[38:39] op_sel_hi:[1,0]
	v_pk_mul_f32 v[30:31], v[32:33], v[38:39] op_sel_hi:[1,0]
	s_waitcnt vmcnt(0)
	v_pk_fma_f32 v[20:21], v[36:37], v[20:21], v[54:55]
	v_pk_fma_f32 v[10:11], v[34:35], v[10:11], v[52:53]
	s_nop 0
	v_cvt_pk_bf16_f32 v10, v10, v11
	v_cvt_pk_bf16_f32 v11, v20, v21
	global_store_dwordx2 v39, v[10:11], s[4:5] offset:3072
	global_load_dwordx4 v[34:37], v[86:87], off
	global_load_dwordx4 v[48:51], v[88:89], off
	v_pk_mul_f32 v[10:11], v[12:13], v[38:39] op_sel_hi:[1,0]
	v_pk_mul_f32 v[12:13], v[60:61], v[38:39] op_sel_hi:[1,0]
	v_pk_mul_f32 v[20:21], v[46:47], v[38:39] op_sel_hi:[1,0]
	s_waitcnt vmcnt(0)
	v_pk_fma_f32 v[8:9], v[36:37], v[8:9], v[50:51]
	v_pk_fma_f32 v[10:11], v[34:35], v[10:11], v[48:49]
	s_nop 0
	v_cvt_pk_bf16_f32 v10, v10, v11
	v_cvt_pk_bf16_f32 v11, v8, v9
	global_store_dwordx2 v39, v[10:11], s[4:5] offset:3584
	global_load_dwordx4 v[8:11], v[90:91], off
	s_nop 0
	global_load_dwordx4 v[34:37], v[92:93], off
	s_waitcnt vmcnt(0)
	v_pk_fma_f32 v[10:11], v[12:13], v[10:11], v[36:37]
	v_pk_fma_f32 v[6:7], v[6:7], v[8:9], v[34:35]
	s_nop 0
	v_cvt_pk_bf16_f32 v6, v6, v7
	v_cvt_pk_bf16_f32 v7, v10, v11
	global_store_dwordx2 v134, v[6:7], s[4:5]
	global_load_dwordx4 v[6:9], v[94:95], off
	s_nop 0
	global_load_dwordx4 v[10:13], v[96:97], off
	s_waitcnt vmcnt(0)
	v_pk_fma_f32 v[8:9], v[30:31], v[8:9], v[12:13]
	v_pk_fma_f32 v[6:7], v[20:21], v[6:7], v[10:11]
	v_pk_mul_f32 v[20:21], v[44:45], v[38:39] op_sel_hi:[1,0]
	v_cvt_pk_bf16_f32 v6, v6, v7
	v_cvt_pk_bf16_f32 v7, v8, v9
	global_store_dwordx2 v135, v[6:7], s[4:5]
	global_load_dwordx4 v[6:9], v[98:99], off
	s_nop 0
	global_load_dwordx4 v[10:13], v[100:101], off
	s_waitcnt vmcnt(0)
	v_pk_fma_f32 v[8:9], v[20:21], v[8:9], v[12:13]
	v_pk_fma_f32 v[6:7], v[18:19], v[6:7], v[10:11]
	v_pk_mul_f32 v[18:19], v[26:27], v[38:39] op_sel_hi:[1,0]
	v_cvt_pk_bf16_f32 v6, v6, v7
	v_cvt_pk_bf16_f32 v7, v8, v9
	global_store_dwordx2 v136, v[6:7], s[4:5]
	global_load_dwordx4 v[6:9], v[102:103], off
	s_nop 0
	global_load_dwordx4 v[10:13], v[104:105], off
	v_pk_mul_f32 v[20:21], v[28:29], v[38:39] op_sel_hi:[1,0]
	s_waitcnt vmcnt(0)
	v_pk_fma_f32 v[6:7], v[18:19], v[6:7], v[10:11]
	v_pk_fma_f32 v[8:9], v[20:21], v[8:9], v[12:13]
	v_cvt_pk_bf16_f32 v6, v6, v7
	v_cvt_pk_bf16_f32 v7, v8, v9
	global_store_dwordx2 v137, v[6:7], s[4:5]
	global_load_dwordx4 v[6:9], v[106:107], off
	s_nop 0
	global_load_dwordx4 v[10:13], v[108:109], off
	v_pk_mul_f32 v[18:19], v[42:43], v[38:39] op_sel_hi:[1,0]
	s_waitcnt vmcnt(0)
	v_pk_fma_f32 v[6:7], v[14:15], v[6:7], v[10:11]
	v_pk_fma_f32 v[8:9], v[18:19], v[8:9], v[12:13]
	v_cvt_pk_bf16_f32 v6, v6, v7
	v_cvt_pk_bf16_f32 v7, v8, v9
	global_store_dwordx2 v138, v[6:7], s[4:5]
	global_load_dwordx4 v[6:9], v[110:111], off
	s_nop 0
	global_load_dwordx4 v[10:13], v[112:113], off
	v_pk_mul_f32 v[14:15], v[16:17], v[38:39] op_sel_hi:[1,0]
	v_pk_mul_f32 v[16:17], v[40:41], v[38:39] op_sel_hi:[1,0]
	s_waitcnt vmcnt(0)
	v_pk_fma_f32 v[6:7], v[14:15], v[6:7], v[10:11]
	v_pk_fma_f32 v[8:9], v[16:17], v[8:9], v[12:13]
	v_cvt_pk_bf16_f32 v6, v6, v7
	v_cvt_pk_bf16_f32 v7, v8, v9
	global_store_dwordx2 v139, v[6:7], s[4:5]
	global_load_dwordx4 v[6:9], v[114:115], off
	s_nop 0
	global_load_dwordx4 v[10:13], v[116:117], off
	v_pk_mul_f32 v[14:15], v[22:23], v[38:39] op_sel_hi:[1,0]
	v_pk_mul_f32 v[16:17], v[24:25], v[38:39] op_sel_hi:[1,0]
	s_waitcnt vmcnt(0)
	v_pk_fma_f32 v[6:7], v[14:15], v[6:7], v[10:11]
	v_pk_fma_f32 v[8:9], v[16:17], v[8:9], v[12:13]
	v_cvt_pk_bf16_f32 v6, v6, v7
	v_cvt_pk_bf16_f32 v7, v8, v9
	global_store_dwordx2 v140, v[6:7], s[4:5]
	global_load_dwordx4 v[6:9], v[118:119], off
	s_nop 0
	global_load_dwordx4 v[10:13], v[120:121], off
	s_waitcnt vmcnt(0)
	v_pk_fma_f32 v[4:5], v[4:5], v[8:9], v[12:13]
	v_pk_fma_f32 v[2:3], v[2:3], v[6:7], v[10:11]
	s_nop 0
	v_cvt_pk_bf16_f32 v2, v2, v3
	v_cvt_pk_bf16_f32 v3, v4, v5
	global_store_dwordx2 v141, v[2:3], s[4:5]
	s_cbranch_scc0 .LBB0_105

.LBB0_252:
	s_add_u32 s12, s54, 0xfff00080
	s_addc_u32 s13, s55, -1
	s_add_i32 s95, 0, 0x10000
	s_cmp_eq_u32 s94, 60
	s_cselect_b32 s65, s47, s13
	s_cselect_b32 s64, s66, s12
	v_add_u32_e32 v142, s95, v144
	s_cselect_b32 s63, s45, s61
	s_cselect_b32 s62, vcc_lo, vcc_hi
	s_add_i32 s56, 0, 0x14000
	ds_read_b128 v[148:151], v142
	ds_read_b128 v[152:155], v142 offset:1024
	ds_read_b128 v[156:159], v142 offset:2048
	ds_read_b128 v[160:163], v142 offset:3072
	v_add_u32_e32 v142, s56, v144
	ds_read_b128 v[164:167], v142
	ds_read_b128 v[168:171], v142 offset:1024
	ds_read_b128 v[172:175], v142 offset:2048
	ds_read_b128 v[176:179], v142 offset:3072
	v_lshl_add_u64 v[142:143], s[54:55], 0, v[136:137]
	s_add_i32 m0, s53, 0xc000
	ds_read_b128 v[180:183], v146
	ds_read_b128 v[184:187], v146 offset:1024
	ds_read_b128 v[210:213], v146 offset:2048
	ds_read_b128 v[214:217], v146 offset:3072
	ds_read_b128 v[218:221], v146 offset:4096
	ds_read_b128 v[222:225], v146 offset:5120
	ds_read_b128 v[226:229], v146 offset:6144
	ds_read_b128 v[230:233], v146 offset:7168
	global_load_lds_dwordx4 v[142:143], off
	v_lshl_add_u64 v[142:143], s[54:55], 0, v[138:139]
	s_add_i32 m0, s53, 0xe000
	s_nop 0
	global_load_lds_dwordx4 v[142:143], off
	s_waitcnt vmcnt(8)
	s_waitcnt lgkmcnt(0)
	s_barrier
	s_setprio 1
	s_waitcnt lgkmcnt(0)
	v_mfma_f32_16x16x32_bf16 v[126:129], v[148:151], v[180:183], v[126:129]
	v_mfma_f32_16x16x32_bf16 v[126:129], v[152:155], v[184:187], v[126:129]
	v_mfma_f32_16x16x32_bf16 v[122:125], v[156:159], v[180:183], v[122:125]
	v_mfma_f32_16x16x32_bf16 v[122:125], v[160:163], v[184:187], v[122:125]
	v_mfma_f32_16x16x32_bf16 v[114:117], v[148:151], v[210:213], v[114:117]
	v_mfma_f32_16x16x32_bf16 v[114:117], v[152:155], v[214:217], v[114:117]
	v_mfma_f32_16x16x32_bf16 v[106:109], v[156:159], v[210:213], v[106:109]
	v_mfma_f32_16x16x32_bf16 v[106:109], v[160:163], v[214:217], v[106:109]
	v_mfma_f32_16x16x32_bf16 v[98:101], v[148:151], v[218:221], v[98:101]
	v_mfma_f32_16x16x32_bf16 v[98:101], v[152:155], v[222:225], v[98:101]
	v_mfma_f32_16x16x32_bf16 v[90:93], v[156:159], v[218:221], v[90:93]
	v_mfma_f32_16x16x32_bf16 v[90:93], v[160:163], v[222:225], v[90:93]
	v_mfma_f32_16x16x32_bf16 v[82:85], v[148:151], v[226:229], v[82:85]
	v_mfma_f32_16x16x32_bf16 v[82:85], v[152:155], v[230:233], v[82:85]
	v_mfma_f32_16x16x32_bf16 v[74:77], v[156:159], v[226:229], v[74:77]
	v_mfma_f32_16x16x32_bf16 v[74:77], v[160:163], v[230:233], v[74:77]
	s_setprio 0
	s_setprio 1
	v_mfma_f32_16x16x32_bf16 v[118:121], v[164:167], v[180:183], v[118:121]
	v_mfma_f32_16x16x32_bf16 v[118:121], v[168:171], v[184:187], v[118:121]
	v_mfma_f32_16x16x32_bf16 v[110:113], v[172:175], v[180:183], v[110:113]
	v_mfma_f32_16x16x32_bf16 v[110:113], v[176:179], v[184:187], v[110:113]
	v_mfma_f32_16x16x32_bf16 v[102:105], v[164:167], v[210:213], v[102:105]
	v_mfma_f32_16x16x32_bf16 v[102:105], v[168:171], v[214:217], v[102:105]
	v_mfma_f32_16x16x32_bf16 v[94:97], v[172:175], v[210:213], v[94:97]
	v_mfma_f32_16x16x32_bf16 v[94:97], v[176:179], v[214:217], v[94:97]
	v_mfma_f32_16x16x32_bf16 v[86:89], v[164:167], v[218:221], v[86:89]
	v_mfma_f32_16x16x32_bf16 v[86:89], v[168:171], v[222:225], v[86:89]
	v_mfma_f32_16x16x32_bf16 v[78:81], v[172:175], v[218:221], v[78:81]
	v_mfma_f32_16x16x32_bf16 v[78:81], v[176:179], v[222:225], v[78:81]
	v_mfma_f32_16x16x32_bf16 v[70:73], v[164:167], v[226:229], v[70:73]
	v_mfma_f32_16x16x32_bf16 v[70:73], v[168:171], v[230:233], v[70:73]
	v_mfma_f32_16x16x32_bf16 v[66:69], v[172:175], v[226:229], v[66:69]
	v_mfma_f32_16x16x32_bf16 v[66:69], v[176:179], v[230:233], v[66:69]
	s_setprio 0
	s_barrier
	s_add_i32 s12, s95, s82
	v_lshl_add_u64 v[142:143], s[62:63], 0, v[190:191]
	s_mov_b32 m0, s12
	ds_read_b128 v[180:183], v146 offset:16384
	ds_read_b128 v[184:187], v146 offset:17408
	ds_read_b128 v[210:213], v146 offset:18432
	ds_read_b128 v[214:217], v146 offset:19456
	ds_read_b128 v[218:221], v146 offset:20480
	ds_read_b128 v[222:225], v146 offset:21504
	ds_read_b128 v[226:229], v146 offset:22528
	ds_read_b128 v[230:233], v146 offset:23552
	global_load_lds_dwordx4 v[142:143], off
	s_add_i32 m0, s12, 0x2000
	s_add_u32 s12, s62, 0x100000
	v_lshl_add_u64 v[188:189], s[62:63], 0, v[134:135]
	s_addc_u32 s13, s63, 0
	s_add_i32 s56, s56, s82
	global_load_lds_dwordx4 v[188:189], off
	v_lshl_add_u64 v[234:235], s[12:13], 0, v[190:191]
	s_mov_b32 m0, s56
	v_lshl_add_u64 v[244:245], s[64:65], 0, v[132:133]
	global_load_lds_dwordx4 v[234:235], off
	v_lshl_add_u64 v[234:235], s[12:13], 0, v[134:135]
	s_add_i32 m0, s56, 0x2000
	s_nop 0
	global_load_lds_dwordx4 v[234:235], off
	v_lshl_add_u64 v[234:235], s[64:65], 0, v[130:131]
	s_mov_b32 m0, s53
	s_nop 0
	global_load_lds_dwordx4 v[234:235], off
	s_mov_b32 m0, s84
	s_nop 0
	global_load_lds_dwordx4 v[244:245], off
	s_waitcnt vmcnt(8)
	s_waitcnt lgkmcnt(0)
	s_barrier
	s_setprio 1
	s_waitcnt lgkmcnt(0)
	v_mfma_f32_16x16x32_bf16 v[62:65], v[148:151], v[180:183], v[62:65]
	v_mfma_f32_16x16x32_bf16 v[62:65], v[152:155], v[184:187], v[62:65]
	v_mfma_f32_16x16x32_bf16 v[58:61], v[156:159], v[180:183], v[58:61]
	v_mfma_f32_16x16x32_bf16 v[58:61], v[160:163], v[184:187], v[58:61]
	v_mfma_f32_16x16x32_bf16 v[50:53], v[148:151], v[210:213], v[50:53]
	v_mfma_f32_16x16x32_bf16 v[50:53], v[152:155], v[214:217], v[50:53]
	v_mfma_f32_16x16x32_bf16 v[42:45], v[156:159], v[210:213], v[42:45]
	v_mfma_f32_16x16x32_bf16 v[42:45], v[160:163], v[214:217], v[42:45]
	v_mfma_f32_16x16x32_bf16 v[34:37], v[148:151], v[218:221], v[34:37]
	v_mfma_f32_16x16x32_bf16 v[34:37], v[152:155], v[222:225], v[34:37]
	v_mfma_f32_16x16x32_bf16 v[26:29], v[156:159], v[218:221], v[26:29]
	v_mfma_f32_16x16x32_bf16 v[26:29], v[160:163], v[222:225], v[26:29]
	v_mfma_f32_16x16x32_bf16 v[18:21], v[148:151], v[226:229], v[18:21]
	v_mfma_f32_16x16x32_bf16 v[18:21], v[152:155], v[230:233], v[18:21]
	v_mfma_f32_16x16x32_bf16 v[10:13], v[156:159], v[226:229], v[10:13]
	v_mfma_f32_16x16x32_bf16 v[10:13], v[160:163], v[230:233], v[10:13]
	s_setprio 0
	s_setprio 1
	v_mfma_f32_16x16x32_bf16 v[54:57], v[164:167], v[180:183], v[54:57]
	v_mfma_f32_16x16x32_bf16 v[54:57], v[168:171], v[184:187], v[54:57]
	v_mfma_f32_16x16x32_bf16 v[46:49], v[172:175], v[180:183], v[46:49]
	v_mfma_f32_16x16x32_bf16 v[46:49], v[176:179], v[184:187], v[46:49]
	v_mfma_f32_16x16x32_bf16 v[38:41], v[164:167], v[210:213], v[38:41]
	v_mfma_f32_16x16x32_bf16 v[38:41], v[168:171], v[214:217], v[38:41]
	v_mfma_f32_16x16x32_bf16 v[30:33], v[172:175], v[210:213], v[30:33]
	v_mfma_f32_16x16x32_bf16 v[30:33], v[176:179], v[214:217], v[30:33]
	v_mfma_f32_16x16x32_bf16 v[22:25], v[164:167], v[218:221], v[22:25]
	v_mfma_f32_16x16x32_bf16 v[22:25], v[168:171], v[222:225], v[22:25]
	v_mfma_f32_16x16x32_bf16 v[14:17], v[172:175], v[218:221], v[14:17]
	v_mfma_f32_16x16x32_bf16 v[14:17], v[176:179], v[222:225], v[14:17]
	v_mfma_f32_16x16x32_bf16 v[6:9], v[164:167], v[226:229], v[6:9]
	v_mfma_f32_16x16x32_bf16 v[6:9], v[168:171], v[230:233], v[6:9]
	v_mfma_f32_16x16x32_bf16 v[2:5], v[172:175], v[226:229], v[2:5]
	v_mfma_f32_16x16x32_bf16 v[2:5], v[176:179], v[230:233], v[2:5]
	s_setprio 0
	s_barrier
	s_add_i32 s56, 0, 0x18000
	v_add_u32_e32 v147, s56, v144
	s_add_i32 s95, 0, 0x1c000
	ds_read_b128 v[148:151], v147
	ds_read_b128 v[152:155], v147 offset:1024
	ds_read_b128 v[156:159], v147 offset:2048
	ds_read_b128 v[160:163], v147 offset:3072
	v_add_u32_e32 v147, s95, v144
	ds_read_b128 v[164:167], v147
	ds_read_b128 v[168:171], v147 offset:1024
	ds_read_b128 v[172:175], v147 offset:2048
	ds_read_b128 v[176:179], v147 offset:3072
	s_add_u32 s12, s64, 0x100000
	s_addc_u32 s13, s65, 0
	s_mov_b32 m0, s85
	v_lshl_add_u64 v[246:247], s[12:13], 0, v[130:131]
	ds_read_b128 v[180:183], v146 offset:32768
	ds_read_b128 v[184:187], v146 offset:33792
	ds_read_b128 v[210:213], v146 offset:34816
	ds_read_b128 v[214:217], v146 offset:35840
	ds_read_b128 v[218:221], v146 offset:36864
	ds_read_b128 v[222:225], v146 offset:37888
	ds_read_b128 v[226:229], v146 offset:38912
	ds_read_b128 v[230:233], v146 offset:39936
	global_load_lds_dwordx4 v[246:247], off
	v_lshl_add_u64 v[246:247], s[12:13], 0, v[132:133]
	s_mov_b32 m0, s86
	s_nop 0
	global_load_lds_dwordx4 v[246:247], off
	s_waitcnt vmcnt(8)
	s_waitcnt lgkmcnt(0)
	s_barrier
	s_setprio 1
	s_waitcnt lgkmcnt(0)
	v_mfma_f32_16x16x32_bf16 v[126:129], v[148:151], v[180:183], v[126:129]
	v_mfma_f32_16x16x32_bf16 v[126:129], v[152:155], v[184:187], v[126:129]
	v_mfma_f32_16x16x32_bf16 v[122:125], v[156:159], v[180:183], v[122:125]
	v_mfma_f32_16x16x32_bf16 v[122:125], v[160:163], v[184:187], v[122:125]
	v_mfma_f32_16x16x32_bf16 v[114:117], v[148:151], v[210:213], v[114:117]
	v_mfma_f32_16x16x32_bf16 v[114:117], v[152:155], v[214:217], v[114:117]
	v_mfma_f32_16x16x32_bf16 v[106:109], v[156:159], v[210:213], v[106:109]
	v_mfma_f32_16x16x32_bf16 v[106:109], v[160:163], v[214:217], v[106:109]
	v_mfma_f32_16x16x32_bf16 v[98:101], v[148:151], v[218:221], v[98:101]
	v_mfma_f32_16x16x32_bf16 v[98:101], v[152:155], v[222:225], v[98:101]
	v_mfma_f32_16x16x32_bf16 v[90:93], v[156:159], v[218:221], v[90:93]
	v_mfma_f32_16x16x32_bf16 v[90:93], v[160:163], v[222:225], v[90:93]
	v_mfma_f32_16x16x32_bf16 v[82:85], v[148:151], v[226:229], v[82:85]
	v_mfma_f32_16x16x32_bf16 v[82:85], v[152:155], v[230:233], v[82:85]
	v_mfma_f32_16x16x32_bf16 v[74:77], v[156:159], v[226:229], v[74:77]
	v_mfma_f32_16x16x32_bf16 v[74:77], v[160:163], v[230:233], v[74:77]
	s_setprio 0
	s_setprio 1
	v_mfma_f32_16x16x32_bf16 v[118:121], v[164:167], v[180:183], v[118:121]
	v_mfma_f32_16x16x32_bf16 v[118:121], v[168:171], v[184:187], v[118:121]
	v_mfma_f32_16x16x32_bf16 v[110:113], v[172:175], v[180:183], v[110:113]
	v_mfma_f32_16x16x32_bf16 v[110:113], v[176:179], v[184:187], v[110:113]
	v_mfma_f32_16x16x32_bf16 v[102:105], v[164:167], v[210:213], v[102:105]
	v_mfma_f32_16x16x32_bf16 v[102:105], v[168:171], v[214:217], v[102:105]
	v_mfma_f32_16x16x32_bf16 v[94:97], v[172:175], v[210:213], v[94:97]
	v_mfma_f32_16x16x32_bf16 v[94:97], v[176:179], v[214:217], v[94:97]
	v_mfma_f32_16x16x32_bf16 v[86:89], v[164:167], v[218:221], v[86:89]
	v_mfma_f32_16x16x32_bf16 v[86:89], v[168:171], v[222:225], v[86:89]
	v_mfma_f32_16x16x32_bf16 v[78:81], v[172:175], v[218:221], v[78:81]
	v_mfma_f32_16x16x32_bf16 v[78:81], v[176:179], v[222:225], v[78:81]
	v_mfma_f32_16x16x32_bf16 v[70:73], v[164:167], v[226:229], v[70:73]
	v_mfma_f32_16x16x32_bf16 v[70:73], v[168:171], v[230:233], v[70:73]
	v_mfma_f32_16x16x32_bf16 v[66:69], v[172:175], v[226:229], v[66:69]
	v_mfma_f32_16x16x32_bf16 v[66:69], v[176:179], v[230:233], v[66:69]
	s_setprio 0
	s_barrier
	s_add_i32 s12, s56, s82
	v_lshl_add_u64 v[142:143], v[142:143], 0, s[34:35]
	s_mov_b32 m0, s12
	ds_read_b128 v[180:183], v146 offset:49152
	ds_read_b128 v[184:187], v146 offset:50176
	ds_read_b128 v[210:213], v146 offset:51200
	ds_read_b128 v[214:217], v146 offset:52224
	ds_read_b128 v[218:221], v146 offset:53248
	ds_read_b128 v[222:225], v146 offset:54272
	ds_read_b128 v[226:229], v146 offset:55296
	ds_read_b128 v[230:233], v146 offset:56320
	global_load_lds_dwordx4 v[142:143], off
	s_add_i32 m0, s12, 0x2000
	s_add_u32 s12, s62, 0x100080
	v_lshl_add_u64 v[142:143], v[188:189], 0, s[34:35]
	s_addc_u32 s13, s63, 0
	s_add_i32 s56, s95, s82
	global_load_lds_dwordx4 v[142:143], off
	v_lshl_add_u64 v[142:143], s[12:13], 0, v[190:191]
	s_mov_b32 m0, s56
	s_nop 0
	global_load_lds_dwordx4 v[142:143], off
	v_lshl_add_u64 v[142:143], s[12:13], 0, v[134:135]
	s_add_i32 m0, s56, 0x2000
	s_nop 0
	global_load_lds_dwordx4 v[142:143], off
	v_lshl_add_u64 v[142:143], v[234:235], 0, s[34:35]
	s_mov_b32 m0, s90
	s_nop 0
	global_load_lds_dwordx4 v[142:143], off
	v_lshl_add_u64 v[142:143], v[244:245], 0, s[34:35]
	s_mov_b32 m0, s97
	s_nop 0
	global_load_lds_dwordx4 v[142:143], off
	s_waitcnt vmcnt(8)
	s_waitcnt lgkmcnt(0)
	s_barrier
	s_setprio 1
	s_waitcnt lgkmcnt(0)
	v_mfma_f32_16x16x32_bf16 v[62:65], v[148:151], v[180:183], v[62:65]
	v_mfma_f32_16x16x32_bf16 v[62:65], v[152:155], v[184:187], v[62:65]
	v_mfma_f32_16x16x32_bf16 v[58:61], v[156:159], v[180:183], v[58:61]
	v_mfma_f32_16x16x32_bf16 v[58:61], v[160:163], v[184:187], v[58:61]
	v_mfma_f32_16x16x32_bf16 v[50:53], v[148:151], v[210:213], v[50:53]
	v_mfma_f32_16x16x32_bf16 v[50:53], v[152:155], v[214:217], v[50:53]
	v_mfma_f32_16x16x32_bf16 v[42:45], v[156:159], v[210:213], v[42:45]
	v_mfma_f32_16x16x32_bf16 v[42:45], v[160:163], v[214:217], v[42:45]
	v_mfma_f32_16x16x32_bf16 v[34:37], v[148:151], v[218:221], v[34:37]
	v_mfma_f32_16x16x32_bf16 v[34:37], v[152:155], v[222:225], v[34:37]
	v_mfma_f32_16x16x32_bf16 v[26:29], v[156:159], v[218:221], v[26:29]
	v_mfma_f32_16x16x32_bf16 v[26:29], v[160:163], v[222:225], v[26:29]
	v_mfma_f32_16x16x32_bf16 v[18:21], v[148:151], v[226:229], v[18:21]
	v_mfma_f32_16x16x32_bf16 v[18:21], v[152:155], v[230:233], v[18:21]
	v_mfma_f32_16x16x32_bf16 v[10:13], v[156:159], v[226:229], v[10:13]
	v_mfma_f32_16x16x32_bf16 v[10:13], v[160:163], v[230:233], v[10:13]
	s_setprio 0
	s_setprio 1
	v_mfma_f32_16x16x32_bf16 v[54:57], v[164:167], v[180:183], v[54:57]
	v_mfma_f32_16x16x32_bf16 v[54:57], v[168:171], v[184:187], v[54:57]
	v_mfma_f32_16x16x32_bf16 v[46:49], v[172:175], v[180:183], v[46:49]
	v_mfma_f32_16x16x32_bf16 v[46:49], v[176:179], v[184:187], v[46:49]
	v_mfma_f32_16x16x32_bf16 v[38:41], v[164:167], v[210:213], v[38:41]
	v_mfma_f32_16x16x32_bf16 v[38:41], v[168:171], v[214:217], v[38:41]
	v_mfma_f32_16x16x32_bf16 v[30:33], v[172:175], v[210:213], v[30:33]
	v_mfma_f32_16x16x32_bf16 v[30:33], v[176:179], v[214:217], v[30:33]
	v_mfma_f32_16x16x32_bf16 v[22:25], v[164:167], v[218:221], v[22:25]
	v_mfma_f32_16x16x32_bf16 v[22:25], v[168:171], v[222:225], v[22:25]
	v_mfma_f32_16x16x32_bf16 v[14:17], v[172:175], v[218:221], v[14:17]
	v_mfma_f32_16x16x32_bf16 v[14:17], v[176:179], v[222:225], v[14:17]
	v_mfma_f32_16x16x32_bf16 v[6:9], v[164:167], v[226:229], v[6:9]
	v_mfma_f32_16x16x32_bf16 v[6:9], v[168:171], v[230:233], v[6:9]
	v_mfma_f32_16x16x32_bf16 v[2:5], v[172:175], v[226:229], v[2:5]
	v_mfma_f32_16x16x32_bf16 v[2:5], v[176:179], v[230:233], v[2:5]
	s_setprio 0
	s_barrier
	s_add_i32 s94, s94, 2
	s_add_u32 s54, s54, 0x100
	s_addc_u32 s55, s55, 0
	s_add_u32 vcc_hi, vcc_hi, 0x100
	s_addc_u32 s61, s61, 0
	s_cmp_gt_u32 s94, 61
	s_cbranch_scc0 .LBB0_252
	s_and_b64 vcc, exec, s[42:43]
	s_cbranch_vccz .LBB0_255
	s_barrier

.LBB0_692:
	s_add_u32 s12, s40, 0xfffc0080
	s_addc_u32 s13, s41, -1
	s_add_i32 s56, 0, 0x10000
	s_cmp_eq_u32 s74, 12
	s_cselect_b32 s63, s47, s13
	s_cselect_b32 s62, s71, s12
	s_cselect_b32 s55, s45, s61
	s_cselect_b32 s54, s72, s73
	s_add_i32 s75, 0, 0x14000
	v_add_u32_e32 v142, s56, v160
	v_add_u32_e32 v163, s75, v160
	ds_read_b128 v[130:133], v142
	ds_read_b128 v[134:137], v142 offset:1024
	ds_read_b128 v[138:141], v142 offset:2048
	ds_read_b128 v[142:145], v142 offset:3072
	ds_read_b128 v[156:159], v163
	ds_read_b128 v[164:167], v163 offset:1024
	ds_read_b128 v[168:171], v163 offset:2048
	ds_read_b128 v[172:175], v163 offset:3072
	v_lshl_add_u64 v[188:189], s[40:41], 0, v[152:153]
	s_add_i32 m0, s53, 0xc000
	ds_read_b128 v[176:179], v162
	ds_read_b128 v[180:183], v162 offset:1024
	ds_read_b128 v[184:187], v162 offset:2048
	ds_read_b128 v[210:213], v162 offset:3072
	ds_read_b128 v[214:217], v162 offset:4096
	ds_read_b128 v[218:221], v162 offset:5120
	ds_read_b128 v[222:225], v162 offset:6144
	ds_read_b128 v[226:229], v162 offset:7168
	global_load_lds_dwordx4 v[188:189], off
	v_lshl_add_u64 v[188:189], s[40:41], 0, v[154:155]
	s_add_i32 m0, s53, 0xe000
	s_nop 0
	global_load_lds_dwordx4 v[188:189], off
	s_waitcnt vmcnt(8)
	s_waitcnt lgkmcnt(0)
	s_barrier
	s_setprio 1
	s_waitcnt lgkmcnt(0)
	v_mfma_f32_16x16x32_bf16 v[126:129], v[130:133], v[176:179], v[126:129]
	v_mfma_f32_16x16x32_bf16 v[126:129], v[134:137], v[180:183], v[126:129]
	v_mfma_f32_16x16x32_bf16 v[122:125], v[138:141], v[176:179], v[122:125]
	v_mfma_f32_16x16x32_bf16 v[122:125], v[142:145], v[180:183], v[122:125]
	v_mfma_f32_16x16x32_bf16 v[114:117], v[130:133], v[184:187], v[114:117]
	v_mfma_f32_16x16x32_bf16 v[114:117], v[134:137], v[210:213], v[114:117]
	v_mfma_f32_16x16x32_bf16 v[106:109], v[138:141], v[184:187], v[106:109]
	v_mfma_f32_16x16x32_bf16 v[106:109], v[142:145], v[210:213], v[106:109]
	v_mfma_f32_16x16x32_bf16 v[98:101], v[130:133], v[214:217], v[98:101]
	v_mfma_f32_16x16x32_bf16 v[98:101], v[134:137], v[218:221], v[98:101]
	v_mfma_f32_16x16x32_bf16 v[90:93], v[138:141], v[214:217], v[90:93]
	v_mfma_f32_16x16x32_bf16 v[90:93], v[142:145], v[218:221], v[90:93]
	v_mfma_f32_16x16x32_bf16 v[82:85], v[130:133], v[222:225], v[82:85]
	v_mfma_f32_16x16x32_bf16 v[82:85], v[134:137], v[226:229], v[82:85]
	v_mfma_f32_16x16x32_bf16 v[74:77], v[138:141], v[222:225], v[74:77]
	v_mfma_f32_16x16x32_bf16 v[74:77], v[142:145], v[226:229], v[74:77]
	s_setprio 0
	s_setprio 1
	v_mfma_f32_16x16x32_bf16 v[118:121], v[156:159], v[176:179], v[118:121]
	v_mfma_f32_16x16x32_bf16 v[118:121], v[164:167], v[180:183], v[118:121]
	v_mfma_f32_16x16x32_bf16 v[110:113], v[168:171], v[176:179], v[110:113]
	v_mfma_f32_16x16x32_bf16 v[110:113], v[172:175], v[180:183], v[110:113]
	v_mfma_f32_16x16x32_bf16 v[102:105], v[156:159], v[184:187], v[102:105]
	v_mfma_f32_16x16x32_bf16 v[102:105], v[164:167], v[210:213], v[102:105]
	v_mfma_f32_16x16x32_bf16 v[94:97], v[168:171], v[184:187], v[94:97]
	v_mfma_f32_16x16x32_bf16 v[94:97], v[172:175], v[210:213], v[94:97]
	v_mfma_f32_16x16x32_bf16 v[86:89], v[156:159], v[214:217], v[86:89]
	v_mfma_f32_16x16x32_bf16 v[86:89], v[164:167], v[218:221], v[86:89]
	v_mfma_f32_16x16x32_bf16 v[78:81], v[168:171], v[214:217], v[78:81]
	v_mfma_f32_16x16x32_bf16 v[78:81], v[172:175], v[218:221], v[78:81]
	v_mfma_f32_16x16x32_bf16 v[70:73], v[156:159], v[222:225], v[70:73]
	v_mfma_f32_16x16x32_bf16 v[70:73], v[164:167], v[226:229], v[70:73]
	v_mfma_f32_16x16x32_bf16 v[66:69], v[168:171], v[222:225], v[66:69]
	v_mfma_f32_16x16x32_bf16 v[66:69], v[172:175], v[226:229], v[66:69]
	s_setprio 0
	s_barrier
	s_add_i32 s12, s56, s59
	v_lshl_add_u64 v[188:189], s[54:55], 0, v[190:191]
	s_mov_b32 m0, s12
	ds_read_b128 v[176:179], v162 offset:16384
	ds_read_b128 v[180:183], v162 offset:17408
	ds_read_b128 v[184:187], v162 offset:18432
	ds_read_b128 v[210:213], v162 offset:19456
	ds_read_b128 v[214:217], v162 offset:20480
	ds_read_b128 v[218:221], v162 offset:21504
	ds_read_b128 v[222:225], v162 offset:22528
	ds_read_b128 v[226:229], v162 offset:23552
	global_load_lds_dwordx4 v[188:189], off
	s_add_i32 m0, s12, 0x2000
	s_add_u32 s12, s54, 0x40000
	v_lshl_add_u64 v[230:231], s[54:55], 0, v[150:151]
	s_addc_u32 s13, s55, 0
	s_add_i32 s56, s75, s59
	global_load_lds_dwordx4 v[230:231], off
	v_lshl_add_u64 v[232:233], s[12:13], 0, v[190:191]
	s_mov_b32 m0, s56
	v_lshl_add_u64 v[234:235], s[62:63], 0, v[148:149]
	global_load_lds_dwordx4 v[232:233], off
	v_lshl_add_u64 v[232:233], s[12:13], 0, v[150:151]
	s_add_i32 m0, s56, 0x2000
	s_nop 0
	global_load_lds_dwordx4 v[232:233], off
	v_lshl_add_u64 v[232:233], s[62:63], 0, v[146:147]
	s_mov_b32 m0, s53
	s_nop 0
	global_load_lds_dwordx4 v[232:233], off
	s_mov_b32 m0, s60
	s_nop 0
	global_load_lds_dwordx4 v[234:235], off
	s_waitcnt vmcnt(8)
	s_waitcnt lgkmcnt(0)
	s_barrier
	s_setprio 1
	s_waitcnt lgkmcnt(0)
	v_mfma_f32_16x16x32_bf16 v[62:65], v[130:133], v[176:179], v[62:65]
	v_mfma_f32_16x16x32_bf16 v[62:65], v[134:137], v[180:183], v[62:65]
	v_mfma_f32_16x16x32_bf16 v[58:61], v[138:141], v[176:179], v[58:61]
	v_mfma_f32_16x16x32_bf16 v[58:61], v[142:145], v[180:183], v[58:61]
	v_mfma_f32_16x16x32_bf16 v[50:53], v[130:133], v[184:187], v[50:53]
	v_mfma_f32_16x16x32_bf16 v[50:53], v[134:137], v[210:213], v[50:53]
	v_mfma_f32_16x16x32_bf16 v[42:45], v[138:141], v[184:187], v[42:45]
	v_mfma_f32_16x16x32_bf16 v[42:45], v[142:145], v[210:213], v[42:45]
	v_mfma_f32_16x16x32_bf16 v[34:37], v[130:133], v[214:217], v[34:37]
	v_mfma_f32_16x16x32_bf16 v[34:37], v[134:137], v[218:221], v[34:37]
	v_mfma_f32_16x16x32_bf16 v[26:29], v[138:141], v[214:217], v[26:29]
	v_mfma_f32_16x16x32_bf16 v[26:29], v[142:145], v[218:221], v[26:29]
	v_mfma_f32_16x16x32_bf16 v[18:21], v[130:133], v[222:225], v[18:21]
	v_mfma_f32_16x16x32_bf16 v[18:21], v[134:137], v[226:229], v[18:21]
	v_mfma_f32_16x16x32_bf16 v[10:13], v[138:141], v[222:225], v[10:13]
	v_mfma_f32_16x16x32_bf16 v[10:13], v[142:145], v[226:229], v[10:13]
	s_setprio 0
	s_setprio 1
	v_mfma_f32_16x16x32_bf16 v[54:57], v[156:159], v[176:179], v[54:57]
	v_mfma_f32_16x16x32_bf16 v[54:57], v[164:167], v[180:183], v[54:57]
	v_mfma_f32_16x16x32_bf16 v[46:49], v[168:171], v[176:179], v[46:49]
	v_mfma_f32_16x16x32_bf16 v[46:49], v[172:175], v[180:183], v[46:49]
	v_mfma_f32_16x16x32_bf16 v[38:41], v[156:159], v[184:187], v[38:41]
	v_mfma_f32_16x16x32_bf16 v[38:41], v[164:167], v[210:213], v[38:41]
	v_mfma_f32_16x16x32_bf16 v[30:33], v[168:171], v[184:187], v[30:33]
	v_mfma_f32_16x16x32_bf16 v[30:33], v[172:175], v[210:213], v[30:33]
	v_mfma_f32_16x16x32_bf16 v[22:25], v[156:159], v[214:217], v[22:25]
	v_mfma_f32_16x16x32_bf16 v[22:25], v[164:167], v[218:221], v[22:25]
	v_mfma_f32_16x16x32_bf16 v[14:17], v[168:171], v[214:217], v[14:17]
	v_mfma_f32_16x16x32_bf16 v[14:17], v[172:175], v[218:221], v[14:17]
	v_mfma_f32_16x16x32_bf16 v[6:9], v[156:159], v[222:225], v[6:9]
	v_mfma_f32_16x16x32_bf16 v[6:9], v[164:167], v[226:229], v[6:9]
	v_mfma_f32_16x16x32_bf16 v[2:5], v[168:171], v[222:225], v[2:5]
	v_mfma_f32_16x16x32_bf16 v[2:5], v[172:175], v[226:229], v[2:5]
	s_setprio 0
	s_barrier
	s_add_i32 s56, 0, 0x18000
	s_add_i32 s75, 0, 0x1c000
	v_add_u32_e32 v142, s56, v160
	v_add_u32_e32 v163, s75, v160
	ds_read_b128 v[130:133], v142
	ds_read_b128 v[134:137], v142 offset:1024
	ds_read_b128 v[138:141], v142 offset:2048
	ds_read_b128 v[142:145], v142 offset:3072
	ds_read_b128 v[156:159], v163
	ds_read_b128 v[164:167], v163 offset:1024
	ds_read_b128 v[168:171], v163 offset:2048
	ds_read_b128 v[172:175], v163 offset:3072
	s_add_u32 s12, s62, 0x40000
	s_addc_u32 s13, s63, 0
	s_mov_b32 m0, s64
	v_lshl_add_u64 v[244:245], s[12:13], 0, v[146:147]
	ds_read_b128 v[176:179], v162 offset:32768
	ds_read_b128 v[180:183], v162 offset:33792
	ds_read_b128 v[184:187], v162 offset:34816
	ds_read_b128 v[210:213], v162 offset:35840
	ds_read_b128 v[214:217], v162 offset:36864
	ds_read_b128 v[218:221], v162 offset:37888
	ds_read_b128 v[222:225], v162 offset:38912
	ds_read_b128 v[226:229], v162 offset:39936
	global_load_lds_dwordx4 v[244:245], off
	v_lshl_add_u64 v[244:245], s[12:13], 0, v[148:149]
	s_mov_b32 m0, s65
	s_nop 0
	global_load_lds_dwordx4 v[244:245], off
	s_waitcnt vmcnt(8)
	s_waitcnt lgkmcnt(0)
	s_barrier
	s_setprio 1
	s_waitcnt lgkmcnt(0)
	v_mfma_f32_16x16x32_bf16 v[126:129], v[130:133], v[176:179], v[126:129]
	v_mfma_f32_16x16x32_bf16 v[126:129], v[134:137], v[180:183], v[126:129]
	v_mfma_f32_16x16x32_bf16 v[122:125], v[138:141], v[176:179], v[122:125]
	v_mfma_f32_16x16x32_bf16 v[122:125], v[142:145], v[180:183], v[122:125]
	v_mfma_f32_16x16x32_bf16 v[114:117], v[130:133], v[184:187], v[114:117]
	v_mfma_f32_16x16x32_bf16 v[114:117], v[134:137], v[210:213], v[114:117]
	v_mfma_f32_16x16x32_bf16 v[106:109], v[138:141], v[184:187], v[106:109]
	v_mfma_f32_16x16x32_bf16 v[106:109], v[142:145], v[210:213], v[106:109]
	v_mfma_f32_16x16x32_bf16 v[98:101], v[130:133], v[214:217], v[98:101]
	v_mfma_f32_16x16x32_bf16 v[98:101], v[134:137], v[218:221], v[98:101]
	v_mfma_f32_16x16x32_bf16 v[90:93], v[138:141], v[214:217], v[90:93]
	v_mfma_f32_16x16x32_bf16 v[90:93], v[142:145], v[218:221], v[90:93]
	v_mfma_f32_16x16x32_bf16 v[82:85], v[130:133], v[222:225], v[82:85]
	v_mfma_f32_16x16x32_bf16 v[82:85], v[134:137], v[226:229], v[82:85]
	v_mfma_f32_16x16x32_bf16 v[74:77], v[138:141], v[222:225], v[74:77]
	v_mfma_f32_16x16x32_bf16 v[74:77], v[142:145], v[226:229], v[74:77]
	s_setprio 0
	s_setprio 1
	v_mfma_f32_16x16x32_bf16 v[118:121], v[156:159], v[176:179], v[118:121]
	v_mfma_f32_16x16x32_bf16 v[118:121], v[164:167], v[180:183], v[118:121]
	v_mfma_f32_16x16x32_bf16 v[110:113], v[168:171], v[176:179], v[110:113]
	v_mfma_f32_16x16x32_bf16 v[110:113], v[172:175], v[180:183], v[110:113]
	v_mfma_f32_16x16x32_bf16 v[102:105], v[156:159], v[184:187], v[102:105]
	v_mfma_f32_16x16x32_bf16 v[102:105], v[164:167], v[210:213], v[102:105]
	v_mfma_f32_16x16x32_bf16 v[94:97], v[168:171], v[184:187], v[94:97]
	v_mfma_f32_16x16x32_bf16 v[94:97], v[172:175], v[210:213], v[94:97]
	v_mfma_f32_16x16x32_bf16 v[86:89], v[156:159], v[214:217], v[86:89]
	v_mfma_f32_16x16x32_bf16 v[86:89], v[164:167], v[218:221], v[86:89]
	v_mfma_f32_16x16x32_bf16 v[78:81], v[168:171], v[214:217], v[78:81]
	v_mfma_f32_16x16x32_bf16 v[78:81], v[172:175], v[218:221], v[78:81]
	v_mfma_f32_16x16x32_bf16 v[70:73], v[156:159], v[222:225], v[70:73]
	v_mfma_f32_16x16x32_bf16 v[70:73], v[164:167], v[226:229], v[70:73]
	v_mfma_f32_16x16x32_bf16 v[66:69], v[168:171], v[222:225], v[66:69]
	v_mfma_f32_16x16x32_bf16 v[66:69], v[172:175], v[226:229], v[66:69]
	s_setprio 0
	s_barrier
	s_add_i32 s12, s56, s59
	v_lshl_add_u64 v[188:189], v[188:189], 0, s[34:35]
	s_mov_b32 m0, s12
	ds_read_b128 v[176:179], v162 offset:49152
	ds_read_b128 v[180:183], v162 offset:50176
	ds_read_b128 v[184:187], v162 offset:51200
	ds_read_b128 v[210:213], v162 offset:52224
	ds_read_b128 v[214:217], v162 offset:53248
	ds_read_b128 v[218:221], v162 offset:54272
	ds_read_b128 v[222:225], v162 offset:55296
	ds_read_b128 v[226:229], v162 offset:56320
	global_load_lds_dwordx4 v[188:189], off
	s_add_i32 m0, s12, 0x2000
	s_add_u32 s12, s54, 0x40080
	v_lshl_add_u64 v[188:189], v[230:231], 0, s[34:35]
	s_addc_u32 s13, s55, 0
	s_add_i32 s54, s75, s59
	global_load_lds_dwordx4 v[188:189], off
	v_lshl_add_u64 v[188:189], s[12:13], 0, v[190:191]
	s_mov_b32 m0, s54
	s_nop 0
	global_load_lds_dwordx4 v[188:189], off
	v_lshl_add_u64 v[188:189], s[12:13], 0, v[150:151]
	s_add_i32 m0, s54, 0x2000
	s_nop 0
	global_load_lds_dwordx4 v[188:189], off
	v_lshl_add_u64 v[188:189], v[232:233], 0, s[34:35]
	s_mov_b32 m0, s66
	s_nop 0
	global_load_lds_dwordx4 v[188:189], off
	v_lshl_add_u64 v[188:189], v[234:235], 0, s[34:35]
	s_mov_b32 m0, s68
	s_nop 0
	global_load_lds_dwordx4 v[188:189], off
	s_waitcnt vmcnt(8)
	s_waitcnt lgkmcnt(0)
	s_barrier
	s_setprio 1
	s_waitcnt lgkmcnt(0)
	v_mfma_f32_16x16x32_bf16 v[62:65], v[130:133], v[176:179], v[62:65]
	v_mfma_f32_16x16x32_bf16 v[62:65], v[134:137], v[180:183], v[62:65]
	v_mfma_f32_16x16x32_bf16 v[58:61], v[138:141], v[176:179], v[58:61]
	v_mfma_f32_16x16x32_bf16 v[58:61], v[142:145], v[180:183], v[58:61]
	v_mfma_f32_16x16x32_bf16 v[50:53], v[130:133], v[184:187], v[50:53]
	v_mfma_f32_16x16x32_bf16 v[50:53], v[134:137], v[210:213], v[50:53]
	v_mfma_f32_16x16x32_bf16 v[42:45], v[138:141], v[184:187], v[42:45]
	v_mfma_f32_16x16x32_bf16 v[42:45], v[142:145], v[210:213], v[42:45]
	v_mfma_f32_16x16x32_bf16 v[34:37], v[130:133], v[214:217], v[34:37]
	v_mfma_f32_16x16x32_bf16 v[34:37], v[134:137], v[218:221], v[34:37]
	v_mfma_f32_16x16x32_bf16 v[26:29], v[138:141], v[214:217], v[26:29]
	v_mfma_f32_16x16x32_bf16 v[26:29], v[142:145], v[218:221], v[26:29]
	v_mfma_f32_16x16x32_bf16 v[18:21], v[130:133], v[222:225], v[18:21]
	v_mfma_f32_16x16x32_bf16 v[18:21], v[134:137], v[226:229], v[18:21]
	v_mfma_f32_16x16x32_bf16 v[10:13], v[138:141], v[222:225], v[10:13]
	v_mfma_f32_16x16x32_bf16 v[10:13], v[142:145], v[226:229], v[10:13]
	s_setprio 0
	s_setprio 1
	v_mfma_f32_16x16x32_bf16 v[54:57], v[156:159], v[176:179], v[54:57]
	v_mfma_f32_16x16x32_bf16 v[54:57], v[164:167], v[180:183], v[54:57]
	v_mfma_f32_16x16x32_bf16 v[46:49], v[168:171], v[176:179], v[46:49]
	v_mfma_f32_16x16x32_bf16 v[46:49], v[172:175], v[180:183], v[46:49]
	v_mfma_f32_16x16x32_bf16 v[38:41], v[156:159], v[184:187], v[38:41]
	v_mfma_f32_16x16x32_bf16 v[38:41], v[164:167], v[210:213], v[38:41]
	v_mfma_f32_16x16x32_bf16 v[30:33], v[168:171], v[184:187], v[30:33]
	v_mfma_f32_16x16x32_bf16 v[30:33], v[172:175], v[210:213], v[30:33]
	v_mfma_f32_16x16x32_bf16 v[22:25], v[156:159], v[214:217], v[22:25]
	v_mfma_f32_16x16x32_bf16 v[22:25], v[164:167], v[218:221], v[22:25]
	v_mfma_f32_16x16x32_bf16 v[14:17], v[168:171], v[214:217], v[14:17]
	v_mfma_f32_16x16x32_bf16 v[14:17], v[172:175], v[218:221], v[14:17]
	v_mfma_f32_16x16x32_bf16 v[6:9], v[156:159], v[222:225], v[6:9]
	v_mfma_f32_16x16x32_bf16 v[6:9], v[164:167], v[226:229], v[6:9]
	v_mfma_f32_16x16x32_bf16 v[2:5], v[168:171], v[222:225], v[2:5]
	v_mfma_f32_16x16x32_bf16 v[2:5], v[172:175], v[226:229], v[2:5]
	s_setprio 0
	s_barrier
	s_add_i32 s74, s74, 2
	s_add_u32 s40, s40, 0x100
	s_addc_u32 s41, s41, 0
	s_add_u32 s73, s73, 0x100
	s_addc_u32 s61, s61, 0
	s_cmp_gt_u32 s74, 13
	s_cbranch_scc0 .LBB0_692
	s_and_b64 vcc, exec, s[30:31]
	s_cbranch_vccz .LBB0_695
	s_barrier

.LBB0_777:
	s_add_u32 s12, s50, 0xfff00080
	s_addc_u32 s13, s51, -1
	s_add_i32 s56, 0, 0x10000
	s_cmp_eq_u32 s72, 60
	s_cselect_b32 s55, s43, s13
	s_cselect_b32 s54, s49, s12
	s_cselect_b32 s53, s41, s61
	s_cselect_b32 s52, s70, s71
	s_add_i32 s73, 0, 0x14000
	v_add_u32_e32 v142, s56, v193
	v_add_u32_e32 v158, s73, v193
	ds_read_b128 v[130:133], v142
	ds_read_b128 v[134:137], v142 offset:1024
	ds_read_b128 v[138:141], v142 offset:2048
	ds_read_b128 v[142:145], v142 offset:3072
	ds_read_b128 v[146:149], v158
	ds_read_b128 v[150:153], v158 offset:1024
	ds_read_b128 v[154:157], v158 offset:2048
	ds_read_b128 v[158:161], v158 offset:3072
	v_lshl_add_u64 v[224:225], s[50:51], 0, v[216:217]
	s_add_i32 m0, s33, 0xc000
	ds_read_b128 v[162:165], v197
	ds_read_b128 v[166:169], v197 offset:1024
	ds_read_b128 v[170:173], v197 offset:2048
	ds_read_b128 v[174:177], v197 offset:3072
	ds_read_b128 v[178:181], v197 offset:4096
	ds_read_b128 v[182:185], v197 offset:5120
	ds_read_b128 v[186:189], v197 offset:6144
	ds_read_b128 v[220:223], v197 offset:7168
	global_load_lds_dwordx4 v[224:225], off
	v_lshl_add_u64 v[224:225], s[50:51], 0, v[218:219]
	s_add_i32 m0, s33, 0xe000
	s_nop 0
	global_load_lds_dwordx4 v[224:225], off
	s_waitcnt vmcnt(8)
	s_waitcnt lgkmcnt(0)
	s_barrier
	s_setprio 1
	s_waitcnt lgkmcnt(0)
	v_mfma_f32_16x16x32_bf16 v[126:129], v[130:133], v[162:165], v[126:129]
	v_mfma_f32_16x16x32_bf16 v[126:129], v[134:137], v[166:169], v[126:129]
	v_mfma_f32_16x16x32_bf16 v[122:125], v[138:141], v[162:165], v[122:125]
	v_mfma_f32_16x16x32_bf16 v[122:125], v[142:145], v[166:169], v[122:125]
	v_mfma_f32_16x16x32_bf16 v[110:113], v[130:133], v[170:173], v[110:113]
	v_mfma_f32_16x16x32_bf16 v[110:113], v[134:137], v[174:177], v[110:113]
	v_mfma_f32_16x16x32_bf16 v[106:109], v[138:141], v[170:173], v[106:109]
	v_mfma_f32_16x16x32_bf16 v[106:109], v[142:145], v[174:177], v[106:109]
	v_mfma_f32_16x16x32_bf16 v[98:101], v[130:133], v[178:181], v[98:101]
	v_mfma_f32_16x16x32_bf16 v[98:101], v[134:137], v[182:185], v[98:101]
	v_mfma_f32_16x16x32_bf16 v[90:93], v[138:141], v[178:181], v[90:93]
	v_mfma_f32_16x16x32_bf16 v[90:93], v[142:145], v[182:185], v[90:93]
	v_mfma_f32_16x16x32_bf16 v[82:85], v[130:133], v[186:189], v[82:85]
	v_mfma_f32_16x16x32_bf16 v[82:85], v[134:137], v[220:223], v[82:85]
	v_mfma_f32_16x16x32_bf16 v[74:77], v[138:141], v[186:189], v[74:77]
	v_mfma_f32_16x16x32_bf16 v[74:77], v[142:145], v[220:223], v[74:77]
	s_setprio 0
	s_setprio 1
	v_mfma_f32_16x16x32_bf16 v[118:121], v[146:149], v[162:165], v[118:121]
	v_mfma_f32_16x16x32_bf16 v[118:121], v[150:153], v[166:169], v[118:121]
	v_mfma_f32_16x16x32_bf16 v[114:117], v[154:157], v[162:165], v[114:117]
	v_mfma_f32_16x16x32_bf16 v[114:117], v[158:161], v[166:169], v[114:117]
	v_mfma_f32_16x16x32_bf16 v[102:105], v[146:149], v[170:173], v[102:105]
	v_mfma_f32_16x16x32_bf16 v[102:105], v[150:153], v[174:177], v[102:105]
	v_mfma_f32_16x16x32_bf16 v[94:97], v[154:157], v[170:173], v[94:97]
	v_mfma_f32_16x16x32_bf16 v[94:97], v[158:161], v[174:177], v[94:97]
	v_mfma_f32_16x16x32_bf16 v[86:89], v[146:149], v[178:181], v[86:89]
	v_mfma_f32_16x16x32_bf16 v[86:89], v[150:153], v[182:185], v[86:89]
	v_mfma_f32_16x16x32_bf16 v[78:81], v[154:157], v[178:181], v[78:81]
	v_mfma_f32_16x16x32_bf16 v[78:81], v[158:161], v[182:185], v[78:81]
	v_mfma_f32_16x16x32_bf16 v[70:73], v[146:149], v[186:189], v[70:73]
	v_mfma_f32_16x16x32_bf16 v[70:73], v[150:153], v[220:223], v[70:73]
	v_mfma_f32_16x16x32_bf16 v[66:69], v[154:157], v[186:189], v[66:69]
	v_mfma_f32_16x16x32_bf16 v[66:69], v[158:161], v[220:223], v[66:69]
	s_setprio 0
	s_barrier
	s_add_i32 s12, s56, s29
	v_lshl_add_u64 v[224:225], s[52:53], 0, v[190:191]
	s_mov_b32 m0, s12
	ds_read_b128 v[162:165], v197 offset:16384
	ds_read_b128 v[166:169], v197 offset:17408
	ds_read_b128 v[170:173], v197 offset:18432
	ds_read_b128 v[174:177], v197 offset:19456
	ds_read_b128 v[178:181], v197 offset:20480
	ds_read_b128 v[182:185], v197 offset:21504
	ds_read_b128 v[186:189], v197 offset:22528
	ds_read_b128 v[220:223], v197 offset:23552
	global_load_lds_dwordx4 v[224:225], off
	s_add_i32 m0, s12, 0x2000
	s_add_u32 s12, s52, 0x100000
	v_lshl_add_u64 v[226:227], s[52:53], 0, v[214:215]
	s_addc_u32 s13, s53, 0
	s_add_i32 s56, s73, s29
	global_load_lds_dwordx4 v[226:227], off
	v_lshl_add_u64 v[228:229], s[12:13], 0, v[190:191]
	s_mov_b32 m0, s56
	v_lshl_add_u64 v[230:231], s[54:55], 0, v[212:213]
	global_load_lds_dwordx4 v[228:229], off
	v_lshl_add_u64 v[228:229], s[12:13], 0, v[214:215]
	s_add_i32 m0, s56, 0x2000
	s_nop 0
	global_load_lds_dwordx4 v[228:229], off
	v_lshl_add_u64 v[228:229], s[54:55], 0, v[210:211]
	s_mov_b32 m0, s33
	s_nop 0
	global_load_lds_dwordx4 v[228:229], off
	s_mov_b32 m0, s62
	s_nop 0
	global_load_lds_dwordx4 v[230:231], off
	s_waitcnt vmcnt(8)
	s_waitcnt lgkmcnt(0)
	s_barrier
	s_setprio 1
	s_waitcnt lgkmcnt(0)
	v_mfma_f32_16x16x32_bf16 v[62:65], v[130:133], v[162:165], v[62:65]
	v_mfma_f32_16x16x32_bf16 v[62:65], v[134:137], v[166:169], v[62:65]
	v_mfma_f32_16x16x32_bf16 v[58:61], v[138:141], v[162:165], v[58:61]
	v_mfma_f32_16x16x32_bf16 v[58:61], v[142:145], v[166:169], v[58:61]
	v_mfma_f32_16x16x32_bf16 v[50:53], v[130:133], v[170:173], v[50:53]
	v_mfma_f32_16x16x32_bf16 v[50:53], v[134:137], v[174:177], v[50:53]
	v_mfma_f32_16x16x32_bf16 v[42:45], v[138:141], v[170:173], v[42:45]
	v_mfma_f32_16x16x32_bf16 v[42:45], v[142:145], v[174:177], v[42:45]
	v_mfma_f32_16x16x32_bf16 v[34:37], v[130:133], v[178:181], v[34:37]
	v_mfma_f32_16x16x32_bf16 v[34:37], v[134:137], v[182:185], v[34:37]
	v_mfma_f32_16x16x32_bf16 v[26:29], v[138:141], v[178:181], v[26:29]
	v_mfma_f32_16x16x32_bf16 v[26:29], v[142:145], v[182:185], v[26:29]
	v_mfma_f32_16x16x32_bf16 v[18:21], v[130:133], v[186:189], v[18:21]
	v_mfma_f32_16x16x32_bf16 v[18:21], v[134:137], v[220:223], v[18:21]
	v_mfma_f32_16x16x32_bf16 v[10:13], v[138:141], v[186:189], v[10:13]
	v_mfma_f32_16x16x32_bf16 v[10:13], v[142:145], v[220:223], v[10:13]
	s_setprio 0
	s_setprio 1
	v_mfma_f32_16x16x32_bf16 v[54:57], v[146:149], v[162:165], v[54:57]
	v_mfma_f32_16x16x32_bf16 v[54:57], v[150:153], v[166:169], v[54:57]
	v_mfma_f32_16x16x32_bf16 v[46:49], v[154:157], v[162:165], v[46:49]
	v_mfma_f32_16x16x32_bf16 v[46:49], v[158:161], v[166:169], v[46:49]
	v_mfma_f32_16x16x32_bf16 v[38:41], v[146:149], v[170:173], v[38:41]
	v_mfma_f32_16x16x32_bf16 v[38:41], v[150:153], v[174:177], v[38:41]
	v_mfma_f32_16x16x32_bf16 v[30:33], v[154:157], v[170:173], v[30:33]
	v_mfma_f32_16x16x32_bf16 v[30:33], v[158:161], v[174:177], v[30:33]
	v_mfma_f32_16x16x32_bf16 v[22:25], v[146:149], v[178:181], v[22:25]
	v_mfma_f32_16x16x32_bf16 v[22:25], v[150:153], v[182:185], v[22:25]
	v_mfma_f32_16x16x32_bf16 v[14:17], v[154:157], v[178:181], v[14:17]
	v_mfma_f32_16x16x32_bf16 v[14:17], v[158:161], v[182:185], v[14:17]
	v_mfma_f32_16x16x32_bf16 v[6:9], v[146:149], v[186:189], v[6:9]
	v_mfma_f32_16x16x32_bf16 v[6:9], v[150:153], v[220:223], v[6:9]
	v_mfma_f32_16x16x32_bf16 v[2:5], v[154:157], v[186:189], v[2:5]
	v_mfma_f32_16x16x32_bf16 v[2:5], v[158:161], v[220:223], v[2:5]
	s_setprio 0
	s_barrier
	s_add_i32 s56, 0, 0x18000
	s_add_i32 s73, 0, 0x1c000
	v_add_u32_e32 v142, s56, v193
	v_add_u32_e32 v158, s73, v193
	ds_read_b128 v[130:133], v142
	ds_read_b128 v[134:137], v142 offset:1024
	ds_read_b128 v[138:141], v142 offset:2048
	ds_read_b128 v[142:145], v142 offset:3072
	ds_read_b128 v[146:149], v158
	ds_read_b128 v[150:153], v158 offset:1024
	ds_read_b128 v[154:157], v158 offset:2048
	ds_read_b128 v[158:161], v158 offset:3072
	s_add_u32 s12, s54, 0x100000
	s_addc_u32 s13, s55, 0
	s_mov_b32 m0, s63
	v_lshl_add_u64 v[232:233], s[12:13], 0, v[210:211]
	ds_read_b128 v[162:165], v197 offset:32768
	ds_read_b128 v[166:169], v197 offset:33792
	ds_read_b128 v[170:173], v197 offset:34816
	ds_read_b128 v[174:177], v197 offset:35840
	ds_read_b128 v[178:181], v197 offset:36864
	ds_read_b128 v[182:185], v197 offset:37888
	ds_read_b128 v[186:189], v197 offset:38912
	ds_read_b128 v[220:223], v197 offset:39936
	global_load_lds_dwordx4 v[232:233], off
	v_lshl_add_u64 v[232:233], s[12:13], 0, v[212:213]
	s_mov_b32 m0, s64
	s_nop 0
	global_load_lds_dwordx4 v[232:233], off
	s_waitcnt vmcnt(8)
	s_waitcnt lgkmcnt(0)
	s_barrier
	s_setprio 1
	s_waitcnt lgkmcnt(0)
	v_mfma_f32_16x16x32_bf16 v[126:129], v[130:133], v[162:165], v[126:129]
	v_mfma_f32_16x16x32_bf16 v[126:129], v[134:137], v[166:169], v[126:129]
	v_mfma_f32_16x16x32_bf16 v[122:125], v[138:141], v[162:165], v[122:125]
	v_mfma_f32_16x16x32_bf16 v[122:125], v[142:145], v[166:169], v[122:125]
	v_mfma_f32_16x16x32_bf16 v[110:113], v[130:133], v[170:173], v[110:113]
	v_mfma_f32_16x16x32_bf16 v[110:113], v[134:137], v[174:177], v[110:113]
	v_mfma_f32_16x16x32_bf16 v[106:109], v[138:141], v[170:173], v[106:109]
	v_mfma_f32_16x16x32_bf16 v[106:109], v[142:145], v[174:177], v[106:109]
	v_mfma_f32_16x16x32_bf16 v[98:101], v[130:133], v[178:181], v[98:101]
	v_mfma_f32_16x16x32_bf16 v[98:101], v[134:137], v[182:185], v[98:101]
	v_mfma_f32_16x16x32_bf16 v[90:93], v[138:141], v[178:181], v[90:93]
	v_mfma_f32_16x16x32_bf16 v[90:93], v[142:145], v[182:185], v[90:93]
	v_mfma_f32_16x16x32_bf16 v[82:85], v[130:133], v[186:189], v[82:85]
	v_mfma_f32_16x16x32_bf16 v[82:85], v[134:137], v[220:223], v[82:85]
	v_mfma_f32_16x16x32_bf16 v[74:77], v[138:141], v[186:189], v[74:77]
	v_mfma_f32_16x16x32_bf16 v[74:77], v[142:145], v[220:223], v[74:77]
	s_setprio 0
	s_setprio 1
	v_mfma_f32_16x16x32_bf16 v[118:121], v[146:149], v[162:165], v[118:121]
	v_mfma_f32_16x16x32_bf16 v[118:121], v[150:153], v[166:169], v[118:121]
	v_mfma_f32_16x16x32_bf16 v[114:117], v[154:157], v[162:165], v[114:117]
	v_mfma_f32_16x16x32_bf16 v[114:117], v[158:161], v[166:169], v[114:117]
	v_mfma_f32_16x16x32_bf16 v[102:105], v[146:149], v[170:173], v[102:105]
	v_mfma_f32_16x16x32_bf16 v[102:105], v[150:153], v[174:177], v[102:105]
	v_mfma_f32_16x16x32_bf16 v[94:97], v[154:157], v[170:173], v[94:97]
	v_mfma_f32_16x16x32_bf16 v[94:97], v[158:161], v[174:177], v[94:97]
	v_mfma_f32_16x16x32_bf16 v[86:89], v[146:149], v[178:181], v[86:89]
	v_mfma_f32_16x16x32_bf16 v[86:89], v[150:153], v[182:185], v[86:89]
	v_mfma_f32_16x16x32_bf16 v[78:81], v[154:157], v[178:181], v[78:81]
	v_mfma_f32_16x16x32_bf16 v[78:81], v[158:161], v[182:185], v[78:81]
	v_mfma_f32_16x16x32_bf16 v[70:73], v[146:149], v[186:189], v[70:73]
	v_mfma_f32_16x16x32_bf16 v[70:73], v[150:153], v[220:223], v[70:73]
	v_mfma_f32_16x16x32_bf16 v[66:69], v[154:157], v[186:189], v[66:69]
	v_mfma_f32_16x16x32_bf16 v[66:69], v[158:161], v[220:223], v[66:69]
	s_setprio 0
	s_barrier
	s_add_i32 s12, s56, s29
	v_lshl_add_u64 v[224:225], v[224:225], 0, s[34:35]
	s_mov_b32 m0, s12
	ds_read_b128 v[162:165], v197 offset:49152
	ds_read_b128 v[166:169], v197 offset:50176
	ds_read_b128 v[170:173], v197 offset:51200
	ds_read_b128 v[174:177], v197 offset:52224
	ds_read_b128 v[178:181], v197 offset:53248
	ds_read_b128 v[182:185], v197 offset:54272
	ds_read_b128 v[186:189], v197 offset:55296
	ds_read_b128 v[220:223], v197 offset:56320
	global_load_lds_dwordx4 v[224:225], off
	s_add_i32 m0, s12, 0x2000
	s_add_u32 s12, s52, 0x100080
	v_lshl_add_u64 v[224:225], v[226:227], 0, s[34:35]
	s_addc_u32 s13, s53, 0
	s_add_i32 s52, s73, s29
	global_load_lds_dwordx4 v[224:225], off
	v_lshl_add_u64 v[224:225], s[12:13], 0, v[190:191]
	s_mov_b32 m0, s52
	s_nop 0
	global_load_lds_dwordx4 v[224:225], off
	v_lshl_add_u64 v[224:225], s[12:13], 0, v[214:215]
	s_add_i32 m0, s52, 0x2000
	s_nop 0
	global_load_lds_dwordx4 v[224:225], off
	v_lshl_add_u64 v[224:225], v[228:229], 0, s[34:35]
	s_mov_b32 m0, s65
	s_nop 0
	global_load_lds_dwordx4 v[224:225], off
	v_lshl_add_u64 v[224:225], v[230:231], 0, s[34:35]
	s_mov_b32 m0, s66
	s_nop 0
	global_load_lds_dwordx4 v[224:225], off
	s_waitcnt vmcnt(8)
	s_waitcnt lgkmcnt(0)
	s_barrier
	s_setprio 1
	s_waitcnt lgkmcnt(0)
	v_mfma_f32_16x16x32_bf16 v[62:65], v[130:133], v[162:165], v[62:65]
	v_mfma_f32_16x16x32_bf16 v[62:65], v[134:137], v[166:169], v[62:65]
	v_mfma_f32_16x16x32_bf16 v[58:61], v[138:141], v[162:165], v[58:61]
	v_mfma_f32_16x16x32_bf16 v[58:61], v[142:145], v[166:169], v[58:61]
	v_mfma_f32_16x16x32_bf16 v[50:53], v[130:133], v[170:173], v[50:53]
	v_mfma_f32_16x16x32_bf16 v[50:53], v[134:137], v[174:177], v[50:53]
	v_mfma_f32_16x16x32_bf16 v[42:45], v[138:141], v[170:173], v[42:45]
	v_mfma_f32_16x16x32_bf16 v[42:45], v[142:145], v[174:177], v[42:45]
	v_mfma_f32_16x16x32_bf16 v[34:37], v[130:133], v[178:181], v[34:37]
	v_mfma_f32_16x16x32_bf16 v[34:37], v[134:137], v[182:185], v[34:37]
	v_mfma_f32_16x16x32_bf16 v[26:29], v[138:141], v[178:181], v[26:29]
	v_mfma_f32_16x16x32_bf16 v[26:29], v[142:145], v[182:185], v[26:29]
	v_mfma_f32_16x16x32_bf16 v[18:21], v[130:133], v[186:189], v[18:21]
	v_mfma_f32_16x16x32_bf16 v[18:21], v[134:137], v[220:223], v[18:21]
	v_mfma_f32_16x16x32_bf16 v[10:13], v[138:141], v[186:189], v[10:13]
	v_mfma_f32_16x16x32_bf16 v[10:13], v[142:145], v[220:223], v[10:13]
	s_setprio 0
	s_setprio 1
	v_mfma_f32_16x16x32_bf16 v[54:57], v[146:149], v[162:165], v[54:57]
	v_mfma_f32_16x16x32_bf16 v[54:57], v[150:153], v[166:169], v[54:57]
	v_mfma_f32_16x16x32_bf16 v[46:49], v[154:157], v[162:165], v[46:49]
	v_mfma_f32_16x16x32_bf16 v[46:49], v[158:161], v[166:169], v[46:49]
	v_mfma_f32_16x16x32_bf16 v[38:41], v[146:149], v[170:173], v[38:41]
	v_mfma_f32_16x16x32_bf16 v[38:41], v[150:153], v[174:177], v[38:41]
	v_mfma_f32_16x16x32_bf16 v[30:33], v[154:157], v[170:173], v[30:33]
	v_mfma_f32_16x16x32_bf16 v[30:33], v[158:161], v[174:177], v[30:33]
	v_mfma_f32_16x16x32_bf16 v[22:25], v[146:149], v[178:181], v[22:25]
	v_mfma_f32_16x16x32_bf16 v[22:25], v[150:153], v[182:185], v[22:25]
	v_mfma_f32_16x16x32_bf16 v[14:17], v[154:157], v[178:181], v[14:17]
	v_mfma_f32_16x16x32_bf16 v[14:17], v[158:161], v[182:185], v[14:17]
	v_mfma_f32_16x16x32_bf16 v[6:9], v[146:149], v[186:189], v[6:9]
	v_mfma_f32_16x16x32_bf16 v[6:9], v[150:153], v[220:223], v[6:9]
	v_mfma_f32_16x16x32_bf16 v[2:5], v[154:157], v[186:189], v[2:5]
	v_mfma_f32_16x16x32_bf16 v[2:5], v[158:161], v[220:223], v[2:5]
	s_setprio 0
	s_barrier
	s_add_i32 s72, s72, 2
	s_add_u32 s50, s50, 0x100
	s_addc_u32 s51, s51, 0
	s_add_u32 s71, s71, 0x100
	s_addc_u32 s61, s61, 0
	s_cmp_gt_u32 s72, 61
	s_cbranch_scc0 .LBB0_777
	s_and_b64 vcc, exec, s[30:31]
	s_cbranch_vccz .LBB0_780
	s_barrier

.LBB0_839:
	v_add_co_u32_e32 v48, vcc, 0xd4000000, v46
	global_load_dwordx4 v[2:5], v[18:19], off offset:16
	global_load_dwordx4 v[6:9], v[18:19], off
	global_load_dwordx4 v[10:13], v[20:21], off offset:16
	global_load_dwordx4 v[14:17], v[20:21], off
	v_addc_co_u32_e32 v49, vcc, -1, v47, vcc
	v_add_co_u32_e32 v50, vcc, 0xd4001000, v46
	global_load_dwordx4 v[56:59], v[48:49], off
	s_nop 0
	v_addc_co_u32_e32 v51, vcc, -1, v47, vcc
	global_load_dwordx4 v[60:63], v[50:51], off offset:-3072
	global_load_dwordx4 v[64:67], v[50:51], off offset:-2048
	global_load_dwordx4 v[68:71], v[50:51], off offset:-1024
	global_load_dwordx4 v[72:75], v[50:51], off
	s_mov_b32 s1, 0xd4002000
	v_add_co_u32_e32 v48, vcc, s1, v46
	s_add_i32 s3, s3, s0
	s_nop 0
	v_addc_co_u32_e32 v49, vcc, -1, v47, vcc
	global_load_dwordx4 v[76:79], v[48:49], off offset:-1024
	global_load_dwordx4 v[80:83], v[48:49], off offset:-3072
	global_load_dwordx4 v[84:87], v[48:49], off offset:-2048
	s_cmpk_gt_i32 s3, 0x7fff
	s_waitcnt vmcnt(0)
	v_lshlrev_b32_e32 v88, 16, v60
	v_lshlrev_b32_e32 v54, 16, v56
	v_and_b32_e32 v55, 0xffff0000, v56
	v_add_f32_e32 v92, 0, v54
	v_lshlrev_b32_e32 v52, 16, v57
	v_lshlrev_b32_e32 v108, 16, v72
	v_and_b32_e32 v109, 0xffff0000, v72
	v_add_f32_e32 v72, v92, v55
	v_and_b32_e32 v53, 0xffff0000, v57
	v_add_f32_e32 v72, v72, v52
	v_lshlrev_b32_e32 v50, 16, v58
	v_add_f32_e32 v72, v72, v53
	v_and_b32_e32 v51, 0xffff0000, v58
	v_add_f32_e32 v72, v72, v50
	v_lshlrev_b32_e32 v48, 16, v59
	v_add_f32_e32 v72, v72, v51
	v_and_b32_e32 v49, 0xffff0000, v59
	v_add_f32_e32 v72, v72, v48
	v_add_f32_e32 v72, v72, v49
	v_and_b32_e32 v89, 0xffff0000, v60
	v_add_f32_e32 v72, v72, v88
	v_lshlrev_b32_e32 v58, 16, v62
	v_and_b32_e32 v59, 0xffff0000, v62
	v_lshlrev_b32_e32 v62, 16, v61
	v_add_f32_e32 v72, v72, v89
	v_lshlrev_b32_e32 v56, 16, v63
	v_and_b32_e32 v57, 0xffff0000, v63
	v_and_b32_e32 v63, 0xffff0000, v61
	v_add_f32_e32 v72, v72, v62
	v_add_f32_e32 v72, v72, v63
	v_add_f32_e32 v72, v72, v58
	v_add_f32_e32 v72, v72, v59
	v_add_f32_e32 v72, v72, v56
	v_lshlrev_b32_e32 v90, 16, v64
	v_add_f32_e32 v72, v72, v57
	v_and_b32_e32 v91, 0xffff0000, v64
	v_add_f32_e32 v72, v72, v90
	v_lshlrev_b32_e32 v96, 16, v66
	v_and_b32_e32 v97, 0xffff0000, v66
	v_lshlrev_b32_e32 v66, 16, v65
	v_add_f32_e32 v72, v72, v91
	v_lshlrev_b32_e32 v60, 16, v67
	v_and_b32_e32 v61, 0xffff0000, v67
	v_and_b32_e32 v67, 0xffff0000, v65
	v_add_f32_e32 v72, v72, v66
	v_add_f32_e32 v72, v72, v67
	v_add_f32_e32 v72, v72, v96
	v_add_f32_e32 v72, v72, v97
	v_add_f32_e32 v72, v72, v60
	v_lshlrev_b32_e32 v104, 16, v68
	v_add_f32_e32 v72, v72, v61
	v_and_b32_e32 v105, 0xffff0000, v68
	v_add_f32_e32 v72, v72, v104
	v_lshlrev_b32_e32 v102, 16, v70
	v_and_b32_e32 v103, 0xffff0000, v70
	v_lshlrev_b32_e32 v70, 16, v69
	v_add_f32_e32 v72, v72, v105
	v_lshlrev_b32_e32 v64, 16, v71
	v_and_b32_e32 v65, 0xffff0000, v71
	v_and_b32_e32 v71, 0xffff0000, v69
	v_add_f32_e32 v72, v72, v70
	v_add_f32_e32 v72, v72, v71
	v_add_f32_e32 v72, v72, v102
	v_add_f32_e32 v72, v72, v103
	v_add_f32_e32 v72, v72, v64
	v_add_f32_e32 v72, v72, v65
	v_add_f32_e32 v72, v72, v108
	v_lshlrev_b32_e32 v106, 16, v74
	v_and_b32_e32 v107, 0xffff0000, v74
	v_lshlrev_b32_e32 v74, 16, v73
	v_add_f32_e32 v72, v72, v109
	v_lshlrev_b32_e32 v68, 16, v75
	v_and_b32_e32 v69, 0xffff0000, v75
	v_and_b32_e32 v75, 0xffff0000, v73
	v_add_f32_e32 v72, v72, v74
	v_add_f32_e32 v72, v72, v75
	v_add_f32_e32 v72, v72, v106
	v_add_f32_e32 v72, v72, v107
	v_add_f32_e32 v72, v72, v68
	v_lshlrev_b32_e32 v118, 16, v80
	v_add_f32_e32 v72, v72, v69
	v_and_b32_e32 v119, 0xffff0000, v80
	v_add_f32_e32 v72, v72, v118
	v_lshlrev_b32_e32 v116, 16, v81
	v_add_f32_e32 v72, v72, v119
	v_and_b32_e32 v117, 0xffff0000, v81
	v_add_f32_e32 v72, v72, v116
	v_lshlrev_b32_e32 v114, 16, v82
	v_add_f32_e32 v72, v72, v117
	v_and_b32_e32 v115, 0xffff0000, v82
	v_add_f32_e32 v72, v72, v114
	v_lshlrev_b32_e32 v112, 16, v83
	v_add_f32_e32 v72, v72, v115
	v_and_b32_e32 v113, 0xffff0000, v83
	v_add_f32_e32 v72, v72, v112
	v_lshlrev_b32_e32 v126, 16, v84
	v_add_f32_e32 v72, v72, v113
	v_and_b32_e32 v127, 0xffff0000, v84
	v_add_f32_e32 v72, v72, v126
	v_lshlrev_b32_e32 v124, 16, v85
	v_add_f32_e32 v72, v72, v127
	v_and_b32_e32 v125, 0xffff0000, v85
	v_add_f32_e32 v72, v72, v124
	v_lshlrev_b32_e32 v122, 16, v86
	v_add_f32_e32 v72, v72, v125
	v_and_b32_e32 v123, 0xffff0000, v86
	v_add_f32_e32 v72, v72, v122
	v_lshlrev_b32_e32 v120, 16, v87
	v_add_f32_e32 v72, v72, v123
	v_and_b32_e32 v121, 0xffff0000, v87
	v_add_f32_e32 v72, v72, v120
	v_lshlrev_b32_e32 v132, 16, v76
	v_add_f32_e32 v72, v72, v121
	v_and_b32_e32 v133, 0xffff0000, v76
	v_add_f32_e32 v72, v72, v132
	v_lshlrev_b32_e32 v130, 16, v77
	v_add_f32_e32 v72, v72, v133
	v_and_b32_e32 v131, 0xffff0000, v77
	v_add_f32_e32 v72, v72, v130
	v_lshlrev_b32_e32 v128, 16, v78
	v_add_f32_e32 v72, v72, v131
	v_and_b32_e32 v129, 0xffff0000, v78
	v_add_f32_e32 v72, v72, v128
	v_lshlrev_b32_e32 v111, 16, v79
	v_add_f32_e32 v72, v72, v129
	v_and_b32_e32 v110, 0xffff0000, v79
	v_add_f32_e32 v72, v72, v111
	v_add_f32_e32 v72, v72, v110
	ds_bpermute_b32 v73, v1, v72
	s_waitcnt lgkmcnt(0)
	v_add_f32_e32 v72, v72, v73
	ds_bpermute_b32 v73, v95, v72
	s_waitcnt lgkmcnt(0)
	v_add_f32_e32 v72, v72, v73
	ds_bpermute_b32 v73, v98, v72
	s_waitcnt lgkmcnt(0)
	v_add_f32_e32 v72, v72, v73
	ds_bpermute_b32 v73, v99, v72
	s_waitcnt lgkmcnt(0)
	v_add_f32_e32 v72, v72, v73
	ds_bpermute_b32 v73, v100, v72
	s_waitcnt lgkmcnt(0)
	v_add_f32_e32 v72, v72, v73
	ds_bpermute_b32 v73, v101, v72
	s_waitcnt lgkmcnt(0)
	v_add_f32_e32 v72, v72, v73
	v_mul_f32_e32 v94, 0x39800000, v72
	v_pk_add_f32 v[134:135], v[54:55], v[94:95] op_sel_hi:[1,0] neg_lo:[0,1] neg_hi:[0,1]
	v_pk_add_f32 v[136:137], v[52:53], v[94:95] op_sel_hi:[1,0] neg_lo:[0,1] neg_hi:[0,1]
	v_pk_add_f32 v[86:87], v[102:103], v[94:95] op_sel_hi:[1,0] neg_lo:[0,1] neg_hi:[0,1]
	v_pk_mul_f32 v[102:103], v[134:135], v[134:135]
	v_pk_add_f32 v[138:139], v[50:51], v[94:95] op_sel_hi:[1,0] neg_lo:[0,1] neg_hi:[0,1]
	v_pk_add_f32 v[140:141], v[48:49], v[94:95] op_sel_hi:[1,0] neg_lo:[0,1] neg_hi:[0,1]
	v_pk_add_f32 v[142:143], v[88:89], v[94:95] op_sel_hi:[1,0] neg_lo:[0,1] neg_hi:[0,1]
	v_pk_add_f32 v[144:145], v[62:63], v[94:95] op_sel_hi:[1,0] neg_lo:[0,1] neg_hi:[0,1]
	v_pk_add_f32 v[146:147], v[58:59], v[94:95] op_sel_hi:[1,0] neg_lo:[0,1] neg_hi:[0,1]
	v_pk_add_f32 v[148:149], v[56:57], v[94:95] op_sel_hi:[1,0] neg_lo:[0,1] neg_hi:[0,1]
	v_pk_add_f32 v[92:93], v[90:91], v[94:95] op_sel_hi:[1,0] neg_lo:[0,1] neg_hi:[0,1]
	v_pk_add_f32 v[90:91], v[66:67], v[94:95] op_sel_hi:[1,0] neg_lo:[0,1] neg_hi:[0,1]
	v_pk_add_f32 v[96:97], v[96:97], v[94:95] op_sel_hi:[1,0] neg_lo:[0,1] neg_hi:[0,1]
	v_pk_add_f32 v[88:89], v[60:61], v[94:95] op_sel_hi:[1,0] neg_lo:[0,1] neg_hi:[0,1]
	v_pk_add_f32 v[84:85], v[104:105], v[94:95] op_sel_hi:[1,0] neg_lo:[0,1] neg_hi:[0,1]
	v_pk_add_f32 v[82:83], v[70:71], v[94:95] op_sel_hi:[1,0] neg_lo:[0,1] neg_hi:[0,1]
	v_pk_add_f32 v[80:81], v[64:65], v[94:95] op_sel_hi:[1,0] neg_lo:[0,1] neg_hi:[0,1]
	v_pk_add_f32 v[72:73], v[108:109], v[94:95] op_sel_hi:[1,0] neg_lo:[0,1] neg_hi:[0,1]
	v_pk_add_f32 v[74:75], v[74:75], v[94:95] op_sel_hi:[1,0] neg_lo:[0,1] neg_hi:[0,1]
	v_pk_add_f32 v[76:77], v[106:107], v[94:95] op_sel_hi:[1,0] neg_lo:[0,1] neg_hi:[0,1]
	v_pk_add_f32 v[78:79], v[68:69], v[94:95] op_sel_hi:[1,0] neg_lo:[0,1] neg_hi:[0,1]
	v_pk_add_f32 v[68:69], v[118:119], v[94:95] op_sel_hi:[1,0] neg_lo:[0,1] neg_hi:[0,1]
	v_pk_add_f32 v[66:67], v[116:117], v[94:95] op_sel_hi:[1,0] neg_lo:[0,1] neg_hi:[0,1]
	v_pk_add_f32 v[70:71], v[114:115], v[94:95] op_sel_hi:[1,0] neg_lo:[0,1] neg_hi:[0,1]
	v_pk_add_f32 v[64:65], v[112:113], v[94:95] op_sel_hi:[1,0] neg_lo:[0,1] neg_hi:[0,1]
	v_pk_add_f32 v[60:61], v[126:127], v[94:95] op_sel_hi:[1,0] neg_lo:[0,1] neg_hi:[0,1]
	v_pk_add_f32 v[58:59], v[124:125], v[94:95] op_sel_hi:[1,0] neg_lo:[0,1] neg_hi:[0,1]
	v_pk_add_f32 v[62:63], v[122:123], v[94:95] op_sel_hi:[1,0] neg_lo:[0,1] neg_hi:[0,1]
	v_pk_add_f32 v[56:57], v[120:121], v[94:95] op_sel_hi:[1,0] neg_lo:[0,1] neg_hi:[0,1]
	v_pk_add_f32 v[48:49], v[132:133], v[94:95] op_sel_hi:[1,0] neg_lo:[0,1] neg_hi:[0,1]
	v_pk_add_f32 v[50:51], v[130:131], v[94:95] op_sel_hi:[1,0] neg_lo:[0,1] neg_hi:[0,1]
	v_pk_add_f32 v[52:53], v[128:129], v[94:95] op_sel_hi:[1,0] neg_lo:[0,1] neg_hi:[0,1]
	v_pk_add_f32 v[54:55], v[110:111], v[94:95] op_sel_hi:[1,0] neg_lo:[0,1] neg_hi:[0,1]
	v_pk_mul_f32 v[104:105], v[136:137], v[136:137]
	v_add_f32_e32 v94, v102, v103
	v_add_f32_e32 v94, v104, v94
	v_pk_mul_f32 v[106:107], v[138:139], v[138:139]
	v_add_f32_e32 v94, v105, v94
	v_add_f32_e32 v94, v106, v94
	v_pk_mul_f32 v[108:109], v[140:141], v[140:141]
	v_add_f32_e32 v94, v107, v94
	v_add_f32_e32 v94, v108, v94
	v_pk_mul_f32 v[110:111], v[142:143], v[142:143]
	v_add_f32_e32 v94, v109, v94
	v_add_f32_e32 v94, v110, v94
	v_pk_mul_f32 v[112:113], v[144:145], v[144:145]
	v_add_f32_e32 v94, v111, v94
	v_add_f32_e32 v94, v112, v94
	v_pk_mul_f32 v[114:115], v[146:147], v[146:147]
	v_add_f32_e32 v94, v113, v94
	v_add_f32_e32 v94, v114, v94
	v_pk_mul_f32 v[116:117], v[148:149], v[148:149]
	v_add_f32_e32 v94, v115, v94
	v_add_f32_e32 v94, v116, v94
	v_pk_mul_f32 v[118:119], v[92:93], v[92:93]
	v_add_f32_e32 v94, v117, v94
	v_add_f32_e32 v94, v118, v94
	v_pk_mul_f32 v[120:121], v[90:91], v[90:91]
	v_add_f32_e32 v94, v119, v94
	v_add_f32_e32 v94, v120, v94
	v_pk_mul_f32 v[122:123], v[96:97], v[96:97]
	v_add_f32_e32 v94, v121, v94
	v_add_f32_e32 v94, v122, v94
	v_pk_mul_f32 v[124:125], v[88:89], v[88:89]
	v_add_f32_e32 v94, v123, v94
	v_add_f32_e32 v94, v124, v94
	v_pk_mul_f32 v[126:127], v[84:85], v[84:85]
	v_add_f32_e32 v94, v125, v94
	v_add_f32_e32 v94, v126, v94
	v_pk_mul_f32 v[128:129], v[82:83], v[82:83]
	v_add_f32_e32 v94, v127, v94
	v_add_f32_e32 v94, v128, v94
	v_pk_mul_f32 v[130:131], v[86:87], v[86:87]
	v_add_f32_e32 v94, v129, v94
	v_add_f32_e32 v94, v130, v94
	v_pk_mul_f32 v[132:133], v[80:81], v[80:81]
	v_add_f32_e32 v94, v131, v94
	v_add_f32_e32 v94, v132, v94
	v_pk_mul_f32 v[150:151], v[72:73], v[72:73]
	v_add_f32_e32 v94, v133, v94
	v_add_f32_e32 v94, v150, v94
	v_pk_mul_f32 v[152:153], v[74:75], v[74:75]
	v_add_f32_e32 v94, v151, v94
	v_add_f32_e32 v94, v152, v94
	v_pk_mul_f32 v[154:155], v[76:77], v[76:77]
	v_add_f32_e32 v94, v153, v94
	v_add_f32_e32 v94, v154, v94
	v_pk_mul_f32 v[156:157], v[78:79], v[78:79]
	v_add_f32_e32 v94, v155, v94
	v_add_f32_e32 v94, v156, v94
	v_pk_mul_f32 v[158:159], v[68:69], v[68:69]
	v_add_f32_e32 v94, v157, v94
	v_add_f32_e32 v94, v158, v94
	v_pk_mul_f32 v[160:161], v[66:67], v[66:67]
	v_add_f32_e32 v94, v159, v94
	v_add_f32_e32 v94, v160, v94
	v_pk_mul_f32 v[162:163], v[70:71], v[70:71]
	v_add_f32_e32 v94, v161, v94
	v_add_f32_e32 v94, v162, v94
	v_pk_mul_f32 v[164:165], v[64:65], v[64:65]
	v_add_f32_e32 v94, v163, v94
	v_add_f32_e32 v94, v164, v94
	v_pk_mul_f32 v[166:167], v[60:61], v[60:61]
	v_add_f32_e32 v94, v165, v94
	v_add_f32_e32 v94, v166, v94
	v_pk_mul_f32 v[168:169], v[58:59], v[58:59]
	v_add_f32_e32 v94, v167, v94
	v_add_f32_e32 v94, v168, v94
	v_pk_mul_f32 v[170:171], v[62:63], v[62:63]
	v_add_f32_e32 v94, v169, v94
	v_add_f32_e32 v94, v170, v94
	v_pk_mul_f32 v[172:173], v[56:57], v[56:57]
	v_add_f32_e32 v94, v171, v94
	v_add_f32_e32 v94, v172, v94
	v_pk_mul_f32 v[174:175], v[48:49], v[48:49]
	v_add_f32_e32 v94, v173, v94
	v_add_f32_e32 v94, v174, v94
	v_pk_mul_f32 v[176:177], v[50:51], v[50:51]
	v_add_f32_e32 v94, v175, v94
	v_add_f32_e32 v94, v176, v94
	v_pk_mul_f32 v[178:179], v[52:53], v[52:53]
	v_add_f32_e32 v94, v177, v94
	v_add_f32_e32 v94, v178, v94
	v_pk_mul_f32 v[180:181], v[54:55], v[54:55]
	v_add_f32_e32 v94, v179, v94
	v_add_f32_e32 v94, v181, v94
	v_add_f32_e32 v94, v180, v94
	ds_bpermute_b32 v102, v1, v94
	s_waitcnt lgkmcnt(0)
	v_add_f32_e32 v94, v94, v102
	ds_bpermute_b32 v102, v95, v94
	s_waitcnt lgkmcnt(0)
	v_add_f32_e32 v94, v94, v102
	ds_bpermute_b32 v102, v98, v94
	s_waitcnt lgkmcnt(0)
	v_add_f32_e32 v94, v94, v102
	ds_bpermute_b32 v102, v99, v94
	s_waitcnt lgkmcnt(0)
	v_add_f32_e32 v94, v94, v102
	ds_bpermute_b32 v102, v100, v94
	s_waitcnt lgkmcnt(0)
	v_add_f32_e32 v94, v94, v102
	ds_bpermute_b32 v102, v101, v94
	s_waitcnt lgkmcnt(0)
	v_add_f32_e32 v94, v94, v102
	v_fmamk_f32 v94, v94, 0x39800000, v237
	v_mul_f32_e32 v102, 0x4f800000, v94
	v_cmp_gt_f32_e32 vcc, s62, v94
	s_nop 1
	v_cndmask_b32_e32 v94, v94, v102, vcc
	v_sqrt_f32_e32 v102, v94
	s_nop 0
	v_add_u32_e32 v103, -1, v102
	v_add_u32_e32 v104, 1, v102
	v_fma_f32 v105, -v103, v102, v94
	v_fma_f32 v106, -v104, v102, v94
	v_cmp_ge_f32_e64 s[38:39], 0, v105
	s_nop 1
	v_cndmask_b32_e64 v102, v102, v103, s[38:39]
	v_cmp_lt_f32_e64 s[38:39], 0, v106
	s_nop 1
	v_cndmask_b32_e64 v102, v102, v104, s[38:39]
	v_mul_f32_e32 v103, 0x37800000, v102
	v_cndmask_b32_e32 v102, v102, v103, vcc
	v_cmp_class_f32_e32 vcc, v94, v238
	s_nop 1
	v_cndmask_b32_e32 v94, v102, v94, vcc
	v_div_scale_f32 v102, s[10:11], v94, v94, 1.0
	v_rcp_f32_e32 v104, v102
	v_div_scale_f32 v103, vcc, 1.0, v94, 1.0
	v_fma_f32 v105, -v102, v104, 1.0
	v_fmac_f32_e32 v104, v105, v104
	v_mul_f32_e32 v105, v103, v104
	v_fma_f32 v106, -v102, v105, v103
	v_fmac_f32_e32 v105, v106, v104
	v_fma_f32 v102, -v102, v105, v103
	v_div_fmas_f32 v102, v102, v104, v105
	v_div_fixup_f32 v94, v102, v94, 1.0
	v_pk_mul_f32 v[102:103], v[134:135], v[94:95] op_sel_hi:[1,0]
	v_pk_mul_f32 v[104:105], v[138:139], v[94:95] op_sel_hi:[1,0]
	v_pk_mul_f32 v[106:107], v[136:137], v[94:95] op_sel_hi:[1,0]
	v_pk_mul_f32 v[108:109], v[140:141], v[94:95] op_sel_hi:[1,0]
	v_pk_fma_f32 v[6:7], v[6:7], v[102:103], v[14:15]
	v_pk_fma_f32 v[10:11], v[2:3], v[104:105], v[10:11]
	v_pk_fma_f32 v[8:9], v[8:9], v[106:107], v[16:17]
	v_pk_fma_f32 v[12:13], v[4:5], v[108:109], v[12:13]
	v_cvt_pk_bf16_f32 v2, v6, v7
	v_cvt_pk_bf16_f32 v3, v8, v9
	v_cvt_pk_bf16_f32 v4, v10, v11
	v_cvt_pk_bf16_f32 v5, v12, v13
	global_store_dwordx4 v[46:47], v[2:5], off
	global_load_dwordx4 v[2:5], v[18:19], off offset:2064
	s_nop 0
	global_load_dwordx4 v[6:9], v[18:19], off offset:2048
	global_load_dwordx4 v[10:13], v[20:21], off offset:2048
	global_load_dwordx4 v[14:17], v[20:21], off offset:2064
	v_pk_mul_f32 v[102:103], v[142:143], v[94:95] op_sel_hi:[1,0]
	v_pk_mul_f32 v[104:105], v[146:147], v[94:95] op_sel_hi:[1,0]
	v_pk_mul_f32 v[106:107], v[144:145], v[94:95] op_sel_hi:[1,0]
	v_pk_mul_f32 v[108:109], v[148:149], v[94:95] op_sel_hi:[1,0]
	v_pk_mul_f32 v[92:93], v[92:93], v[94:95] op_sel_hi:[1,0]
	v_pk_mul_f32 v[96:97], v[96:97], v[94:95] op_sel_hi:[1,0]
	v_pk_mul_f32 v[90:91], v[90:91], v[94:95] op_sel_hi:[1,0]
	v_pk_mul_f32 v[88:89], v[88:89], v[94:95] op_sel_hi:[1,0]
	v_pk_mul_f32 v[84:85], v[84:85], v[94:95] op_sel_hi:[1,0]
	v_pk_mul_f32 v[86:87], v[86:87], v[94:95] op_sel_hi:[1,0]
	v_pk_mul_f32 v[82:83], v[82:83], v[94:95] op_sel_hi:[1,0]
	v_pk_mul_f32 v[80:81], v[80:81], v[94:95] op_sel_hi:[1,0]
	v_pk_mul_f32 v[72:73], v[72:73], v[94:95] op_sel_hi:[1,0]
	v_pk_mul_f32 v[76:77], v[76:77], v[94:95] op_sel_hi:[1,0]
	v_pk_mul_f32 v[74:75], v[74:75], v[94:95] op_sel_hi:[1,0]
	v_pk_mul_f32 v[78:79], v[78:79], v[94:95] op_sel_hi:[1,0]
	v_pk_mul_f32 v[68:69], v[68:69], v[94:95] op_sel_hi:[1,0]
	v_pk_mul_f32 v[70:71], v[70:71], v[94:95] op_sel_hi:[1,0]
	v_pk_mul_f32 v[66:67], v[66:67], v[94:95] op_sel_hi:[1,0]
	v_pk_mul_f32 v[64:65], v[64:65], v[94:95] op_sel_hi:[1,0]
	v_pk_mul_f32 v[60:61], v[60:61], v[94:95] op_sel_hi:[1,0]
	v_pk_mul_f32 v[62:63], v[62:63], v[94:95] op_sel_hi:[1,0]
	v_pk_mul_f32 v[58:59], v[58:59], v[94:95] op_sel_hi:[1,0]
	v_pk_mul_f32 v[56:57], v[56:57], v[94:95] op_sel_hi:[1,0]
	v_pk_mul_f32 v[48:49], v[48:49], v[94:95] op_sel_hi:[1,0]
	v_pk_mul_f32 v[52:53], v[52:53], v[94:95] op_sel_hi:[1,0]
	v_pk_mul_f32 v[50:51], v[50:51], v[94:95] op_sel_hi:[1,0]
	v_pk_mul_f32 v[54:55], v[54:55], v[94:95] op_sel_hi:[1,0]
	s_waitcnt vmcnt(1)
	v_pk_fma_f32 v[6:7], v[6:7], v[102:103], v[10:11]
	s_waitcnt vmcnt(0)
	v_pk_fma_f32 v[10:11], v[2:3], v[104:105], v[14:15]
	v_pk_fma_f32 v[8:9], v[8:9], v[106:107], v[12:13]
	v_pk_fma_f32 v[12:13], v[4:5], v[108:109], v[16:17]
	v_cvt_pk_bf16_f32 v2, v6, v7
	v_cvt_pk_bf16_f32 v3, v8, v9
	v_cvt_pk_bf16_f32 v4, v10, v11
	v_cvt_pk_bf16_f32 v5, v12, v13
	global_store_dwordx4 v[46:47], v[2:5], off offset:1024
	global_load_dwordx4 v[2:5], v[22:23], off offset:16
	s_nop 0
	global_load_dwordx4 v[6:9], v[22:23], off
	global_load_dwordx4 v[10:13], v[24:25], off
	global_load_dwordx4 v[14:17], v[24:25], off offset:16
	s_waitcnt vmcnt(1)
	v_pk_fma_f32 v[6:7], v[6:7], v[92:93], v[10:11]
	s_waitcnt vmcnt(0)
	v_pk_fma_f32 v[10:11], v[2:3], v[96:97], v[14:15]
	v_pk_fma_f32 v[8:9], v[8:9], v[90:91], v[12:13]
	v_pk_fma_f32 v[12:13], v[4:5], v[88:89], v[16:17]
	v_cvt_pk_bf16_f32 v2, v6, v7
	v_cvt_pk_bf16_f32 v3, v8, v9
	v_cvt_pk_bf16_f32 v4, v10, v11
	v_cvt_pk_bf16_f32 v5, v12, v13
	global_store_dwordx4 v[46:47], v[2:5], off offset:2048
	global_load_dwordx4 v[2:5], v[26:27], off offset:16
	s_nop 0
	global_load_dwordx4 v[6:9], v[26:27], off
	global_load_dwordx4 v[10:13], v[28:29], off
	global_load_dwordx4 v[14:17], v[28:29], off offset:16
	s_waitcnt vmcnt(1)
	v_pk_fma_f32 v[6:7], v[6:7], v[84:85], v[10:11]
	s_waitcnt vmcnt(0)
	v_pk_fma_f32 v[10:11], v[2:3], v[86:87], v[14:15]
	v_pk_fma_f32 v[8:9], v[8:9], v[82:83], v[12:13]
	v_pk_fma_f32 v[12:13], v[4:5], v[80:81], v[16:17]
	v_cvt_pk_bf16_f32 v2, v6, v7
	v_cvt_pk_bf16_f32 v3, v8, v9
	v_cvt_pk_bf16_f32 v4, v10, v11
	v_cvt_pk_bf16_f32 v5, v12, v13
	global_store_dwordx4 v[46:47], v[2:5], off offset:3072
	global_load_dwordx4 v[2:5], v[30:31], off offset:16
	s_nop 0
	global_load_dwordx4 v[6:9], v[30:31], off
	global_load_dwordx4 v[10:13], v[32:33], off
	global_load_dwordx4 v[14:17], v[32:33], off offset:16
	v_add_co_u32_e32 v80, vcc, s59, v46
	s_waitcnt vmcnt(1)
	v_pk_fma_f32 v[6:7], v[6:7], v[72:73], v[10:11]
	s_waitcnt vmcnt(0)
	v_pk_fma_f32 v[10:11], v[2:3], v[76:77], v[14:15]
	v_pk_fma_f32 v[8:9], v[8:9], v[74:75], v[12:13]
	v_pk_fma_f32 v[12:13], v[4:5], v[78:79], v[16:17]
	v_addc_co_u32_e32 v81, vcc, 0, v47, vcc
	v_cvt_pk_bf16_f32 v2, v6, v7
	v_cvt_pk_bf16_f32 v3, v8, v9
	v_cvt_pk_bf16_f32 v4, v10, v11
	v_cvt_pk_bf16_f32 v5, v12, v13
	global_store_dwordx4 v[80:81], v[2:5], off
	global_load_dwordx4 v[2:5], v[34:35], off offset:16
	s_nop 0
	global_load_dwordx4 v[6:9], v[34:35], off
	global_load_dwordx4 v[10:13], v[36:37], off
	global_load_dwordx4 v[14:17], v[36:37], off offset:16
	v_lshl_add_u64 v[46:47], v[46:47], 0, s[4:5]
	s_waitcnt vmcnt(1)
	v_pk_fma_f32 v[6:7], v[6:7], v[68:69], v[10:11]
	s_waitcnt vmcnt(0)
	v_pk_fma_f32 v[10:11], v[2:3], v[70:71], v[14:15]
	v_pk_fma_f32 v[8:9], v[8:9], v[66:67], v[12:13]
	v_pk_fma_f32 v[12:13], v[4:5], v[64:65], v[16:17]
	v_cvt_pk_bf16_f32 v2, v6, v7
	v_cvt_pk_bf16_f32 v3, v8, v9
	v_cvt_pk_bf16_f32 v4, v10, v11
	v_cvt_pk_bf16_f32 v5, v12, v13
	global_store_dwordx4 v[80:81], v[2:5], off offset:1024
	global_load_dwordx4 v[2:5], v[38:39], off offset:16
	s_nop 0
	global_load_dwordx4 v[6:9], v[38:39], off
	global_load_dwordx4 v[10:13], v[40:41], off
	global_load_dwordx4 v[14:17], v[40:41], off offset:16
	s_waitcnt vmcnt(1)
	v_pk_fma_f32 v[6:7], v[6:7], v[60:61], v[10:11]
	s_waitcnt vmcnt(0)
	v_pk_fma_f32 v[10:11], v[2:3], v[62:63], v[14:15]
	v_pk_fma_f32 v[8:9], v[8:9], v[58:59], v[12:13]
	v_pk_fma_f32 v[12:13], v[4:5], v[56:57], v[16:17]
	v_cvt_pk_bf16_f32 v2, v6, v7
	v_cvt_pk_bf16_f32 v3, v8, v9
	v_cvt_pk_bf16_f32 v4, v10, v11
	v_cvt_pk_bf16_f32 v5, v12, v13
	global_store_dwordx4 v[80:81], v[2:5], off offset:2048
	global_load_dwordx4 v[2:5], v[42:43], off offset:16
	s_nop 0
	global_load_dwordx4 v[6:9], v[42:43], off
	global_load_dwordx4 v[10:13], v[44:45], off
	global_load_dwordx4 v[14:17], v[44:45], off offset:16
	s_waitcnt vmcnt(1)
	v_pk_fma_f32 v[6:7], v[6:7], v[48:49], v[10:11]
	s_waitcnt vmcnt(0)
	v_pk_fma_f32 v[10:11], v[2:3], v[52:53], v[14:15]
	v_pk_fma_f32 v[8:9], v[8:9], v[50:51], v[12:13]
	v_pk_fma_f32 v[12:13], v[4:5], v[54:55], v[16:17] op_sel:[0,1,0] op_sel_hi:[1,0,1]
	v_cvt_pk_bf16_f32 v2, v6, v7
	v_cvt_pk_bf16_f32 v3, v8, v9
	v_cvt_pk_bf16_f32 v4, v10, v11
	v_cvt_pk_bf16_f32 v5, v12, v13
	global_store_dwordx4 v[80:81], v[2:5], off offset:3072
	s_cbranch_scc0 .LBB0_839

.LBB0_902:
	s_add_u32 s12, s22, 0xfff00080
	s_addc_u32 s13, s23, -1
	s_add_i32 s56, 0, 0x10000
	s_cmp_eq_u32 s47, 60
	s_cselect_b32 s53, s5, s13
	s_cselect_b32 s52, s10, s12
	v_add_u32_e32 v147, s56, v144
	s_cselect_b32 s31, s25, s45
	s_cselect_b32 s30, s29, s33
	s_add_i32 s61, 0, 0x14000
	ds_read_b128 v[140:143], v147
	ds_read_b128 v[148:151], v147 offset:1024
	ds_read_b128 v[152:155], v147 offset:2048
	ds_read_b128 v[156:159], v147 offset:3072
	v_add_u32_e32 v147, s61, v144
	ds_read_b128 v[160:163], v147
	ds_read_b128 v[164:167], v147 offset:1024
	ds_read_b128 v[168:171], v147 offset:2048
	ds_read_b128 v[172:175], v147 offset:3072
	v_lshl_add_u64 v[188:189], s[22:23], 0, v[136:137]
	s_add_i32 m0, s63, 0xc000
	ds_read_b128 v[176:179], v146
	ds_read_b128 v[180:183], v146 offset:1024
	ds_read_b128 v[184:187], v146 offset:2048
	ds_read_b128 v[210:213], v146 offset:3072
	ds_read_b128 v[214:217], v146 offset:4096
	ds_read_b128 v[218:221], v146 offset:5120
	ds_read_b128 v[222:225], v146 offset:6144
	ds_read_b128 v[226:229], v146 offset:7168
	global_load_lds_dwordx4 v[188:189], off
	v_lshl_add_u64 v[188:189], s[22:23], 0, v[138:139]
	s_add_i32 m0, s63, 0xe000
	s_nop 0
	global_load_lds_dwordx4 v[188:189], off
	s_waitcnt vmcnt(8)
	s_waitcnt lgkmcnt(0)
	s_barrier
	s_setprio 1
	s_waitcnt lgkmcnt(0)
	v_mfma_f32_16x16x32_bf16 v[126:129], v[140:143], v[176:179], v[126:129]
	v_mfma_f32_16x16x32_bf16 v[126:129], v[148:151], v[180:183], v[126:129]
	v_mfma_f32_16x16x32_bf16 v[118:121], v[152:155], v[176:179], v[118:121]
	v_mfma_f32_16x16x32_bf16 v[118:121], v[156:159], v[180:183], v[118:121]
	v_mfma_f32_16x16x32_bf16 v[110:113], v[140:143], v[184:187], v[110:113]
	v_mfma_f32_16x16x32_bf16 v[110:113], v[148:151], v[210:213], v[110:113]
	v_mfma_f32_16x16x32_bf16 v[102:105], v[152:155], v[184:187], v[102:105]
	v_mfma_f32_16x16x32_bf16 v[102:105], v[156:159], v[210:213], v[102:105]
	v_mfma_f32_16x16x32_bf16 v[94:97], v[140:143], v[214:217], v[94:97]
	v_mfma_f32_16x16x32_bf16 v[94:97], v[148:151], v[218:221], v[94:97]
	v_mfma_f32_16x16x32_bf16 v[86:89], v[152:155], v[214:217], v[86:89]
	v_mfma_f32_16x16x32_bf16 v[86:89], v[156:159], v[218:221], v[86:89]
	v_mfma_f32_16x16x32_bf16 v[78:81], v[140:143], v[222:225], v[78:81]
	v_mfma_f32_16x16x32_bf16 v[78:81], v[148:151], v[226:229], v[78:81]
	v_mfma_f32_16x16x32_bf16 v[70:73], v[152:155], v[222:225], v[70:73]
	v_mfma_f32_16x16x32_bf16 v[70:73], v[156:159], v[226:229], v[70:73]
	s_setprio 0
	s_setprio 1
	v_mfma_f32_16x16x32_bf16 v[122:125], v[160:163], v[176:179], v[122:125]
	v_mfma_f32_16x16x32_bf16 v[122:125], v[164:167], v[180:183], v[122:125]
	v_mfma_f32_16x16x32_bf16 v[114:117], v[168:171], v[176:179], v[114:117]
	v_mfma_f32_16x16x32_bf16 v[114:117], v[172:175], v[180:183], v[114:117]
	v_mfma_f32_16x16x32_bf16 v[106:109], v[160:163], v[184:187], v[106:109]
	v_mfma_f32_16x16x32_bf16 v[106:109], v[164:167], v[210:213], v[106:109]
	v_mfma_f32_16x16x32_bf16 v[98:101], v[168:171], v[184:187], v[98:101]
	v_mfma_f32_16x16x32_bf16 v[98:101], v[172:175], v[210:213], v[98:101]
	v_mfma_f32_16x16x32_bf16 v[90:93], v[160:163], v[214:217], v[90:93]
	v_mfma_f32_16x16x32_bf16 v[90:93], v[164:167], v[218:221], v[90:93]
	v_mfma_f32_16x16x32_bf16 v[82:85], v[168:171], v[214:217], v[82:85]
	v_mfma_f32_16x16x32_bf16 v[82:85], v[172:175], v[218:221], v[82:85]
	v_mfma_f32_16x16x32_bf16 v[74:77], v[160:163], v[222:225], v[74:77]
	v_mfma_f32_16x16x32_bf16 v[74:77], v[164:167], v[226:229], v[74:77]
	v_mfma_f32_16x16x32_bf16 v[66:69], v[168:171], v[222:225], v[66:69]
	v_mfma_f32_16x16x32_bf16 v[66:69], v[172:175], v[226:229], v[66:69]
	s_setprio 0
	s_barrier
	s_add_i32 s12, s56, s60
	v_lshl_add_u64 v[188:189], s[30:31], 0, v[190:191]
	s_mov_b32 m0, s12
	ds_read_b128 v[176:179], v146 offset:16384
	ds_read_b128 v[180:183], v146 offset:17408
	ds_read_b128 v[184:187], v146 offset:18432
	ds_read_b128 v[210:213], v146 offset:19456
	ds_read_b128 v[214:217], v146 offset:20480
	ds_read_b128 v[218:221], v146 offset:21504
	ds_read_b128 v[222:225], v146 offset:22528
	ds_read_b128 v[226:229], v146 offset:23552
	global_load_lds_dwordx4 v[188:189], off
	s_add_i32 m0, s12, 0x2000
	s_add_u32 s12, s30, 0x100000
	v_lshl_add_u64 v[230:231], s[30:31], 0, v[130:131]
	s_addc_u32 s13, s31, 0
	s_add_i32 s56, s61, s60
	global_load_lds_dwordx4 v[230:231], off
	v_lshl_add_u64 v[232:233], s[12:13], 0, v[190:191]
	s_mov_b32 m0, s56
	v_lshl_add_u64 v[234:235], s[52:53], 0, v[132:133]
	global_load_lds_dwordx4 v[232:233], off
	v_lshl_add_u64 v[232:233], s[12:13], 0, v[130:131]
	s_add_i32 m0, s56, 0x2000
	s_nop 0
	global_load_lds_dwordx4 v[232:233], off
	v_lshl_add_u64 v[232:233], s[52:53], 0, v[134:135]
	s_mov_b32 m0, s63
	s_nop 0
	global_load_lds_dwordx4 v[232:233], off
	s_mov_b32 m0, s64
	s_nop 0
	global_load_lds_dwordx4 v[234:235], off
	s_waitcnt vmcnt(8)
	s_waitcnt lgkmcnt(0)
	s_barrier
	s_setprio 1
	s_waitcnt lgkmcnt(0)
	v_mfma_f32_16x16x32_bf16 v[62:65], v[140:143], v[176:179], v[62:65]
	v_mfma_f32_16x16x32_bf16 v[62:65], v[148:151], v[180:183], v[62:65]
	v_mfma_f32_16x16x32_bf16 v[54:57], v[152:155], v[176:179], v[54:57]
	v_mfma_f32_16x16x32_bf16 v[54:57], v[156:159], v[180:183], v[54:57]
	v_mfma_f32_16x16x32_bf16 v[46:49], v[140:143], v[184:187], v[46:49]
	v_mfma_f32_16x16x32_bf16 v[46:49], v[148:151], v[210:213], v[46:49]
	v_mfma_f32_16x16x32_bf16 v[38:41], v[152:155], v[184:187], v[38:41]
	v_mfma_f32_16x16x32_bf16 v[38:41], v[156:159], v[210:213], v[38:41]
	v_mfma_f32_16x16x32_bf16 v[30:33], v[140:143], v[214:217], v[30:33]
	v_mfma_f32_16x16x32_bf16 v[30:33], v[148:151], v[218:221], v[30:33]
	v_mfma_f32_16x16x32_bf16 v[22:25], v[152:155], v[214:217], v[22:25]
	v_mfma_f32_16x16x32_bf16 v[22:25], v[156:159], v[218:221], v[22:25]
	v_mfma_f32_16x16x32_bf16 v[14:17], v[140:143], v[222:225], v[14:17]
	v_mfma_f32_16x16x32_bf16 v[14:17], v[148:151], v[226:229], v[14:17]
	v_mfma_f32_16x16x32_bf16 v[6:9], v[152:155], v[222:225], v[6:9]
	v_mfma_f32_16x16x32_bf16 v[6:9], v[156:159], v[226:229], v[6:9]
	s_setprio 0
	s_setprio 1
	v_mfma_f32_16x16x32_bf16 v[58:61], v[160:163], v[176:179], v[58:61]
	v_mfma_f32_16x16x32_bf16 v[58:61], v[164:167], v[180:183], v[58:61]
	v_mfma_f32_16x16x32_bf16 v[50:53], v[168:171], v[176:179], v[50:53]
	v_mfma_f32_16x16x32_bf16 v[50:53], v[172:175], v[180:183], v[50:53]
	v_mfma_f32_16x16x32_bf16 v[42:45], v[160:163], v[184:187], v[42:45]
	v_mfma_f32_16x16x32_bf16 v[42:45], v[164:167], v[210:213], v[42:45]
	v_mfma_f32_16x16x32_bf16 v[34:37], v[168:171], v[184:187], v[34:37]
	v_mfma_f32_16x16x32_bf16 v[34:37], v[172:175], v[210:213], v[34:37]
	v_mfma_f32_16x16x32_bf16 v[26:29], v[160:163], v[214:217], v[26:29]
	v_mfma_f32_16x16x32_bf16 v[26:29], v[164:167], v[218:221], v[26:29]
	v_mfma_f32_16x16x32_bf16 v[18:21], v[168:171], v[214:217], v[18:21]
	v_mfma_f32_16x16x32_bf16 v[18:21], v[172:175], v[218:221], v[18:21]
	v_mfma_f32_16x16x32_bf16 v[10:13], v[160:163], v[222:225], v[10:13]
	v_mfma_f32_16x16x32_bf16 v[10:13], v[164:167], v[226:229], v[10:13]
	v_mfma_f32_16x16x32_bf16 v[2:5], v[168:171], v[222:225], v[2:5]
	v_mfma_f32_16x16x32_bf16 v[2:5], v[172:175], v[226:229], v[2:5]
	s_setprio 0
	s_barrier
	s_add_i32 s56, 0, 0x18000
	v_add_u32_e32 v147, s56, v144
	s_add_i32 s61, 0, 0x1c000
	ds_read_b128 v[140:143], v147
	ds_read_b128 v[148:151], v147 offset:1024
	ds_read_b128 v[152:155], v147 offset:2048
	ds_read_b128 v[156:159], v147 offset:3072
	v_add_u32_e32 v147, s61, v144
	ds_read_b128 v[160:163], v147
	ds_read_b128 v[164:167], v147 offset:1024
	ds_read_b128 v[168:171], v147 offset:2048
	ds_read_b128 v[172:175], v147 offset:3072
	s_add_u32 s12, s52, 0x100000
	s_addc_u32 s13, s53, 0
	s_mov_b32 m0, s65
	v_lshl_add_u64 v[244:245], s[12:13], 0, v[134:135]
	ds_read_b128 v[176:179], v146 offset:32768
	ds_read_b128 v[180:183], v146 offset:33792
	ds_read_b128 v[184:187], v146 offset:34816
	ds_read_b128 v[210:213], v146 offset:35840
	ds_read_b128 v[214:217], v146 offset:36864
	ds_read_b128 v[218:221], v146 offset:37888
	ds_read_b128 v[222:225], v146 offset:38912
	ds_read_b128 v[226:229], v146 offset:39936
	global_load_lds_dwordx4 v[244:245], off
	v_lshl_add_u64 v[244:245], s[12:13], 0, v[132:133]
	s_mov_b32 m0, s66
	s_nop 0
	global_load_lds_dwordx4 v[244:245], off
	s_waitcnt vmcnt(8)
	s_waitcnt lgkmcnt(0)
	s_barrier
	s_setprio 1
	s_waitcnt lgkmcnt(0)
	v_mfma_f32_16x16x32_bf16 v[126:129], v[140:143], v[176:179], v[126:129]
	v_mfma_f32_16x16x32_bf16 v[126:129], v[148:151], v[180:183], v[126:129]
	v_mfma_f32_16x16x32_bf16 v[118:121], v[152:155], v[176:179], v[118:121]
	v_mfma_f32_16x16x32_bf16 v[118:121], v[156:159], v[180:183], v[118:121]
	v_mfma_f32_16x16x32_bf16 v[110:113], v[140:143], v[184:187], v[110:113]
	v_mfma_f32_16x16x32_bf16 v[110:113], v[148:151], v[210:213], v[110:113]
	v_mfma_f32_16x16x32_bf16 v[102:105], v[152:155], v[184:187], v[102:105]
	v_mfma_f32_16x16x32_bf16 v[102:105], v[156:159], v[210:213], v[102:105]
	v_mfma_f32_16x16x32_bf16 v[94:97], v[140:143], v[214:217], v[94:97]
	v_mfma_f32_16x16x32_bf16 v[94:97], v[148:151], v[218:221], v[94:97]
	v_mfma_f32_16x16x32_bf16 v[86:89], v[152:155], v[214:217], v[86:89]
	v_mfma_f32_16x16x32_bf16 v[86:89], v[156:159], v[218:221], v[86:89]
	v_mfma_f32_16x16x32_bf16 v[78:81], v[140:143], v[222:225], v[78:81]
	v_mfma_f32_16x16x32_bf16 v[78:81], v[148:151], v[226:229], v[78:81]
	v_mfma_f32_16x16x32_bf16 v[70:73], v[152:155], v[222:225], v[70:73]
	v_mfma_f32_16x16x32_bf16 v[70:73], v[156:159], v[226:229], v[70:73]
	s_setprio 0
	s_setprio 1
	v_mfma_f32_16x16x32_bf16 v[122:125], v[160:163], v[176:179], v[122:125]
	v_mfma_f32_16x16x32_bf16 v[122:125], v[164:167], v[180:183], v[122:125]
	v_mfma_f32_16x16x32_bf16 v[114:117], v[168:171], v[176:179], v[114:117]
	v_mfma_f32_16x16x32_bf16 v[114:117], v[172:175], v[180:183], v[114:117]
	v_mfma_f32_16x16x32_bf16 v[106:109], v[160:163], v[184:187], v[106:109]
	v_mfma_f32_16x16x32_bf16 v[106:109], v[164:167], v[210:213], v[106:109]
	v_mfma_f32_16x16x32_bf16 v[98:101], v[168:171], v[184:187], v[98:101]
	v_mfma_f32_16x16x32_bf16 v[98:101], v[172:175], v[210:213], v[98:101]
	v_mfma_f32_16x16x32_bf16 v[90:93], v[160:163], v[214:217], v[90:93]
	v_mfma_f32_16x16x32_bf16 v[90:93], v[164:167], v[218:221], v[90:93]
	v_mfma_f32_16x16x32_bf16 v[82:85], v[168:171], v[214:217], v[82:85]
	v_mfma_f32_16x16x32_bf16 v[82:85], v[172:175], v[218:221], v[82:85]
	v_mfma_f32_16x16x32_bf16 v[74:77], v[160:163], v[222:225], v[74:77]
	v_mfma_f32_16x16x32_bf16 v[74:77], v[164:167], v[226:229], v[74:77]
	v_mfma_f32_16x16x32_bf16 v[66:69], v[168:171], v[222:225], v[66:69]
	v_mfma_f32_16x16x32_bf16 v[66:69], v[172:175], v[226:229], v[66:69]
	s_setprio 0
	s_barrier
	s_add_i32 s12, s56, s60
	v_lshl_add_u64 v[188:189], v[188:189], 0, s[34:35]
	s_mov_b32 m0, s12
	ds_read_b128 v[176:179], v146 offset:49152
	ds_read_b128 v[180:183], v146 offset:50176
	ds_read_b128 v[184:187], v146 offset:51200
	ds_read_b128 v[210:213], v146 offset:52224
	ds_read_b128 v[214:217], v146 offset:53248
	ds_read_b128 v[218:221], v146 offset:54272
	ds_read_b128 v[222:225], v146 offset:55296
	ds_read_b128 v[226:229], v146 offset:56320
	global_load_lds_dwordx4 v[188:189], off
	s_add_i32 m0, s12, 0x2000
	s_add_u32 s12, s30, 0x100080
	v_lshl_add_u64 v[188:189], v[230:231], 0, s[34:35]
	s_addc_u32 s13, s31, 0
	s_add_i32 s30, s61, s60
	global_load_lds_dwordx4 v[188:189], off
	v_lshl_add_u64 v[188:189], s[12:13], 0, v[190:191]
	s_mov_b32 m0, s30
	s_nop 0
	global_load_lds_dwordx4 v[188:189], off
	v_lshl_add_u64 v[188:189], s[12:13], 0, v[130:131]
	s_add_i32 m0, s30, 0x2000
	s_nop 0
	global_load_lds_dwordx4 v[188:189], off
	v_lshl_add_u64 v[188:189], v[232:233], 0, s[34:35]
	s_mov_b32 m0, s68
	s_nop 0
	global_load_lds_dwordx4 v[188:189], off
	v_lshl_add_u64 v[188:189], v[234:235], 0, s[34:35]
	s_mov_b32 m0, s69
	s_nop 0
	global_load_lds_dwordx4 v[188:189], off
	s_waitcnt vmcnt(8)
	s_waitcnt lgkmcnt(0)
	s_barrier
	s_setprio 1
	s_waitcnt lgkmcnt(0)
	v_mfma_f32_16x16x32_bf16 v[62:65], v[140:143], v[176:179], v[62:65]
	v_mfma_f32_16x16x32_bf16 v[62:65], v[148:151], v[180:183], v[62:65]
	v_mfma_f32_16x16x32_bf16 v[54:57], v[152:155], v[176:179], v[54:57]
	v_mfma_f32_16x16x32_bf16 v[54:57], v[156:159], v[180:183], v[54:57]
	v_mfma_f32_16x16x32_bf16 v[46:49], v[140:143], v[184:187], v[46:49]
	v_mfma_f32_16x16x32_bf16 v[46:49], v[148:151], v[210:213], v[46:49]
	v_mfma_f32_16x16x32_bf16 v[38:41], v[152:155], v[184:187], v[38:41]
	v_mfma_f32_16x16x32_bf16 v[38:41], v[156:159], v[210:213], v[38:41]
	v_mfma_f32_16x16x32_bf16 v[30:33], v[140:143], v[214:217], v[30:33]
	v_mfma_f32_16x16x32_bf16 v[30:33], v[148:151], v[218:221], v[30:33]
	v_mfma_f32_16x16x32_bf16 v[22:25], v[152:155], v[214:217], v[22:25]
	v_mfma_f32_16x16x32_bf16 v[22:25], v[156:159], v[218:221], v[22:25]
	v_mfma_f32_16x16x32_bf16 v[14:17], v[140:143], v[222:225], v[14:17]
	v_mfma_f32_16x16x32_bf16 v[14:17], v[148:151], v[226:229], v[14:17]
	v_mfma_f32_16x16x32_bf16 v[6:9], v[152:155], v[222:225], v[6:9]
	v_mfma_f32_16x16x32_bf16 v[6:9], v[156:159], v[226:229], v[6:9]
	s_setprio 0
	s_setprio 1
	v_mfma_f32_16x16x32_bf16 v[58:61], v[160:163], v[176:179], v[58:61]
	v_mfma_f32_16x16x32_bf16 v[58:61], v[164:167], v[180:183], v[58:61]
	v_mfma_f32_16x16x32_bf16 v[50:53], v[168:171], v[176:179], v[50:53]
	v_mfma_f32_16x16x32_bf16 v[50:53], v[172:175], v[180:183], v[50:53]
	v_mfma_f32_16x16x32_bf16 v[42:45], v[160:163], v[184:187], v[42:45]
	v_mfma_f32_16x16x32_bf16 v[42:45], v[164:167], v[210:213], v[42:45]
	v_mfma_f32_16x16x32_bf16 v[34:37], v[168:171], v[184:187], v[34:37]
	v_mfma_f32_16x16x32_bf16 v[34:37], v[172:175], v[210:213], v[34:37]
	v_mfma_f32_16x16x32_bf16 v[26:29], v[160:163], v[214:217], v[26:29]
	v_mfma_f32_16x16x32_bf16 v[26:29], v[164:167], v[218:221], v[26:29]
	v_mfma_f32_16x16x32_bf16 v[18:21], v[168:171], v[214:217], v[18:21]
	v_mfma_f32_16x16x32_bf16 v[18:21], v[172:175], v[218:221], v[18:21]
	v_mfma_f32_16x16x32_bf16 v[10:13], v[160:163], v[222:225], v[10:13]
	v_mfma_f32_16x16x32_bf16 v[10:13], v[164:167], v[226:229], v[10:13]
	v_mfma_f32_16x16x32_bf16 v[2:5], v[168:171], v[222:225], v[2:5]
	v_mfma_f32_16x16x32_bf16 v[2:5], v[172:175], v[226:229], v[2:5]
	s_setprio 0
	s_barrier
	s_add_i32 s47, s47, 2
	s_add_u32 s22, s22, 0x100
	s_addc_u32 s23, s23, 0
	s_add_u32 s33, s33, 0x100
	s_addc_u32 s45, s45, 0
	s_cmp_gt_u32 s47, 61
	s_cbranch_scc0 .LBB0_902
	s_and_b64 vcc, exec, s[42:43]
	s_cbranch_vccz .LBB0_905
	s_barrier

.LBB0_983:
	s_add_u32 s46, s44, 0x100
	s_addc_u32 s47, s45, 0
	s_add_i32 s12, 0, 0x10000
	s_cmpk_eq_i32 s70, 0xa8
	s_cselect_b32 s51, s41, s47
	s_cselect_b32 s50, s40, s46
	s_cselect_b32 s49, s43, s69
	s_cselect_b32 s48, s42, s61
	s_add_i32 s56, 0, 0x14000
	v_add_u32_e32 v142, s12, v193
	v_add_u32_e32 v158, s56, v193
	ds_read_b128 v[130:133], v142
	ds_read_b128 v[134:137], v142 offset:1024
	ds_read_b128 v[138:141], v142 offset:2048
	ds_read_b128 v[142:145], v142 offset:3072
	ds_read_b128 v[146:149], v158
	ds_read_b128 v[150:153], v158 offset:1024
	ds_read_b128 v[154:157], v158 offset:2048
	ds_read_b128 v[158:161], v158 offset:3072
	v_lshl_add_u64 v[224:225], s[44:45], 0, v[216:217]
	s_add_i32 m0, s33, 0xc000
	ds_read_b128 v[162:165], v197
	ds_read_b128 v[166:169], v197 offset:1024
	ds_read_b128 v[170:173], v197 offset:2048
	ds_read_b128 v[174:177], v197 offset:3072
	ds_read_b128 v[178:181], v197 offset:4096
	ds_read_b128 v[182:185], v197 offset:5120
	ds_read_b128 v[186:189], v197 offset:6144
	ds_read_b128 v[220:223], v197 offset:7168
	global_load_lds_dwordx4 v[224:225], off
	v_lshl_add_u64 v[224:225], s[44:45], 0, v[218:219]
	s_add_i32 m0, s33, 0xe000
	s_nop 0
	global_load_lds_dwordx4 v[224:225], off
	s_waitcnt vmcnt(8)
	s_waitcnt lgkmcnt(0)
	s_barrier
	s_setprio 1
	s_waitcnt lgkmcnt(0)
	v_mfma_f32_16x16x32_bf16 v[126:129], v[130:133], v[162:165], v[126:129]
	v_mfma_f32_16x16x32_bf16 v[126:129], v[134:137], v[166:169], v[126:129]
	v_mfma_f32_16x16x32_bf16 v[122:125], v[138:141], v[162:165], v[122:125]
	v_mfma_f32_16x16x32_bf16 v[122:125], v[142:145], v[166:169], v[122:125]
	v_mfma_f32_16x16x32_bf16 v[110:113], v[130:133], v[170:173], v[110:113]
	v_mfma_f32_16x16x32_bf16 v[110:113], v[134:137], v[174:177], v[110:113]
	v_mfma_f32_16x16x32_bf16 v[106:109], v[138:141], v[170:173], v[106:109]
	v_mfma_f32_16x16x32_bf16 v[106:109], v[142:145], v[174:177], v[106:109]
	v_mfma_f32_16x16x32_bf16 v[98:101], v[130:133], v[178:181], v[98:101]
	v_mfma_f32_16x16x32_bf16 v[98:101], v[134:137], v[182:185], v[98:101]
	v_mfma_f32_16x16x32_bf16 v[90:93], v[138:141], v[178:181], v[90:93]
	v_mfma_f32_16x16x32_bf16 v[90:93], v[142:145], v[182:185], v[90:93]
	v_mfma_f32_16x16x32_bf16 v[82:85], v[130:133], v[186:189], v[82:85]
	v_mfma_f32_16x16x32_bf16 v[82:85], v[134:137], v[220:223], v[82:85]
	v_mfma_f32_16x16x32_bf16 v[74:77], v[138:141], v[186:189], v[74:77]
	v_mfma_f32_16x16x32_bf16 v[74:77], v[142:145], v[220:223], v[74:77]
	s_setprio 0
	s_setprio 1
	v_mfma_f32_16x16x32_bf16 v[118:121], v[146:149], v[162:165], v[118:121]
	v_mfma_f32_16x16x32_bf16 v[118:121], v[150:153], v[166:169], v[118:121]
	v_mfma_f32_16x16x32_bf16 v[114:117], v[154:157], v[162:165], v[114:117]
	v_mfma_f32_16x16x32_bf16 v[114:117], v[158:161], v[166:169], v[114:117]
	v_mfma_f32_16x16x32_bf16 v[102:105], v[146:149], v[170:173], v[102:105]
	v_mfma_f32_16x16x32_bf16 v[102:105], v[150:153], v[174:177], v[102:105]
	v_mfma_f32_16x16x32_bf16 v[94:97], v[154:157], v[170:173], v[94:97]
	v_mfma_f32_16x16x32_bf16 v[94:97], v[158:161], v[174:177], v[94:97]
	v_mfma_f32_16x16x32_bf16 v[86:89], v[146:149], v[178:181], v[86:89]
	v_mfma_f32_16x16x32_bf16 v[86:89], v[150:153], v[182:185], v[86:89]
	v_mfma_f32_16x16x32_bf16 v[78:81], v[154:157], v[178:181], v[78:81]
	v_mfma_f32_16x16x32_bf16 v[78:81], v[158:161], v[182:185], v[78:81]
	v_mfma_f32_16x16x32_bf16 v[70:73], v[146:149], v[186:189], v[70:73]
	v_mfma_f32_16x16x32_bf16 v[70:73], v[150:153], v[220:223], v[70:73]
	v_mfma_f32_16x16x32_bf16 v[66:69], v[154:157], v[186:189], v[66:69]
	v_mfma_f32_16x16x32_bf16 v[66:69], v[158:161], v[220:223], v[66:69]
	s_setprio 0
	s_barrier
	s_add_i32 s12, s12, s29
	v_lshl_add_u64 v[224:225], s[48:49], 0, v[190:191]
	s_mov_b32 m0, s12
	ds_read_b128 v[162:165], v197 offset:16384
	ds_read_b128 v[166:169], v197 offset:17408
	ds_read_b128 v[170:173], v197 offset:18432
	ds_read_b128 v[174:177], v197 offset:19456
	ds_read_b128 v[178:181], v197 offset:20480
	ds_read_b128 v[182:185], v197 offset:21504
	ds_read_b128 v[186:189], v197 offset:22528
	ds_read_b128 v[220:223], v197 offset:23552
	global_load_lds_dwordx4 v[224:225], off
	s_add_i32 m0, s12, 0x2000
	s_add_u32 s12, s48, 0x2b0000
	v_lshl_add_u64 v[226:227], s[48:49], 0, v[214:215]
	s_addc_u32 s13, s49, 0
	s_add_i32 s44, s56, s29
	global_load_lds_dwordx4 v[226:227], off
	v_lshl_add_u64 v[228:229], s[12:13], 0, v[190:191]
	s_mov_b32 m0, s44
	v_lshl_add_u64 v[230:231], s[50:51], 0, v[212:213]
	global_load_lds_dwordx4 v[228:229], off
	v_lshl_add_u64 v[228:229], s[12:13], 0, v[214:215]
	s_add_i32 m0, s44, 0x2000
	s_nop 0
	global_load_lds_dwordx4 v[228:229], off
	v_lshl_add_u64 v[228:229], s[50:51], 0, v[210:211]
	s_mov_b32 m0, s33
	s_nop 0
	global_load_lds_dwordx4 v[228:229], off
	s_mov_b32 m0, s57
	s_nop 0
	global_load_lds_dwordx4 v[230:231], off
	s_waitcnt vmcnt(8)
	s_waitcnt lgkmcnt(0)
	s_barrier
	s_setprio 1
	s_waitcnt lgkmcnt(0)
	v_mfma_f32_16x16x32_bf16 v[62:65], v[130:133], v[162:165], v[62:65]
	v_mfma_f32_16x16x32_bf16 v[62:65], v[134:137], v[166:169], v[62:65]
	v_mfma_f32_16x16x32_bf16 v[58:61], v[138:141], v[162:165], v[58:61]
	v_mfma_f32_16x16x32_bf16 v[58:61], v[142:145], v[166:169], v[58:61]
	v_mfma_f32_16x16x32_bf16 v[50:53], v[130:133], v[170:173], v[50:53]
	v_mfma_f32_16x16x32_bf16 v[50:53], v[134:137], v[174:177], v[50:53]
	v_mfma_f32_16x16x32_bf16 v[42:45], v[138:141], v[170:173], v[42:45]
	v_mfma_f32_16x16x32_bf16 v[42:45], v[142:145], v[174:177], v[42:45]
	v_mfma_f32_16x16x32_bf16 v[34:37], v[130:133], v[178:181], v[34:37]
	v_mfma_f32_16x16x32_bf16 v[34:37], v[134:137], v[182:185], v[34:37]
	v_mfma_f32_16x16x32_bf16 v[26:29], v[138:141], v[178:181], v[26:29]
	v_mfma_f32_16x16x32_bf16 v[26:29], v[142:145], v[182:185], v[26:29]
	v_mfma_f32_16x16x32_bf16 v[18:21], v[130:133], v[186:189], v[18:21]
	v_mfma_f32_16x16x32_bf16 v[18:21], v[134:137], v[220:223], v[18:21]
	v_mfma_f32_16x16x32_bf16 v[10:13], v[138:141], v[186:189], v[10:13]
	v_mfma_f32_16x16x32_bf16 v[10:13], v[142:145], v[220:223], v[10:13]
	s_setprio 0
	s_setprio 1
	v_mfma_f32_16x16x32_bf16 v[54:57], v[146:149], v[162:165], v[54:57]
	v_mfma_f32_16x16x32_bf16 v[54:57], v[150:153], v[166:169], v[54:57]
	v_mfma_f32_16x16x32_bf16 v[46:49], v[154:157], v[162:165], v[46:49]
	v_mfma_f32_16x16x32_bf16 v[46:49], v[158:161], v[166:169], v[46:49]
	v_mfma_f32_16x16x32_bf16 v[38:41], v[146:149], v[170:173], v[38:41]
	v_mfma_f32_16x16x32_bf16 v[38:41], v[150:153], v[174:177], v[38:41]
	v_mfma_f32_16x16x32_bf16 v[30:33], v[154:157], v[170:173], v[30:33]
	v_mfma_f32_16x16x32_bf16 v[30:33], v[158:161], v[174:177], v[30:33]
	v_mfma_f32_16x16x32_bf16 v[22:25], v[146:149], v[178:181], v[22:25]
	v_mfma_f32_16x16x32_bf16 v[22:25], v[150:153], v[182:185], v[22:25]
	v_mfma_f32_16x16x32_bf16 v[14:17], v[154:157], v[178:181], v[14:17]
	v_mfma_f32_16x16x32_bf16 v[14:17], v[158:161], v[182:185], v[14:17]
	v_mfma_f32_16x16x32_bf16 v[6:9], v[146:149], v[186:189], v[6:9]
	v_mfma_f32_16x16x32_bf16 v[6:9], v[150:153], v[220:223], v[6:9]
	v_mfma_f32_16x16x32_bf16 v[2:5], v[154:157], v[186:189], v[2:5]
	v_mfma_f32_16x16x32_bf16 v[2:5], v[158:161], v[220:223], v[2:5]
	s_setprio 0
	s_barrier
	s_add_i32 s44, 0, 0x18000
	s_add_i32 s45, 0, 0x1c000
	v_add_u32_e32 v142, s44, v193
	v_add_u32_e32 v158, s45, v193
	ds_read_b128 v[130:133], v142
	ds_read_b128 v[134:137], v142 offset:1024
	ds_read_b128 v[138:141], v142 offset:2048
	ds_read_b128 v[142:145], v142 offset:3072
	ds_read_b128 v[146:149], v158
	ds_read_b128 v[150:153], v158 offset:1024
	ds_read_b128 v[154:157], v158 offset:2048
	ds_read_b128 v[158:161], v158 offset:3072
	s_add_u32 s12, s50, 0x2b0000
	s_addc_u32 s13, s51, 0
	s_mov_b32 m0, s58
	v_lshl_add_u64 v[232:233], s[12:13], 0, v[210:211]
	ds_read_b128 v[162:165], v197 offset:32768
	ds_read_b128 v[166:169], v197 offset:33792
	ds_read_b128 v[170:173], v197 offset:34816
	ds_read_b128 v[174:177], v197 offset:35840
	ds_read_b128 v[178:181], v197 offset:36864
	ds_read_b128 v[182:185], v197 offset:37888
	ds_read_b128 v[186:189], v197 offset:38912
	ds_read_b128 v[220:223], v197 offset:39936
	global_load_lds_dwordx4 v[232:233], off
	v_lshl_add_u64 v[232:233], s[12:13], 0, v[212:213]
	s_mov_b32 m0, s59
	s_nop 0
	global_load_lds_dwordx4 v[232:233], off
	s_waitcnt vmcnt(8)
	s_waitcnt lgkmcnt(0)
	s_barrier
	s_setprio 1
	s_waitcnt lgkmcnt(0)
	v_mfma_f32_16x16x32_bf16 v[126:129], v[130:133], v[162:165], v[126:129]
	v_mfma_f32_16x16x32_bf16 v[126:129], v[134:137], v[166:169], v[126:129]
	v_mfma_f32_16x16x32_bf16 v[122:125], v[138:141], v[162:165], v[122:125]
	v_mfma_f32_16x16x32_bf16 v[122:125], v[142:145], v[166:169], v[122:125]
	v_mfma_f32_16x16x32_bf16 v[110:113], v[130:133], v[170:173], v[110:113]
	v_mfma_f32_16x16x32_bf16 v[110:113], v[134:137], v[174:177], v[110:113]
	v_mfma_f32_16x16x32_bf16 v[106:109], v[138:141], v[170:173], v[106:109]
	v_mfma_f32_16x16x32_bf16 v[106:109], v[142:145], v[174:177], v[106:109]
	v_mfma_f32_16x16x32_bf16 v[98:101], v[130:133], v[178:181], v[98:101]
	v_mfma_f32_16x16x32_bf16 v[98:101], v[134:137], v[182:185], v[98:101]
	v_mfma_f32_16x16x32_bf16 v[90:93], v[138:141], v[178:181], v[90:93]
	v_mfma_f32_16x16x32_bf16 v[90:93], v[142:145], v[182:185], v[90:93]
	v_mfma_f32_16x16x32_bf16 v[82:85], v[130:133], v[186:189], v[82:85]
	v_mfma_f32_16x16x32_bf16 v[82:85], v[134:137], v[220:223], v[82:85]
	v_mfma_f32_16x16x32_bf16 v[74:77], v[138:141], v[186:189], v[74:77]
	v_mfma_f32_16x16x32_bf16 v[74:77], v[142:145], v[220:223], v[74:77]
	s_setprio 0
	s_setprio 1
	v_mfma_f32_16x16x32_bf16 v[118:121], v[146:149], v[162:165], v[118:121]
	v_mfma_f32_16x16x32_bf16 v[118:121], v[150:153], v[166:169], v[118:121]
	v_mfma_f32_16x16x32_bf16 v[114:117], v[154:157], v[162:165], v[114:117]
	v_mfma_f32_16x16x32_bf16 v[114:117], v[158:161], v[166:169], v[114:117]
	v_mfma_f32_16x16x32_bf16 v[102:105], v[146:149], v[170:173], v[102:105]
	v_mfma_f32_16x16x32_bf16 v[102:105], v[150:153], v[174:177], v[102:105]
	v_mfma_f32_16x16x32_bf16 v[94:97], v[154:157], v[170:173], v[94:97]
	v_mfma_f32_16x16x32_bf16 v[94:97], v[158:161], v[174:177], v[94:97]
	v_mfma_f32_16x16x32_bf16 v[86:89], v[146:149], v[178:181], v[86:89]
	v_mfma_f32_16x16x32_bf16 v[86:89], v[150:153], v[182:185], v[86:89]
	v_mfma_f32_16x16x32_bf16 v[78:81], v[154:157], v[178:181], v[78:81]
	v_mfma_f32_16x16x32_bf16 v[78:81], v[158:161], v[182:185], v[78:81]
	v_mfma_f32_16x16x32_bf16 v[70:73], v[146:149], v[186:189], v[70:73]
	v_mfma_f32_16x16x32_bf16 v[70:73], v[150:153], v[220:223], v[70:73]
	v_mfma_f32_16x16x32_bf16 v[66:69], v[154:157], v[186:189], v[66:69]
	v_mfma_f32_16x16x32_bf16 v[66:69], v[158:161], v[220:223], v[66:69]
	s_setprio 0
	s_barrier
	s_add_i32 s12, s44, s29
	v_lshl_add_u64 v[224:225], v[224:225], 0, s[34:35]
	s_mov_b32 m0, s12
	ds_read_b128 v[162:165], v197 offset:49152
	ds_read_b128 v[166:169], v197 offset:50176
	ds_read_b128 v[170:173], v197 offset:51200
	ds_read_b128 v[174:177], v197 offset:52224
	ds_read_b128 v[178:181], v197 offset:53248
	ds_read_b128 v[182:185], v197 offset:54272
	ds_read_b128 v[186:189], v197 offset:55296
	ds_read_b128 v[220:223], v197 offset:56320
	global_load_lds_dwordx4 v[224:225], off
	s_add_i32 m0, s12, 0x2000
	s_add_u32 s12, s48, 0x2b0080
	v_lshl_add_u64 v[224:225], v[226:227], 0, s[34:35]
	s_addc_u32 s13, s49, 0
	s_add_i32 s44, s45, s29
	global_load_lds_dwordx4 v[224:225], off
	v_lshl_add_u64 v[224:225], s[12:13], 0, v[190:191]
	s_mov_b32 m0, s44
	s_nop 0
	global_load_lds_dwordx4 v[224:225], off
	v_lshl_add_u64 v[224:225], s[12:13], 0, v[214:215]
	s_add_i32 m0, s44, 0x2000
	s_nop 0
	global_load_lds_dwordx4 v[224:225], off
	v_lshl_add_u64 v[224:225], v[228:229], 0, s[34:35]
	s_mov_b32 m0, s60
	s_nop 0
	global_load_lds_dwordx4 v[224:225], off
	v_lshl_add_u64 v[224:225], v[230:231], 0, s[34:35]
	s_mov_b32 m0, s62
	s_nop 0
	global_load_lds_dwordx4 v[224:225], off
	s_waitcnt vmcnt(8)
	s_waitcnt lgkmcnt(0)
	s_barrier
	s_setprio 1
	s_waitcnt lgkmcnt(0)
	v_mfma_f32_16x16x32_bf16 v[62:65], v[130:133], v[162:165], v[62:65]
	v_mfma_f32_16x16x32_bf16 v[62:65], v[134:137], v[166:169], v[62:65]
	v_mfma_f32_16x16x32_bf16 v[58:61], v[138:141], v[162:165], v[58:61]
	v_mfma_f32_16x16x32_bf16 v[58:61], v[142:145], v[166:169], v[58:61]
	v_mfma_f32_16x16x32_bf16 v[50:53], v[130:133], v[170:173], v[50:53]
	v_mfma_f32_16x16x32_bf16 v[50:53], v[134:137], v[174:177], v[50:53]
	v_mfma_f32_16x16x32_bf16 v[42:45], v[138:141], v[170:173], v[42:45]
	v_mfma_f32_16x16x32_bf16 v[42:45], v[142:145], v[174:177], v[42:45]
	v_mfma_f32_16x16x32_bf16 v[34:37], v[130:133], v[178:181], v[34:37]
	v_mfma_f32_16x16x32_bf16 v[34:37], v[134:137], v[182:185], v[34:37]
	v_mfma_f32_16x16x32_bf16 v[26:29], v[138:141], v[178:181], v[26:29]
	v_mfma_f32_16x16x32_bf16 v[26:29], v[142:145], v[182:185], v[26:29]
	v_mfma_f32_16x16x32_bf16 v[18:21], v[130:133], v[186:189], v[18:21]
	v_mfma_f32_16x16x32_bf16 v[18:21], v[134:137], v[220:223], v[18:21]
	v_mfma_f32_16x16x32_bf16 v[10:13], v[138:141], v[186:189], v[10:13]
	v_mfma_f32_16x16x32_bf16 v[10:13], v[142:145], v[220:223], v[10:13]
	s_setprio 0
	s_setprio 1
	v_mfma_f32_16x16x32_bf16 v[54:57], v[146:149], v[162:165], v[54:57]
	v_mfma_f32_16x16x32_bf16 v[54:57], v[150:153], v[166:169], v[54:57]
	v_mfma_f32_16x16x32_bf16 v[46:49], v[154:157], v[162:165], v[46:49]
	v_mfma_f32_16x16x32_bf16 v[46:49], v[158:161], v[166:169], v[46:49]
	v_mfma_f32_16x16x32_bf16 v[38:41], v[146:149], v[170:173], v[38:41]
	v_mfma_f32_16x16x32_bf16 v[38:41], v[150:153], v[174:177], v[38:41]
	v_mfma_f32_16x16x32_bf16 v[30:33], v[154:157], v[170:173], v[30:33]
	v_mfma_f32_16x16x32_bf16 v[30:33], v[158:161], v[174:177], v[30:33]
	v_mfma_f32_16x16x32_bf16 v[22:25], v[146:149], v[178:181], v[22:25]
	v_mfma_f32_16x16x32_bf16 v[22:25], v[150:153], v[182:185], v[22:25]
	v_mfma_f32_16x16x32_bf16 v[14:17], v[154:157], v[178:181], v[14:17]
	v_mfma_f32_16x16x32_bf16 v[14:17], v[158:161], v[182:185], v[14:17]
	v_mfma_f32_16x16x32_bf16 v[6:9], v[146:149], v[186:189], v[6:9]
	v_mfma_f32_16x16x32_bf16 v[6:9], v[150:153], v[220:223], v[6:9]
	v_mfma_f32_16x16x32_bf16 v[2:5], v[154:157], v[186:189], v[2:5]
	v_mfma_f32_16x16x32_bf16 v[2:5], v[158:161], v[220:223], v[2:5]
	s_setprio 0
	s_barrier
	s_add_i32 s70, s70, 2
	s_add_u32 s61, s61, 0x100
	s_addc_u32 s69, s69, 0
	s_cmpk_gt_u32 s70, 0xa9
	s_mov_b64 s[44:45], s[46:47]
	s_cbranch_scc0 .LBB0_983
	s_and_b64 vcc, exec, s[30:31]
	s_cbranch_vccz .LBB0_986
	s_barrier

.LBB0_1049:
	v_add_co_u32_e32 v38, vcc, 0xfffff000, v36
	global_load_dwordx4 v[66:69], v[36:37], off
	global_load_dwordx4 v[48:51], v[36:37], off offset:-3072
	global_load_dwordx4 v[56:59], v[36:37], off offset:-2048
	global_load_dwordx4 v[62:65], v[36:37], off offset:-1024
	v_addc_co_u32_e32 v39, vcc, -1, v37, vcc
	global_load_dwordx4 v[76:79], v[38:39], off offset:-3072
	global_load_dwordx4 v[82:85], v[38:39], off offset:-2048
	global_load_dwordx4 v[98:101], v[38:39], off offset:-1024
	global_load_dwordx4 v[2:5], v[36:37], off offset:-4096
	s_add_i32 s10, s10, s48
	s_cmpk_gt_i32 s10, 0x7fff
	s_waitcnt vmcnt(0)
	v_lshlrev_b32_e32 v74, 16, v67
	v_and_b32_e32 v75, 0xffff0000, v67
	v_lshlrev_b32_e32 v80, 16, v66
	v_and_b32_e32 v81, 0xffff0000, v66
	v_lshlrev_b32_e32 v66, 16, v78
	v_and_b32_e32 v67, 0xffff0000, v78
	v_lshlrev_b32_e32 v78, 16, v76
	v_lshlrev_b32_e32 v42, 16, v51
	v_and_b32_e32 v43, 0xffff0000, v51
	v_lshlrev_b32_e32 v44, 16, v50
	v_and_b32_e32 v45, 0xffff0000, v50
	v_lshlrev_b32_e32 v46, 16, v49
	v_and_b32_e32 v47, 0xffff0000, v49
	v_lshlrev_b32_e32 v50, 16, v48
	v_and_b32_e32 v51, 0xffff0000, v48
	v_lshlrev_b32_e32 v48, 16, v59
	v_and_b32_e32 v49, 0xffff0000, v59
	v_lshlrev_b32_e32 v52, 16, v58
	v_and_b32_e32 v53, 0xffff0000, v58
	v_lshlrev_b32_e32 v54, 16, v57
	v_and_b32_e32 v55, 0xffff0000, v57
	v_lshlrev_b32_e32 v58, 16, v56
	v_and_b32_e32 v59, 0xffff0000, v56
	v_lshlrev_b32_e32 v56, 16, v65
	v_and_b32_e32 v57, 0xffff0000, v65
	v_lshlrev_b32_e32 v60, 16, v64
	v_and_b32_e32 v61, 0xffff0000, v64
	v_lshlrev_b32_e32 v64, 16, v63
	v_and_b32_e32 v65, 0xffff0000, v63
	v_lshlrev_b32_e32 v72, 16, v62
	v_and_b32_e32 v73, 0xffff0000, v62
	v_lshlrev_b32_e32 v62, 16, v79
	v_and_b32_e32 v63, 0xffff0000, v79
	v_and_b32_e32 v79, 0xffff0000, v76
	v_lshlrev_b32_e32 v124, 16, v2
	v_and_b32_e32 v125, 0xffff0000, v2
	v_add_f32_e32 v2, 0, v78
	v_lshlrev_b32_e32 v70, 16, v68
	v_and_b32_e32 v71, 0xffff0000, v68
	v_lshlrev_b32_e32 v68, 16, v77
	v_add_f32_e32 v2, v2, v79
	v_and_b32_e32 v40, 0xffff0000, v69
	v_lshlrev_b32_e32 v41, 16, v69
	v_and_b32_e32 v69, 0xffff0000, v77
	v_add_f32_e32 v2, v2, v68
	v_add_f32_e32 v2, v2, v69
	v_add_f32_e32 v2, v2, v66
	v_add_f32_e32 v2, v2, v67
	v_add_f32_e32 v2, v2, v62
	v_lshlrev_b32_e32 v94, 16, v82
	v_add_f32_e32 v2, v2, v63
	v_and_b32_e32 v95, 0xffff0000, v82
	v_add_f32_e32 v2, v2, v94
	v_lshlrev_b32_e32 v86, 16, v84
	v_and_b32_e32 v87, 0xffff0000, v84
	v_lshlrev_b32_e32 v84, 16, v83
	v_add_f32_e32 v2, v2, v95
	v_lshlrev_b32_e32 v76, 16, v85
	v_and_b32_e32 v77, 0xffff0000, v85
	v_and_b32_e32 v85, 0xffff0000, v83
	v_add_f32_e32 v2, v2, v84
	v_add_f32_e32 v2, v2, v85
	v_add_f32_e32 v2, v2, v86
	v_add_f32_e32 v2, v2, v87
	v_add_f32_e32 v2, v2, v76
	v_lshlrev_b32_e32 v118, 16, v98
	v_add_f32_e32 v2, v2, v77
	v_and_b32_e32 v119, 0xffff0000, v98
	v_add_f32_e32 v2, v2, v118
	v_lshlrev_b32_e32 v116, 16, v99
	v_add_f32_e32 v2, v2, v119
	v_and_b32_e32 v117, 0xffff0000, v99
	v_add_f32_e32 v2, v2, v116
	v_lshlrev_b32_e32 v114, 16, v100
	v_add_f32_e32 v2, v2, v117
	v_and_b32_e32 v115, 0xffff0000, v100
	v_add_f32_e32 v2, v2, v114
	v_lshlrev_b32_e32 v82, 16, v101
	v_add_f32_e32 v2, v2, v115
	v_and_b32_e32 v83, 0xffff0000, v101
	v_add_f32_e32 v2, v2, v82
	v_add_f32_e32 v2, v2, v83
	v_add_f32_e32 v2, v2, v124
	v_lshlrev_b32_e32 v122, 16, v4
	v_and_b32_e32 v123, 0xffff0000, v4
	v_lshlrev_b32_e32 v4, 16, v3
	v_add_f32_e32 v2, v2, v125
	v_lshlrev_b32_e32 v120, 16, v5
	v_and_b32_e32 v121, 0xffff0000, v5
	v_and_b32_e32 v5, 0xffff0000, v3
	v_add_f32_e32 v2, v2, v4
	v_add_f32_e32 v2, v2, v5
	v_add_f32_e32 v2, v2, v122
	v_add_f32_e32 v2, v2, v123
	v_add_f32_e32 v2, v2, v120
	v_add_f32_e32 v2, v2, v121
	v_add_f32_e32 v2, v2, v50
	v_add_f32_e32 v2, v2, v51
	v_add_f32_e32 v2, v2, v46
	v_add_f32_e32 v2, v2, v47
	v_add_f32_e32 v2, v2, v44
	v_add_f32_e32 v2, v2, v45
	v_add_f32_e32 v2, v2, v42
	v_add_f32_e32 v2, v2, v43
	v_add_f32_e32 v2, v2, v58
	v_add_f32_e32 v2, v2, v59
	v_add_f32_e32 v2, v2, v54
	v_add_f32_e32 v2, v2, v55
	v_add_f32_e32 v2, v2, v52
	v_add_f32_e32 v2, v2, v53
	v_add_f32_e32 v2, v2, v48
	v_add_f32_e32 v2, v2, v49
	v_add_f32_e32 v2, v2, v72
	v_add_f32_e32 v2, v2, v73
	v_add_f32_e32 v2, v2, v64
	v_add_f32_e32 v2, v2, v65
	v_add_f32_e32 v2, v2, v60
	v_add_f32_e32 v2, v2, v61
	v_add_f32_e32 v2, v2, v56
	v_add_f32_e32 v2, v2, v57
	v_add_f32_e32 v2, v2, v80
	v_add_f32_e32 v2, v2, v81
	v_add_f32_e32 v2, v2, v74
	v_add_f32_e32 v2, v2, v75
	v_add_f32_e32 v2, v2, v70
	v_add_f32_e32 v2, v2, v71
	v_add_f32_e32 v2, v2, v41
	v_add_f32_e32 v2, v2, v40
	ds_bpermute_b32 v3, v1, v2
	global_load_dwordx4 v[98:101], v[8:9], off offset:16
	global_load_dwordx4 v[102:105], v[8:9], off
	global_load_dwordx4 v[106:109], v[10:11], off offset:16
	global_load_dwordx4 v[110:113], v[10:11], off
	s_waitcnt lgkmcnt(0)
	v_add_f32_e32 v2, v2, v3
	ds_bpermute_b32 v3, v88, v2
	s_waitcnt lgkmcnt(0)
	v_add_f32_e32 v2, v2, v3
	ds_bpermute_b32 v3, v89, v2
	s_waitcnt lgkmcnt(0)
	v_add_f32_e32 v2, v2, v3
	ds_bpermute_b32 v3, v90, v2
	s_waitcnt lgkmcnt(0)
	v_add_f32_e32 v2, v2, v3
	ds_bpermute_b32 v3, v91, v2
	s_waitcnt lgkmcnt(0)
	v_add_f32_e32 v2, v2, v3
	ds_bpermute_b32 v3, v92, v2
	s_waitcnt lgkmcnt(0)
	v_add_f32_e32 v2, v2, v3
	v_mul_f32_e32 v96, 0x39800000, v2
	v_pk_add_f32 v[126:127], v[78:79], v[96:97] op_sel_hi:[1,0] neg_lo:[0,1] neg_hi:[0,1]
	v_pk_add_f32 v[128:129], v[68:69], v[96:97] op_sel_hi:[1,0] neg_lo:[0,1] neg_hi:[0,1]
	v_pk_add_f32 v[68:69], v[124:125], v[96:97] op_sel_hi:[1,0] neg_lo:[0,1] neg_hi:[0,1]
	v_pk_mul_f32 v[124:125], v[126:127], v[126:127]
	v_pk_mul_f32 v[140:141], v[128:129], v[128:129]
	v_add_f32_e32 v7, v124, v125
	v_pk_add_f32 v[130:131], v[66:67], v[96:97] op_sel_hi:[1,0] neg_lo:[0,1] neg_hi:[0,1]
	v_add_f32_e32 v7, v140, v7
	v_pk_mul_f32 v[142:143], v[130:131], v[130:131]
	v_add_f32_e32 v7, v141, v7
	v_pk_add_f32 v[132:133], v[62:63], v[96:97] op_sel_hi:[1,0] neg_lo:[0,1] neg_hi:[0,1]
	v_add_f32_e32 v7, v142, v7
	v_pk_mul_f32 v[144:145], v[132:133], v[132:133]
	v_add_f32_e32 v7, v143, v7
	v_pk_add_f32 v[94:95], v[94:95], v[96:97] op_sel_hi:[1,0] neg_lo:[0,1] neg_hi:[0,1]
	v_add_f32_e32 v7, v144, v7
	v_pk_mul_f32 v[146:147], v[94:95], v[94:95]
	v_add_f32_e32 v7, v145, v7
	v_pk_add_f32 v[134:135], v[84:85], v[96:97] op_sel_hi:[1,0] neg_lo:[0,1] neg_hi:[0,1]
	v_add_f32_e32 v7, v146, v7
	v_pk_mul_f32 v[148:149], v[134:135], v[134:135]
	v_add_f32_e32 v7, v147, v7
	v_pk_add_f32 v[136:137], v[86:87], v[96:97] op_sel_hi:[1,0] neg_lo:[0,1] neg_hi:[0,1]
	v_add_f32_e32 v7, v148, v7
	v_pk_mul_f32 v[150:151], v[136:137], v[136:137]
	v_add_f32_e32 v7, v149, v7
	v_pk_add_f32 v[138:139], v[76:77], v[96:97] op_sel_hi:[1,0] neg_lo:[0,1] neg_hi:[0,1]
	v_add_f32_e32 v7, v150, v7
	v_pk_mul_f32 v[152:153], v[138:139], v[138:139]
	v_add_f32_e32 v7, v151, v7
	v_pk_add_f32 v[118:119], v[118:119], v[96:97] op_sel_hi:[1,0] neg_lo:[0,1] neg_hi:[0,1]
	v_add_f32_e32 v7, v152, v7
	v_pk_mul_f32 v[154:155], v[118:119], v[118:119]
	v_add_f32_e32 v7, v153, v7
	v_pk_add_f32 v[116:117], v[116:117], v[96:97] op_sel_hi:[1,0] neg_lo:[0,1] neg_hi:[0,1]
	v_add_f32_e32 v7, v154, v7
	v_pk_mul_f32 v[156:157], v[116:117], v[116:117]
	v_add_f32_e32 v7, v155, v7
	v_pk_add_f32 v[114:115], v[114:115], v[96:97] op_sel_hi:[1,0] neg_lo:[0,1] neg_hi:[0,1]
	v_add_f32_e32 v7, v156, v7
	v_pk_mul_f32 v[158:159], v[114:115], v[114:115]
	v_add_f32_e32 v7, v157, v7
	v_pk_add_f32 v[86:87], v[82:83], v[96:97] op_sel_hi:[1,0] neg_lo:[0,1] neg_hi:[0,1]
	v_add_f32_e32 v7, v158, v7
	v_pk_mul_f32 v[160:161], v[86:87], v[86:87]
	v_add_f32_e32 v7, v159, v7
	v_add_f32_e32 v7, v160, v7
	v_pk_mul_f32 v[162:163], v[68:69], v[68:69]
	v_add_f32_e32 v7, v161, v7
	v_pk_add_f32 v[66:67], v[4:5], v[96:97] op_sel_hi:[1,0] neg_lo:[0,1] neg_hi:[0,1]
	v_add_f32_e32 v7, v162, v7
	v_pk_mul_f32 v[164:165], v[66:67], v[66:67]
	v_add_f32_e32 v7, v163, v7
	v_pk_add_f32 v[122:123], v[122:123], v[96:97] op_sel_hi:[1,0] neg_lo:[0,1] neg_hi:[0,1]
	v_add_f32_e32 v7, v164, v7
	v_pk_mul_f32 v[166:167], v[122:123], v[122:123]
	v_add_f32_e32 v7, v165, v7
	v_pk_add_f32 v[120:121], v[120:121], v[96:97] op_sel_hi:[1,0] neg_lo:[0,1] neg_hi:[0,1]
	v_add_f32_e32 v7, v166, v7
	v_pk_mul_f32 v[168:169], v[120:121], v[120:121]
	v_add_f32_e32 v7, v167, v7
	v_pk_add_f32 v[82:83], v[50:51], v[96:97] op_sel_hi:[1,0] neg_lo:[0,1] neg_hi:[0,1]
	v_add_f32_e32 v7, v168, v7
	v_pk_mul_f32 v[170:171], v[82:83], v[82:83]
	v_add_f32_e32 v7, v169, v7
	v_pk_add_f32 v[78:79], v[46:47], v[96:97] op_sel_hi:[1,0] neg_lo:[0,1] neg_hi:[0,1]
	v_add_f32_e32 v7, v170, v7
	v_pk_mul_f32 v[172:173], v[78:79], v[78:79]
	v_add_f32_e32 v7, v171, v7
	v_pk_add_f32 v[84:85], v[44:45], v[96:97] op_sel_hi:[1,0] neg_lo:[0,1] neg_hi:[0,1]
	v_add_f32_e32 v7, v172, v7
	v_pk_mul_f32 v[174:175], v[84:85], v[84:85]
	v_add_f32_e32 v7, v173, v7
	v_pk_add_f32 v[76:77], v[42:43], v[96:97] op_sel_hi:[1,0] neg_lo:[0,1] neg_hi:[0,1]
	v_add_f32_e32 v7, v174, v7
	v_pk_mul_f32 v[176:177], v[76:77], v[76:77]
	v_add_f32_e32 v7, v175, v7
	v_pk_add_f32 v[58:59], v[58:59], v[96:97] op_sel_hi:[1,0] neg_lo:[0,1] neg_hi:[0,1]
	v_add_f32_e32 v7, v176, v7
	v_pk_mul_f32 v[178:179], v[58:59], v[58:59]
	v_add_f32_e32 v7, v177, v7
	v_pk_add_f32 v[54:55], v[54:55], v[96:97] op_sel_hi:[1,0] neg_lo:[0,1] neg_hi:[0,1]
	v_add_f32_e32 v7, v178, v7
	v_pk_mul_f32 v[180:181], v[54:55], v[54:55]
	v_add_f32_e32 v7, v179, v7
	v_pk_add_f32 v[62:63], v[52:53], v[96:97] op_sel_hi:[1,0] neg_lo:[0,1] neg_hi:[0,1]
	v_add_f32_e32 v7, v180, v7
	v_pk_mul_f32 v[182:183], v[62:63], v[62:63]
	v_add_f32_e32 v7, v181, v7
	v_pk_add_f32 v[52:53], v[48:49], v[96:97] op_sel_hi:[1,0] neg_lo:[0,1] neg_hi:[0,1]
	v_add_f32_e32 v7, v182, v7
	v_pk_mul_f32 v[184:185], v[52:53], v[52:53]
	v_add_f32_e32 v7, v183, v7
	v_pk_add_f32 v[48:49], v[72:73], v[96:97] op_sel_hi:[1,0] neg_lo:[0,1] neg_hi:[0,1]
	v_add_f32_e32 v7, v184, v7
	v_pk_mul_f32 v[72:73], v[48:49], v[48:49]
	v_add_f32_e32 v7, v185, v7
	v_pk_add_f32 v[46:47], v[64:65], v[96:97] op_sel_hi:[1,0] neg_lo:[0,1] neg_hi:[0,1]
	v_add_f32_e32 v7, v72, v7
	v_pk_mul_f32 v[64:65], v[46:47], v[46:47]
	v_add_f32_e32 v7, v73, v7
	v_pk_add_f32 v[50:51], v[60:61], v[96:97] op_sel_hi:[1,0] neg_lo:[0,1] neg_hi:[0,1]
	v_add_f32_e32 v7, v64, v7
	v_pk_mul_f32 v[60:61], v[50:51], v[50:51]
	v_add_f32_e32 v7, v65, v7
	v_pk_add_f32 v[44:45], v[56:57], v[96:97] op_sel_hi:[1,0] neg_lo:[0,1] neg_hi:[0,1]
	v_add_f32_e32 v7, v60, v7
	v_pk_mul_f32 v[56:57], v[44:45], v[44:45]
	v_add_f32_e32 v7, v61, v7
	v_pk_add_f32 v[2:3], v[80:81], v[96:97] op_sel_hi:[1,0] neg_lo:[0,1] neg_hi:[0,1]
	v_add_f32_e32 v7, v56, v7
	v_pk_mul_f32 v[80:81], v[2:3], v[2:3]
	v_add_f32_e32 v7, v57, v7
	v_pk_add_f32 v[4:5], v[74:75], v[96:97] op_sel_hi:[1,0] neg_lo:[0,1] neg_hi:[0,1]
	v_add_f32_e32 v7, v80, v7
	v_pk_mul_f32 v[74:75], v[4:5], v[4:5]
	v_add_f32_e32 v7, v81, v7
	v_pk_add_f32 v[42:43], v[70:71], v[96:97] op_sel_hi:[1,0] neg_lo:[0,1] neg_hi:[0,1]
	v_add_f32_e32 v7, v74, v7
	v_pk_mul_f32 v[70:71], v[42:43], v[42:43]
	v_add_f32_e32 v7, v75, v7
	v_pk_add_f32 v[40:41], v[40:41], v[96:97] op_sel_hi:[1,0] neg_lo:[0,1] neg_hi:[0,1]
	v_add_f32_e32 v7, v70, v7
	v_pk_mul_f32 v[186:187], v[40:41], v[40:41]
	v_add_f32_e32 v7, v71, v7
	v_add_f32_e32 v7, v187, v7
	v_add_f32_e32 v7, v186, v7
	ds_bpermute_b32 v56, v1, v7
	s_waitcnt lgkmcnt(0)
	v_add_f32_e32 v7, v7, v56
	ds_bpermute_b32 v56, v88, v7
	s_waitcnt lgkmcnt(0)
	v_add_f32_e32 v7, v7, v56
	ds_bpermute_b32 v56, v89, v7
	s_waitcnt lgkmcnt(0)
	v_add_f32_e32 v7, v7, v56
	ds_bpermute_b32 v56, v90, v7
	s_waitcnt lgkmcnt(0)
	v_add_f32_e32 v7, v7, v56
	ds_bpermute_b32 v56, v91, v7
	s_waitcnt lgkmcnt(0)
	v_add_f32_e32 v7, v7, v56
	ds_bpermute_b32 v56, v92, v7
	s_waitcnt lgkmcnt(0)
	v_add_f32_e32 v7, v7, v56
	v_fmamk_f32 v7, v7, 0x39800000, v237
	v_mul_f32_e32 v56, 0x4f800000, v7
	v_cmp_gt_f32_e32 vcc, s62, v7
	s_nop 1
	v_cndmask_b32_e32 v7, v7, v56, vcc
	v_sqrt_f32_e32 v56, v7
	s_nop 0
	v_add_u32_e32 v57, -1, v56
	v_fma_f32 v60, -v57, v56, v7
	v_cmp_ge_f32_e64 s[38:39], 0, v60
	v_add_u32_e32 v60, 1, v56
	s_nop 0
	v_cndmask_b32_e64 v57, v56, v57, s[38:39]
	v_fma_f32 v56, -v60, v56, v7
	v_cmp_lt_f32_e64 s[38:39], 0, v56
	s_nop 1
	v_cndmask_b32_e64 v56, v57, v60, s[38:39]
	v_mul_f32_e32 v57, 0x37800000, v56
	v_cndmask_b32_e32 v56, v56, v57, vcc
	v_cmp_class_f32_e32 vcc, v7, v238
	s_nop 1
	v_cndmask_b32_e32 v7, v56, v7, vcc
	v_div_scale_f32 v56, s[12:13], v7, v7, 1.0
	v_rcp_f32_e32 v57, v56
	s_nop 0
	v_fma_f32 v60, -v56, v57, 1.0
	v_fmac_f32_e32 v57, v60, v57
	v_div_scale_f32 v60, vcc, 1.0, v7, 1.0
	v_mul_f32_e32 v61, v60, v57
	v_fma_f32 v64, -v56, v61, v60
	v_fmac_f32_e32 v61, v64, v57
	v_fma_f32 v56, -v56, v61, v60
	v_div_fmas_f32 v56, v56, v57, v61
	v_div_fixup_f32 v80, v56, v7, 1.0
	v_pk_mul_f32 v[56:57], v[126:127], v[80:81] op_sel_hi:[1,0]
	v_pk_mul_f32 v[60:61], v[130:131], v[80:81] op_sel_hi:[1,0]
	v_pk_mul_f32 v[64:65], v[128:129], v[80:81] op_sel_hi:[1,0]
	v_pk_mul_f32 v[70:71], v[132:133], v[80:81] op_sel_hi:[1,0]
	s_waitcnt vmcnt(0)
	v_pk_fma_f32 v[56:57], v[102:103], v[56:57], v[110:111]
	v_pk_fma_f32 v[60:61], v[98:99], v[60:61], v[106:107]
	v_pk_fma_f32 v[64:65], v[104:105], v[64:65], v[112:113]
	v_pk_fma_f32 v[74:75], v[100:101], v[70:71], v[108:109]
	v_cvt_pk_bf16_f32 v70, v56, v57
	v_cvt_pk_bf16_f32 v71, v64, v65
	v_cvt_pk_bf16_f32 v72, v60, v61
	v_cvt_pk_bf16_f32 v73, v74, v75
	global_store_dwordx4 v[38:39], v[70:73], off offset:-3072
	global_load_dwordx4 v[70:73], v[8:9], off offset:2064
	s_nop 0
	global_load_dwordx4 v[98:101], v[8:9], off offset:2048
	global_load_dwordx4 v[102:105], v[10:11], off offset:2048
	global_load_dwordx4 v[106:109], v[10:11], off offset:2064
	v_pk_mul_f32 v[56:57], v[94:95], v[80:81] op_sel_hi:[1,0]
	v_pk_mul_f32 v[60:61], v[136:137], v[80:81] op_sel_hi:[1,0]
	v_pk_mul_f32 v[64:65], v[134:135], v[80:81] op_sel_hi:[1,0]
	v_pk_mul_f32 v[74:75], v[138:139], v[80:81] op_sel_hi:[1,0]
	v_pk_mul_f32 v[76:77], v[76:77], v[80:81] op_sel_hi:[1,0]
	v_pk_mul_f32 v[54:55], v[54:55], v[80:81] op_sel_hi:[1,0]
	v_pk_mul_f32 v[52:53], v[52:53], v[80:81] op_sel_hi:[1,0]
	v_pk_mul_f32 v[46:47], v[46:47], v[80:81] op_sel_hi:[1,0]
	v_pk_mul_f32 v[44:45], v[44:45], v[80:81] op_sel_hi:[1,0]
	v_pk_mul_f32 v[2:3], v[2:3], v[80:81] op_sel_hi:[1,0]
	v_pk_mul_f32 v[4:5], v[4:5], v[80:81] op_sel_hi:[1,0]
	v_pk_mul_f32 v[40:41], v[40:41], v[80:81] op_sel_hi:[1,0]
	s_waitcnt vmcnt(1)
	v_pk_fma_f32 v[56:57], v[98:99], v[56:57], v[102:103]
	s_waitcnt vmcnt(0)
	v_pk_fma_f32 v[60:61], v[70:71], v[60:61], v[106:107]
	v_pk_fma_f32 v[64:65], v[100:101], v[64:65], v[104:105]
	v_pk_fma_f32 v[74:75], v[72:73], v[74:75], v[108:109]
	v_cvt_pk_bf16_f32 v70, v56, v57
	v_cvt_pk_bf16_f32 v71, v64, v65
	v_cvt_pk_bf16_f32 v72, v60, v61
	v_cvt_pk_bf16_f32 v73, v74, v75
	global_store_dwordx4 v[38:39], v[70:73], off offset:-2048
	global_load_dwordx4 v[70:73], v[12:13], off offset:16
	s_nop 0
	global_load_dwordx4 v[98:101], v[12:13], off
	global_load_dwordx4 v[102:105], v[14:15], off
	global_load_dwordx4 v[106:109], v[14:15], off offset:16
	v_pk_mul_f32 v[56:57], v[118:119], v[80:81] op_sel_hi:[1,0]
	v_pk_mul_f32 v[60:61], v[114:115], v[80:81] op_sel_hi:[1,0]
	v_pk_mul_f32 v[64:65], v[116:117], v[80:81] op_sel_hi:[1,0]
	v_pk_mul_f32 v[74:75], v[86:87], v[80:81] op_sel_hi:[1,0]
	s_waitcnt vmcnt(1)
	v_pk_fma_f32 v[56:57], v[98:99], v[56:57], v[102:103]
	s_waitcnt vmcnt(0)
	v_pk_fma_f32 v[60:61], v[70:71], v[60:61], v[106:107]
	v_pk_fma_f32 v[64:65], v[100:101], v[64:65], v[104:105]
	v_pk_fma_f32 v[74:75], v[72:73], v[74:75], v[108:109]
	v_cvt_pk_bf16_f32 v70, v56, v57
	v_cvt_pk_bf16_f32 v71, v64, v65
	v_cvt_pk_bf16_f32 v72, v60, v61
	v_cvt_pk_bf16_f32 v73, v74, v75
	global_store_dwordx4 v[38:39], v[70:73], off offset:-1024
	global_load_dwordx4 v[70:73], v[16:17], off offset:16
	s_nop 0
	global_load_dwordx4 v[98:101], v[16:17], off
	global_load_dwordx4 v[102:105], v[18:19], off
	global_load_dwordx4 v[106:109], v[18:19], off offset:16
	v_pk_mul_f32 v[38:39], v[68:69], v[80:81] op_sel_hi:[1,0]
	v_pk_mul_f32 v[56:57], v[122:123], v[80:81] op_sel_hi:[1,0]
	v_pk_mul_f32 v[60:61], v[66:67], v[80:81] op_sel_hi:[1,0]
	v_pk_mul_f32 v[64:65], v[120:121], v[80:81] op_sel_hi:[1,0]
	s_waitcnt vmcnt(1)
	v_pk_fma_f32 v[38:39], v[98:99], v[38:39], v[102:103]
	s_waitcnt vmcnt(0)
	v_pk_fma_f32 v[56:57], v[70:71], v[56:57], v[106:107]
	v_pk_fma_f32 v[60:61], v[100:101], v[60:61], v[104:105]
	v_pk_fma_f32 v[68:69], v[72:73], v[64:65], v[108:109]
	v_cvt_pk_bf16_f32 v64, v38, v39
	v_cvt_pk_bf16_f32 v65, v60, v61
	v_cvt_pk_bf16_f32 v66, v56, v57
	v_cvt_pk_bf16_f32 v67, v68, v69
	global_store_dwordx4 v[36:37], v[64:67], off offset:-4096
	global_load_dwordx4 v[64:67], v[20:21], off offset:16
	s_nop 0
	global_load_dwordx4 v[68:71], v[20:21], off
	global_load_dwordx4 v[72:75], v[22:23], off
	global_load_dwordx4 v[98:101], v[22:23], off offset:16
	v_pk_mul_f32 v[38:39], v[82:83], v[80:81] op_sel_hi:[1,0]
	v_pk_mul_f32 v[56:57], v[84:85], v[80:81] op_sel_hi:[1,0]
	v_pk_mul_f32 v[60:61], v[78:79], v[80:81] op_sel_hi:[1,0]
	s_waitcnt vmcnt(1)
	v_pk_fma_f32 v[38:39], v[68:69], v[38:39], v[72:73]
	s_waitcnt vmcnt(0)
	v_pk_fma_f32 v[56:57], v[64:65], v[56:57], v[98:99]
	v_pk_fma_f32 v[60:61], v[70:71], v[60:61], v[74:75]
	v_pk_fma_f32 v[68:69], v[66:67], v[76:77], v[100:101]
	v_cvt_pk_bf16_f32 v64, v38, v39
	v_cvt_pk_bf16_f32 v65, v60, v61
	v_cvt_pk_bf16_f32 v66, v56, v57
	v_cvt_pk_bf16_f32 v67, v68, v69
	global_store_dwordx4 v[36:37], v[64:67], off offset:-3072
	global_load_dwordx4 v[64:67], v[24:25], off offset:16
	s_nop 0
	global_load_dwordx4 v[68:71], v[24:25], off
	global_load_dwordx4 v[72:75], v[26:27], off
	global_load_dwordx4 v[76:79], v[26:27], off offset:16
	v_pk_mul_f32 v[38:39], v[58:59], v[80:81] op_sel_hi:[1,0]
	v_pk_mul_f32 v[56:57], v[62:63], v[80:81] op_sel_hi:[1,0]
	s_waitcnt vmcnt(1)
	v_pk_fma_f32 v[38:39], v[68:69], v[38:39], v[72:73]
	s_waitcnt vmcnt(0)
	v_pk_fma_f32 v[56:57], v[64:65], v[56:57], v[76:77]
	v_pk_fma_f32 v[54:55], v[70:71], v[54:55], v[74:75]
	v_pk_fma_f32 v[58:59], v[66:67], v[52:53], v[78:79]
	v_cvt_pk_bf16_f32 v52, v38, v39
	v_cvt_pk_bf16_f32 v53, v54, v55
	v_cvt_pk_bf16_f32 v54, v56, v57
	v_cvt_pk_bf16_f32 v55, v58, v59
	global_store_dwordx4 v[36:37], v[52:55], off offset:-2048
	global_load_dwordx4 v[52:55], v[28:29], off offset:16
	s_nop 0
	global_load_dwordx4 v[56:59], v[28:29], off
	global_load_dwordx4 v[60:63], v[30:31], off
	global_load_dwordx4 v[64:67], v[30:31], off offset:16
	v_pk_mul_f32 v[38:39], v[48:49], v[80:81] op_sel_hi:[1,0]
	v_pk_mul_f32 v[48:49], v[50:51], v[80:81] op_sel_hi:[1,0]
	s_waitcnt vmcnt(1)
	v_pk_fma_f32 v[38:39], v[56:57], v[38:39], v[60:61]
	s_waitcnt vmcnt(0)
	v_pk_fma_f32 v[48:49], v[52:53], v[48:49], v[64:65]
	v_pk_fma_f32 v[46:47], v[58:59], v[46:47], v[62:63]
	v_pk_fma_f32 v[50:51], v[54:55], v[44:45], v[66:67]
	v_cvt_pk_bf16_f32 v44, v38, v39
	v_cvt_pk_bf16_f32 v45, v46, v47
	v_cvt_pk_bf16_f32 v46, v48, v49
	v_cvt_pk_bf16_f32 v47, v50, v51
	global_store_dwordx4 v[36:37], v[44:47], off offset:-1024
	global_load_dwordx4 v[44:47], v[32:33], off offset:16
	s_nop 0
	global_load_dwordx4 v[48:51], v[32:33], off
	global_load_dwordx4 v[52:55], v[34:35], off
	global_load_dwordx4 v[56:59], v[34:35], off offset:16
	v_pk_mul_f32 v[38:39], v[42:43], v[80:81] op_sel_hi:[1,0]
	s_waitcnt vmcnt(1)
	v_pk_fma_f32 v[2:3], v[48:49], v[2:3], v[52:53]
	s_waitcnt vmcnt(0)
	v_pk_fma_f32 v[38:39], v[44:45], v[38:39], v[56:57]
	v_pk_fma_f32 v[4:5], v[50:51], v[4:5], v[54:55]
	v_pk_fma_f32 v[40:41], v[46:47], v[40:41], v[58:59] op_sel:[0,1,0] op_sel_hi:[1,0,1]
	v_cvt_pk_bf16_f32 v2, v2, v3
	v_cvt_pk_bf16_f32 v3, v4, v5
	v_cvt_pk_bf16_f32 v4, v38, v39
	v_cvt_pk_bf16_f32 v5, v40, v41
	global_store_dwordx4 v[36:37], v[2:5], off
	v_lshl_add_u64 v[36:37], v[36:37], 0, s[4:5]
	s_cbranch_scc0 .LBB0_1049
